# instruction selection: packed fp32 VALU ops in the four attention item classes split into bit-identical scalar pairs (567 sites)
# speedup vs baseline: 1.0054x; 1.0054x over previous
; __device__ __forceinline__ float wave_sum(float v) { v += lx<1>(v); v += lx<2>(v); v += lx<4>(v); v += lx<8>(v); v += lx<16>(v); return half_sum(v); }
; #define ARG_IN(i) ((const float*)karg64(8 * (i)))
; #define ARG_WS() ((unsigned char*)karg64(8 * 19))
; #define WG_DRAW(cls, q) LAS int* slot = (LAS int*)(lds + MISC_OFF + 64); \
;         if (threadIdx.x == 0) *slot = (int)__hip_atomic_fetch_add(XQ_HEAD(cls, q), 1u, RLX_AGENT); \
;         __syncthreads(); const int it = *slot; __syncthreads();
; __device__ __forceinline__ void dif_coop(const bf16* PROJ, const unsigned char* VTB, bf16* O, float lam, const float* subg, float oscale, int bh, int c, LAS unsigned char* sbuf, int tid) {
;     const int wave = tid >> 6, lane = tid & 63, b = bh >> 2, hd = bh & 3, q = lane & 31, hh = lane >> 5, mp = wave >> 2, qt = 4 * c + (wave & 3), tq = 32 * qt + q; const size_t row = (size_t)b * SEQ + tq;
;     AlibiCausal f; f.setup(__builtin_amdgcn_exp2f(-2.f * (float)(hd + 1)) * LOG2E, hh); f.tq = tq; f.t0 = 32 * qt;
;     bf16x8 qf[4]; load_qfrag(PROJ + row * NINP + C_DIFQ + hd * 128 + mp * 64 + 8 * hh, qf);
; template <int ATTM> __device__ __forceinline__ void attention_phase(int layer, int lane, int rep, LAS unsigned char* lds, int wave) {
;     ...
;             for (;;) { WG_DRAW(0, q); if (it >= 32) break;
;                 unsigned char* ws = ARG_WS(); int tid = threadIdx.x; asm volatile("" : "+v"(tid));
;                 const float* lamv = ARG_IN(A_LAM) + (size_t)layer * 4 * 64;
;                 const float lam_init = 0.8f - 0.6f * __builtin_amdgcn_exp2f(-0.3f * 1.4426950408889634f * (float)layer);
;                 const float sa = wave_sum(lamv[lane] * lamv[64 + lane]), sb = wave_sum(lamv[128 + lane] * lamv[192 + lane]);
;                 const float lam = __builtin_amdgcn_exp2f(1.4426950408889634f * sa) - __builtin_amdgcn_exp2f(1.4426950408889634f * sb) + lam_init;
;                 dif_coop(WSP(bf16, WS_PROJ), ws + WS_VTB, WSP(bf16, WS_O), lam, ARG_IN(A_SUBG) + (size_t)layer * 128, 1.f - lam_init, q, 31 - it, lds, tid); } } }
.LBB0_556:
	s_or_b64 exec, exec, s[14:15]
	v_mov_b32_e32 v2, s87
	s_waitcnt vmcnt(0) lgkmcnt(0)
	s_barrier
	ds_read_b32 v2, v2
	s_mov_b64 s[14:15], -1
	s_waitcnt lgkmcnt(0)
	s_barrier
	v_cmp_lt_i32_e32 vcc, 31, v2
	v_readfirstlane_b32 s4, v2
	s_cbranch_vccnz .LBB0_551
	v_mov_b32_e32 v184, v0
	s_load_dwordx2 s[36:37], s[0:1], 0x98
	s_load_dwordx2 s[12:13], s[0:1], 0x58
	v_mov_b32_e32 v173, v3
	s_movk_i32 s5, 0x1800
	v_bfe_u32 v29, v184, 5, 1
	v_ashrrev_i32_e32 v31, 8, v184
	s_waitcnt lgkmcnt(0)
	s_add_u32 s12, s12, s2
	s_addc_u32 s13, s13, s3
	v_lshl_add_u64 v[20:21], s[12:13], 0, v[172:173]
	flat_load_dword v2, v[20:21]
	flat_load_dword v22, v[20:21] offset:256
	v_lshlrev_b32_e32 v33, 4, v184
	v_and_b32_e32 v34, 48, v184
	v_lshrrev_b32_e32 v35, 1, v184
	v_and_b32_e32 v30, 31, v184
	v_lshlrev_b32_e32 v32, 3, v184
	v_cmp_lt_i32_e32 vcc, s80, v184
	v_lshlrev_b32_e32 v28, 6, v31
	v_lshlrev_b32_e32 v31, 13, v31
	s_movk_i32 s20, 0x1000
	v_cndmask_b32_e64 v26, 20, 21, vcc
	v_lshl_or_b32 v31, v30, 7, v31
	v_mov_b32_e32 v27, v3
	v_bfe_u32 v186, v184, 6, 2
	v_add_lshl_u32 v26, s9, v26, 19
	v_lshrrev_b32_e32 v36, 2, v184
	v_bitop3_b32 v36, v36, v29, 3 bitop3:0x6c
	v_lshlrev_b32_e32 v173, 2, v29
	v_lshlrev_b32_e32 v40, 5, v186
	v_cmp_gt_u32_e64 s[38:39], v173, v30
	v_cmp_lt_u32_e64 s[40:41], v173, v30
	v_mov_b32_e32 v25, v3
	s_mov_b32 s25, s19
	s_mov_b32 s17, s19
	v_mov_b32_e32 v37, v29
	v_mov_b32_e32 v23, v3
	v_mov_b32_e32 v175, v174
	v_mov_b32_e32 v18, v3
	v_mov_b32_e32 v19, v3
	v_mov_b32_e32 v4, v3
	v_mov_b32_e32 v5, v3
	v_mov_b32_e32 v6, v3
	v_mov_b32_e32 v7, v3
	v_mov_b32_e32 v8, v3
	v_mov_b32_e32 v9, v3
	v_mov_b32_e32 v10, v3
	v_mov_b32_e32 v11, v3
	v_mov_b32_e32 v12, v3
	v_mov_b32_e32 v13, v3
	v_mov_b32_e32 v14, v3
	v_mov_b32_e32 v15, v3
	v_mov_b32_e32 v16, v3
	v_mov_b32_e32 v187, 0
	v_mov_b32_e32 v202, 0xf149f2ca
	v_and_b32_e32 v185, 63, v184
	s_waitcnt vmcnt(0) lgkmcnt(0)
	v_mul_f32_e32 v17, v2, v22
	ds_swizzle_b32 v24, v17 offset:swizzle(SWAP,1)
	v_mov_b32_e32 v17, v3
	s_waitcnt lgkmcnt(0)
	v_fmac_f32_e32 v24, v2, v22
	ds_swizzle_b32 v2, v24 offset:swizzle(SWAP,2)
	s_waitcnt lgkmcnt(0)
	v_add_f32_e32 v2, v24, v2
	ds_swizzle_b32 v22, v2 offset:swizzle(SWAP,4)
	v_ashrrev_i32_e32 v24, 3, v184
	v_mad_i64_i32 v[178:179], s[12:13], v24, s5, 0
	s_movk_i32 s5, 0xff0
	s_waitcnt lgkmcnt(0)
	v_add_f32_e32 v2, v2, v22
	ds_swizzle_b32 v22, v2 offset:swizzle(SWAP,8)
	s_add_u32 s12, s36, 0x8800000
	v_and_or_b32 v178, v32, 56, v178
	s_addc_u32 s13, s37, 0
	s_sub_i32 s11, 31, s4
	s_waitcnt lgkmcnt(0)
	v_add_f32_e32 v2, v2, v22
	ds_swizzle_b32 v22, v2 offset:swizzle(SWAP,16)
	s_lshl_b32 s16, s11, 2
	s_lshl_b32 s24, s8, 1
	s_waitcnt lgkmcnt(0)
	v_add_f32_e32 v188, v2, v22
	v_mov_b32_e32 v189, v188
	flat_load_dword v38, v[20:21] offset:512
	flat_load_dword v39, v[20:21] offset:768
	v_lshlrev_b32_e32 v2, 7, v24
	v_xor_b32_e32 v20, v33, v184
	v_bitop3_b32 v21, v33, v34, s5 bitop3:0x6c
	v_bitop3_b32 v34, v35, v29, 7 bitop3:0x6c
	v_and_b32_e32 v24, 0xff0, v33
	v_and_or_b32 v2, v20, s85, v2
	v_and_or_b32 v32, v33, s20, v21
	v_lshlrev_b32_e32 v33, 4, v34
	v_add_u32_e32 v190, 0, v2
	v_bitop3_b32 v2, v33, 32, v31 bitop3:0x36
	v_lshl_add_u64 v[20:21], s[36:37], 0, v[26:27]
	v_or_b32_e32 v26, v33, v31
	v_add_u32_e32 v193, 0, v2
	v_or_b32_e32 v2, s16, v186
	v_add_u32_e32 v192, 0, v26
	v_lshlrev_b32_e32 v197, 5, v2
	v_lshlrev_b32_e32 v35, 6, v30
	v_lshlrev_b32_e32 v34, 4, v36
	v_or_b32_e32 v36, v40, v30
	v_or_b32_e32 v42, v197, v30
	v_add_u32_e32 v191, 0, v32
	v_bitop3_b32 v32, v33, 64, v31 bitop3:0x36
	v_bitop3_b32 v31, v33, s81, v31 bitop3:0x36
	v_add_u32_e32 v195, 0, v31
	v_or_b32_e32 v27, v34, v35
	v_bitop3_b32 v41, v34, 32, v35 bitop3:0x36
	v_lshl_add_u64 v[20:21], v[20:21], 0, v[24:25]
	s_add_u32 s5, s12, s10
	v_lshl_add_u64 v[180:181], v[20:21], 0, s[96:97]
	v_mov_b64_e32 v[20:21], s[12:13]
	s_addc_u32 s12, s13, 0
	s_add_u32 s5, s5, s24
	v_add_u32_e32 v2, s7, v42
	s_addc_u32 s15, s12, 0
	v_mad_u64_u32 v[20:21], s[12:13], v2, s83, v[20:21]
	s_add_u32 s14, s5, 0x2600
	v_lshlrev_b32_e32 v22, 4, v29
	v_ashrrev_i32_e32 v29, 31, v28
	v_lshl_add_u64 v[20:21], v[20:21], 0, s[24:25]
	s_addc_u32 s15, s15, 0
	s_lshr_b32 s5, s16, 1
	s_lshl_b64 s[12:13], s[16:17], 12
	s_lshl_b32 s16, s11, 7
	v_add_u32_e32 v196, 0, v27
	v_lshl_add_u64 v[24:25], v[28:29], 1, v[20:21]
	s_or_b32 s11, s5, 1
	v_lshl_add_u64 v[20:21], v[180:181], 0, s[12:13]
	v_lshl_add_u64 v[22:23], v[24:25], 0, v[22:23]
	v_add_co_u32_e32 v24, vcc, s20, v20
	s_lshl_b32 s18, s11, 1
	s_nop 0
	v_addc_co_u32_e32 v25, vcc, 0, v21, vcc
	v_add_u32_e32 v194, 0, v32
	v_or_b32_e32 v43, v197, v173
	s_lshl_b32 s5, s5, 6
	v_or_b32_e32 v44, 2, v43
	v_or_b32_e32 v45, 3, v43
	v_or_b32_e32 v46, 8, v43
	v_or_b32_e32 v47, 9, v43
	v_or_b32_e32 v48, 10, v43
	v_or_b32_e32 v49, 11, v43
	v_or_b32_e32 v50, 16, v43
	v_or_b32_e32 v51, 17, v43
	v_or_b32_e32 v52, 18, v43
	v_or_b32_e32 v53, 19, v43
	v_or_b32_e32 v54, 24, v43
	v_or_b32_e32 v55, 25, v43
	v_or_b32_e32 v56, 26, v43
	v_cmp_gt_u32_e64 s[42:43], v44, v42
	v_cmp_gt_u32_e64 s[44:45], v45, v42
	v_cmp_gt_u32_e64 s[46:47], v46, v42
	v_cmp_gt_u32_e64 s[48:49], v47, v42
	v_cmp_gt_u32_e64 s[50:51], v48, v42
	v_cmp_gt_u32_e64 s[52:53], v49, v42
	v_cmp_gt_u32_e64 s[54:55], v50, v42
	v_cmp_gt_u32_e64 s[56:57], v51, v42
	v_cmp_gt_u32_e64 s[58:59], v52, v42
	s_waitcnt vmcnt(0) lgkmcnt(0)
; #define LAS __attribute__((address_space(3)))
; #define CP_LOAD(S, st_) do { const size_t ko = ksoff + (size_t)(64 * (st_)) * NINP; const size_t vo = (size_t)(2 * (st_)) * 4096; \
;         kr0[S] = *(const GAS v4u*)(kcol0 + ko); if (NMAP == 2) kr1[S] = *(const GAS v4u*)(kcol1 + ko); \
;         vr0[S] = *(const GAS v4u*)(vsrc + vo); if (NDT == 4) vr1[S] = *(const GAS v4u*)(vsrc + vo + 4096); } while (0)
; #define CP_PARK(S, buf) do { *(LAS v4u*)((buf) + kdst) = kr0[S]; if (NMAP == 2) *(LAS v4u*)((buf) + 8192 + kdst) = kr1[S]; \
;         *(LAS v4u*)((buf) + vdst) = vr0[S]; if (NDT == 4) *(LAS v4u*)((buf) + vdst + Gm::VS) = vr1[S]; } while (0)
; #define CP_BAR() do { asm volatile("s_waitcnt lgkmcnt(0)" ::: "memory"); __builtin_amdgcn_s_barrier(); asm volatile("" ::: "memory"); } while (0)
;     __device__ __forceinline__ void setup(float g_, int hh_) { g = g_; hh = hh_; asm volatile("" : "+v"(hh_));
; #pragma unroll
;         for (int r = 0; r < 16; ++r) cv[r] = g_ * (1.f / QK_SCL) * (float)(CR(r) + 4 * hh_); }
; template <int NDT, int NMAP, class F> ...
;     ...
;     LAS unsigned char* b0 = sbuf; LAS unsigned char* b1 = sbuf + Gm::TB;
;     CP_LOAD(0, step_last); if (step_last >= 1) CP_LOAD(1, step_last - 1);
;     const int t0u = __builtin_amdgcn_readfirstlane(t0_mine);
;     f.fetch2(t0u >> 6);
;     CP_PARK(0, b0);
;     CP_BAR();
	v_mul_f32_e32 v26, v38, v39
	ds_swizzle_b32 v30, v26 offset:swizzle(SWAP,1)
	v_mad_u64_u32 v[26:27], s[12:13], s16, v237, v[178:179]
	s_lshl_b32 s12, s11, 6
	s_mov_b64 s[16:17], 0x2200
	s_waitcnt lgkmcnt(0)
	v_fmac_f32_e32 v30, v38, v39
	ds_swizzle_b32 v31, v30 offset:swizzle(SWAP,2)
	v_lshl_add_u64 v[28:29], v[22:23], 0, s[16:17]
	v_add_co_u32_e32 v22, vcc, s35, v22
	v_lshl_add_u64 v[26:27], v[26:27], 1, s[14:15]
	s_waitcnt lgkmcnt(0)
	v_add_f32_e32 v30, v30, v31
	ds_swizzle_b32 v31, v30 offset:swizzle(SWAP,4)
	v_addc_co_u32_e32 v23, vcc, 0, v23, vcc
	v_cmp_gt_u32_e64 s[60:61], v53, v42
	v_cmp_gt_u32_e64 s[62:63], v54, v42
	s_waitcnt lgkmcnt(0)
	v_add_f32_e32 v34, v30, v31
	ds_swizzle_b32 v35, v34 offset:swizzle(SWAP,8)
	v_mad_u64_u32 v[30:31], s[12:13], s12, v237, v[178:179]
	s_lshl_b64 s[12:13], s[18:19], 12
	s_nop 0
	v_lshl_add_u64 v[32:33], v[180:181], 0, s[12:13]
	s_waitcnt lgkmcnt(0)
	v_add_f32_e32 v38, v34, v35
	ds_swizzle_b32 v39, v38 offset:swizzle(SWAP,16)
	v_lshl_add_u64 v[30:31], v[30:31], 1, s[14:15]
	v_add_co_u32_e32 v34, vcc, s20, v32
	s_lshl_b32 s12, s4, 2
	s_waitcnt lgkmcnt(0)
	v_add_f32_e32 v198, v38, v39
	v_mov_b32_e32 v199, v198
	v_addc_co_u32_e32 v35, vcc, 0, v33, vcc
	s_load_dwordx2 s[16:17], s[0:1], 0x60
	global_load_dwordx4 v[116:119], v[30:31], off
	global_load_dwordx4 v[120:123], v[30:31], off offset:128
	global_load_dwordx4 v[124:127], v[32:33], off
	global_load_dwordx4 v[128:131], v[34:35], off
	global_load_dwordx4 v[100:103], v[28:29], off offset:32
	global_load_dwordx4 v[104:107], v[28:29], off offset:64
	global_load_dwordx4 v[108:111], v[22:23], off offset:512
	global_load_dwordx4 v[112:115], v[28:29], off offset:96
	global_load_dwordx4 v[144:147], v[24:25], off
	global_load_dwordx4 v[140:143], v[20:21], off
	global_load_dwordx4 v[132:135], v[26:27], off offset:128
	global_load_dwordx4 v[136:139], v[26:27], off
	v_or_b32_e32 v20, 27, v43
	v_cmp_gt_u32_e64 s[68:69], v20, v42
	s_lshl_b32 s4, s4, 7
	v_subrev_u32_e32 v20, s5, v36
	v_subrev_u32_e32 v20, s4, v20
	v_add_u32_e32 v201, 0xf20, v20
	v_lshlrev_b32_e32 v20, 2, v37
	v_or_b32_e32 v21, 1, v20
	v_or_b32_e32 v22, 3, v20
	v_or_b32_e32 v24, 2, v20
	v_add_u32_e32 v26, 8, v20
	v_add_u32_e32 v25, 9, v20
	v_add_u32_e32 v28, 10, v20
	v_add_u32_e32 v27, 11, v20
	v_add_u32_e32 v30, 16, v20
	v_add_u32_e32 v29, 17, v20
	v_add_u32_e32 v36, 18, v20
	v_add_u32_e32 v31, 19, v20
	v_add_u32_e32 v32, 24, v20
	v_add_u32_e32 v33, 25, v20
	v_add_u32_e32 v34, 26, v20
	v_add_u32_e32 v35, 27, v20
	v_cvt_f32_i32_e32 v20, v20
	v_cvt_f32_i32_e32 v23, v22
	v_cvt_f32_i32_e32 v22, v24
	v_cvt_f32_i32_e32 v21, v21
	v_cvt_f32_i32_e32 v25, v25
	v_cvt_f32_i32_e32 v24, v26
	v_cvt_f32_i32_e32 v27, v27
	v_cvt_f32_i32_e32 v26, v28
	v_cvt_f32_i32_e32 v29, v29
	v_cvt_f32_i32_e32 v28, v30
	v_cvt_f32_i32_e32 v31, v31
	v_cvt_f32_i32_e32 v33, v33
	v_cvt_f32_i32_e32 v35, v35
	v_cvt_f32_i32_e32 v34, v34
	v_cvt_f32_i32_e32 v32, v32
	v_cvt_f32_i32_e32 v30, v36
	v_cmp_gt_u32_e64 s[64:65], v55, v42
	v_cmp_gt_u32_e64 s[66:67], v56, v42
	v_sub_u32_e32 v200, s4, v40
	v_mul_f32_e32 v70, v174, v22
	v_mul_f32_e32 v71, v175, v23
	v_mul_f32_e32 v82, v174, v34
	v_mul_f32_e32 v83, v175, v35
	v_mul_f32_e32 v80, v174, v32
	v_mul_f32_e32 v81, v175, v33
	v_mul_f32_e32 v78, v174, v30
	v_mul_f32_e32 v79, v175, v31
	v_mul_f32_e32 v76, v174, v28
	v_mul_f32_e32 v77, v175, v29
	v_mul_f32_e32 v74, v174, v26
	v_mul_f32_e32 v75, v175, v27
	v_mul_f32_e32 v72, v174, v24
	v_mul_f32_e32 v73, v175, v25
	v_mul_f32_e32 v68, v176, v20
	v_mul_f32_e32 v69, v177, v21
	v_add_u32_e32 v175, 0, v41
	v_mov_b64_e32 v[34:35], v[18:19]
	v_mov_b64_e32 v[50:51], v[18:19]
	v_mov_b64_e32 v[66:67], v[18:19]
	s_sub_i32 s22, 0x78, s12
	s_add_i32 s25, s5, 0xffffff80
	v_permlane32_swap_b32_e32 v188, v189
	v_permlane32_swap_b32_e32 v198, v199
	v_mov_b64_e32 v[32:33], v[16:17]
	v_mov_b64_e32 v[30:31], v[14:15]
	v_mov_b64_e32 v[28:29], v[12:13]
	v_mov_b64_e32 v[26:27], v[10:11]
	s_waitcnt vmcnt(11)
	ds_write_b128 v190, v[116:119]
	s_waitcnt vmcnt(10)
	ds_write_b128 v190, v[120:123] offset:8192
	s_waitcnt vmcnt(9)
	ds_write_b128 v191, v[124:127] offset:16384
	s_waitcnt vmcnt(8)
	ds_write_b128 v191, v[128:131] offset:24576
	s_waitcnt lgkmcnt(0)
	s_barrier
	v_mov_b64_e32 v[24:25], v[8:9]
	v_mov_b64_e32 v[22:23], v[6:7]
	v_mov_b64_e32 v[20:21], v[4:5]
	v_mov_b64_e32 v[48:49], v[16:17]
	v_mov_b64_e32 v[46:47], v[14:15]
	v_mov_b64_e32 v[44:45], v[12:13]
	v_mov_b64_e32 v[42:43], v[10:11]
	v_mov_b64_e32 v[40:41], v[8:9]
	v_mov_b64_e32 v[38:39], v[6:7]
	v_mov_b64_e32 v[36:37], v[4:5]
	v_mov_b64_e32 v[64:65], v[16:17]
	v_mov_b64_e32 v[62:63], v[14:15]
	v_mov_b64_e32 v[60:61], v[12:13]
	v_mov_b64_e32 v[58:59], v[10:11]
	v_mov_b64_e32 v[56:57], v[8:9]
	v_mov_b64_e32 v[54:55], v[6:7]
	v_mov_b64_e32 v[52:53], v[4:5]
	s_branch .LBB0_559

; #define LAS __attribute__((address_space(3)))
; __device__ __forceinline__ unsigned cvtpk(float lo, float hi) { f32x2_t v = {lo, hi}; bf16x2_t b = __builtin_convertvector(v, bf16x2_t); return __builtin_bit_cast(unsigned, b); }
; #define MFMA32(a, b, c) __builtin_amdgcn_mfma_f32_32x32x16_bf16((a), (b), (c), 0, 0, 0)
; template <int NDT, class F>
; __device__ __forceinline__ void softmax_body(f32x16& s, const F& f, int k0, int hh, f32x16 (&o)[NDT], float& m, float& l, bf16x8& pf0, bf16x8& pf1, const int MASK) {
;     ...
;     const float me = fmaxf(m, -1e29f);
;     const float off = on ? f.tadd - me : NEG_BIG;
;     const f32x2_t sc2 = {QK_SCL, QK_SCL}, of2 = {off, off}; f32x2_t ps2 = {0.f, 0.f};
; #pragma unroll
;     for (int r = 0; r < 16; r += 2) { f32x2_t a = {s[r], s[r + 1]}; a = __builtin_elementwise_fma(a, sc2, of2);
;         f32x2_t p; p.x = __builtin_amdgcn_exp2f(a.x); p.y = __builtin_amdgcn_exp2f(a.y); s[r] = p.x; s[r + 1] = p.y; ps2 += p; }
;     l += ps2.x + ps2.y;
;     v4u p0, p1;
;     p0.x = cvtpk(s[0], s[1]); p0.y = cvtpk(s[2], s[3]); p0.z = cvtpk(s[4], s[5]); p0.w = cvtpk(s[6], s[7]);
;     p1.x = cvtpk(s[8], s[9]); p1.y = cvtpk(s[10], s[11]); p1.z = cvtpk(s[12], s[13]); p1.w = cvtpk(s[14], s[15]);
;     pf0 = __builtin_bit_cast(bf16x8, p0); pf1 = __builtin_bit_cast(bf16x8, p1);
; template <int NDT, bool MASK, class F>
; __device__ __forceinline__ void att_compute_lds(const bf16x8 (&qf)[4], const LAS unsigned char* cur, int fk, int fv, const F& f, int k0, int hh, f32x16 (&o)[NDT], float& m, float& l) {
;     ...
; #pragma unroll
;     for (int dt = 0; dt < NDT; ++dt) { bf16x8 vb0 = va0, vb1 = va1;
;         if (dt + 1 < NDT) { vb0 = *(const LAS bf16x8*)(cur + (dt + 1) * 2048 + fv); vb1 = *(const LAS bf16x8*)(cur + (dt + 1) * 2048 + (fv ^ 32)); __builtin_amdgcn_sched_barrier(0); }
;         o[dt] = MFMA32(va0, pf0, o[dt]); o[dt] = MFMA32(va1, pf1, o[dt]); va0 = vb0; va1 = vb1; }
.LBB0_565:
	v_max_f32_e32 v156, v202, v202
	v_max_f32_e32 v156, 0xefa18f08, v156
	v_sub_f32_e32 v156, v204, v156
	v_fma_f32 v84, v84, s34, v156
	v_fma_f32 v85, v85, s34, v156
	v_fma_f32 v86, v86, s34, v156
	v_fma_f32 v87, v87, s34, v156
	v_exp_f32_e32 v84, v84
	v_exp_f32_e32 v85, v85
	v_exp_f32_e32 v86, v86
	v_exp_f32_e32 v87, v87
	v_fma_f32 v88, v88, s34, v156
	v_fma_f32 v89, v89, s34, v156
	v_fma_f32 v90, v90, s34, v156
	v_fma_f32 v91, v91, s34, v156
	v_exp_f32_e32 v88, v88
	v_exp_f32_e32 v89, v89
	v_exp_f32_e32 v90, v90
	v_exp_f32_e32 v91, v91
	v_fma_f32 v92, v92, s34, v156
	v_fma_f32 v93, v93, s34, v156
	v_pk_add_f32 v[158:159], v[84:85], 0 op_sel_hi:[1,0]
	v_exp_f32_e32 v160, v92
	v_exp_f32_e32 v161, v93
	v_fma_f32 v92, v94, s34, v156
	v_fma_f32 v93, v95, s34, v156
	v_add_f32_e32 v158, v86, v158
	v_add_f32_e32 v159, v87, v159
	v_exp_f32_e32 v162, v92
	v_exp_f32_e32 v163, v93
	v_fma_f32 v92, v96, s34, v156
	v_fma_f32 v93, v97, s34, v156
	v_add_f32_e32 v158, v88, v158
	v_add_f32_e32 v159, v89, v159
	v_exp_f32_e32 v164, v92
	v_exp_f32_e32 v165, v93
	v_fma_f32 v92, v98, s34, v156
	v_fma_f32 v93, v99, s34, v156
	v_add_f32_e32 v158, v90, v158
	v_add_f32_e32 v159, v91, v159
	v_exp_f32_e32 v156, v92
	v_exp_f32_e32 v157, v93
	v_add_f32_e32 v92, v160, v158
	v_add_f32_e32 v93, v161, v159
	v_cvt_pk_bf16_f32 v84, v84, v85
	v_add_f32_e32 v92, v162, v92
	v_add_f32_e32 v93, v163, v93
	v_cvt_pk_bf16_f32 v85, v86, v87
	v_add_f32_e32 v92, v164, v92
	v_add_f32_e32 v93, v165, v93
	v_cvt_pk_bf16_f32 v86, v88, v89
	v_add_f32_e32 v92, v156, v92
	v_add_f32_e32 v93, v157, v93
	v_cvt_pk_bf16_f32 v87, v90, v91
	v_add_f32_e32 v92, v92, v93
	v_add_f32_e32 v187, v187, v92
	ds_read_b128 v[88:91], v196 offset:26624
	ds_read_b128 v[92:95], v175 offset:26624
	v_cvt_pk_bf16_f32 v96, v160, v161
	v_cvt_pk_bf16_f32 v97, v162, v163
	v_cvt_pk_bf16_f32 v98, v164, v165
	v_cvt_pk_bf16_f32 v99, v156, v157
	v_mfma_f32_32x32x16_bf16 v[52:67], v[148:151], v[84:87], v[52:67]
	s_nop 0
	v_mfma_f32_32x32x16_bf16 v[52:67], v[152:155], v[96:99], v[52:67]
	ds_read_b128 v[148:151], v196 offset:28672
	ds_read_b128 v[152:155], v175 offset:28672
	s_waitcnt lgkmcnt(3)
	v_mfma_f32_32x32x16_bf16 v[36:51], v[88:91], v[84:87], v[36:51]
	s_waitcnt lgkmcnt(2)
	v_mfma_f32_32x32x16_bf16 v[36:51], v[92:95], v[96:99], v[36:51]
	ds_read_b128 v[88:91], v196 offset:30720
	ds_read_b128 v[92:95], v175 offset:30720
	s_waitcnt lgkmcnt(3)
	v_mfma_f32_32x32x16_bf16 v[20:35], v[148:151], v[84:87], v[20:35]
	s_waitcnt lgkmcnt(1)
	v_mfma_f32_32x32x16_bf16 v[4:19], v[88:91], v[84:87], v[4:19]
	v_mfma_f32_32x32x16_bf16 v[20:35], v[152:155], v[96:99], v[20:35]
	s_waitcnt lgkmcnt(0)
	v_mfma_f32_32x32x16_bf16 v[4:19], v[92:95], v[96:99], v[4:19]

; #define LAS __attribute__((address_space(3)))
; __device__ __forceinline__ unsigned cvtpk(float lo, float hi) { f32x2_t v = {lo, hi}; bf16x2_t b = __builtin_convertvector(v, bf16x2_t); return __builtin_bit_cast(unsigned, b); }
; #define MFMA32(a, b, c) __builtin_amdgcn_mfma_f32_32x32x16_bf16((a), (b), (c), 0, 0, 0)
; template <int NDT, class F>
; __device__ __forceinline__ void softmax_body(f32x16& s, const F& f, int k0, int hh, f32x16 (&o)[NDT], float& m, float& l, bf16x8& pf0, bf16x8& pf1, const int MASK) {
;     ...
;     const float me = fmaxf(m, -1e29f);
;     const float off = on ? f.tadd - me : NEG_BIG;
;     const f32x2_t sc2 = {QK_SCL, QK_SCL}, of2 = {off, off}; f32x2_t ps2 = {0.f, 0.f};
; #pragma unroll
;     for (int r = 0; r < 16; r += 2) { f32x2_t a = {s[r], s[r + 1]}; a = __builtin_elementwise_fma(a, sc2, of2);
;         f32x2_t p; p.x = __builtin_amdgcn_exp2f(a.x); p.y = __builtin_amdgcn_exp2f(a.y); s[r] = p.x; s[r + 1] = p.y; ps2 += p; }
;     l += ps2.x + ps2.y;
;     v4u p0, p1;
;     p0.x = cvtpk(s[0], s[1]); p0.y = cvtpk(s[2], s[3]); p0.z = cvtpk(s[4], s[5]); p0.w = cvtpk(s[6], s[7]);
;     p1.x = cvtpk(s[8], s[9]); p1.y = cvtpk(s[10], s[11]); p1.z = cvtpk(s[12], s[13]); p1.w = cvtpk(s[14], s[15]);
;     pf0 = __builtin_bit_cast(bf16x8, p0); pf1 = __builtin_bit_cast(bf16x8, p1);
; template <int NDT, bool MASK, class F>
; __device__ __forceinline__ void att_compute_lds(const bf16x8 (&qf)[4], const LAS unsigned char* cur, int fk, int fv, const F& f, int k0, int hh, f32x16 (&o)[NDT], float& m, float& l) {
;     ...
; #pragma unroll
;     for (int dt = 0; dt < NDT; ++dt) { bf16x8 vb0 = va0, vb1 = va1;
;         if (dt + 1 < NDT) { vb0 = *(const LAS bf16x8*)(cur + (dt + 1) * 2048 + fv); vb1 = *(const LAS bf16x8*)(cur + (dt + 1) * 2048 + (fv ^ 32)); __builtin_amdgcn_sched_barrier(0); }
;         o[dt] = MFMA32(va0, pf0, o[dt]); o[dt] = MFMA32(va1, pf1, o[dt]); va0 = vb0; va1 = vb1; }
.LBB0_569:
	v_max_f32_e32 v92, v202, v202
	v_max_f32_e32 v92, 0xefa18f08, v92
	v_sub_f32_e32 v92, v204, v92
	v_fma_f32 v94, v162, s34, v92
	v_fma_f32 v95, v163, s34, v92
	v_fma_f32 v98, v160, s34, v92
	v_fma_f32 v99, v161, s34, v92
	v_exp_f32_e32 v94, v94
	v_exp_f32_e32 v95, v95
	v_exp_f32_e32 v98, v98
	v_exp_f32_e32 v99, v99
	v_fma_f32 v158, v158, s34, v92
	v_fma_f32 v159, v159, s34, v92
	v_fma_f32 v156, v156, s34, v92
	v_fma_f32 v157, v157, s34, v92
	v_exp_f32_e32 v158, v158
	v_exp_f32_e32 v159, v159
	v_exp_f32_e32 v156, v156
	v_exp_f32_e32 v157, v157
	v_fma_f32 v90, v90, s34, v92
	v_fma_f32 v91, v91, s34, v92
	v_pk_add_f32 v[96:97], v[94:95], 0 op_sel_hi:[1,0]
	v_exp_f32_e32 v90, v90
	v_exp_f32_e32 v91, v91
	v_fma_f32 v88, v88, s34, v92
	v_fma_f32 v89, v89, s34, v92
	v_add_f32_e32 v96, v98, v96
	v_add_f32_e32 v97, v99, v97
	v_exp_f32_e32 v160, v88
	v_exp_f32_e32 v161, v89
	v_add_f32_e32 v96, v158, v96
	v_add_f32_e32 v97, v159, v97
	v_fma_f32 v86, v86, s34, v92
	v_fma_f32 v87, v87, s34, v92
	v_add_f32_e32 v96, v156, v96
	v_add_f32_e32 v97, v157, v97
	v_fma_f32 v84, v84, s34, v92
	v_fma_f32 v85, v85, s34, v92
	v_add_f32_e32 v96, v90, v96
	v_add_f32_e32 v97, v91, v97
	v_exp_f32_e32 v92, v84
	v_add_f32_e32 v88, v160, v96
	v_add_f32_e32 v89, v161, v97
	v_exp_f32_e32 v96, v86
	v_exp_f32_e32 v97, v87
	v_exp_f32_e32 v93, v85
	v_add_f32_e32 v86, v96, v88
	v_add_f32_e32 v87, v97, v89
	s_nop 0
	v_add_f32_e32 v84, v92, v86
	v_add_f32_e32 v85, v93, v87
	v_cvt_pk_bf16_f32 v88, v90, v91
	v_add_f32_e32 v84, v84, v85
	v_add_f32_e32 v187, v187, v84
	v_cvt_pk_bf16_f32 v84, v94, v95
	v_cvt_pk_bf16_f32 v85, v98, v99
	v_cvt_pk_bf16_f32 v90, v96, v97
	v_cvt_pk_bf16_f32 v91, v92, v93
	ds_read_b128 v[92:95], v196 offset:26624
	ds_read_b128 v[96:99], v175 offset:26624
	v_cvt_pk_bf16_f32 v86, v158, v159
	v_cvt_pk_bf16_f32 v87, v156, v157
	v_cvt_pk_bf16_f32 v89, v160, v161
	s_nop 0
	v_mfma_f32_32x32x16_bf16 v[52:67], v[148:151], v[84:87], v[52:67]
	v_mfma_f32_32x32x16_bf16 v[52:67], v[152:155], v[88:91], v[52:67]
	ds_read_b128 v[148:151], v196 offset:28672
	ds_read_b128 v[152:155], v175 offset:28672
	s_waitcnt lgkmcnt(3)
	v_mfma_f32_32x32x16_bf16 v[36:51], v[92:95], v[84:87], v[36:51]
	s_waitcnt lgkmcnt(2)
	v_mfma_f32_32x32x16_bf16 v[36:51], v[96:99], v[88:91], v[36:51]
	ds_read_b128 v[92:95], v196 offset:30720
	ds_read_b128 v[96:99], v175 offset:30720
	s_waitcnt lgkmcnt(3)
	v_mfma_f32_32x32x16_bf16 v[20:35], v[148:151], v[84:87], v[20:35]
	s_waitcnt lgkmcnt(1)
	v_mfma_f32_32x32x16_bf16 v[4:19], v[92:95], v[84:87], v[4:19]
	v_mfma_f32_32x32x16_bf16 v[20:35], v[152:155], v[88:91], v[20:35]
	s_waitcnt lgkmcnt(0)
	v_mfma_f32_32x32x16_bf16 v[4:19], v[96:99], v[88:91], v[4:19]

; #define LAS __attribute__((address_space(3)))
; __device__ __forceinline__ unsigned cvtpk(float lo, float hi) { f32x2_t v = {lo, hi}; bf16x2_t b = __builtin_convertvector(v, bf16x2_t); return __builtin_bit_cast(unsigned, b); }
; #define MFMA32(a, b, c) __builtin_amdgcn_mfma_f32_32x32x16_bf16((a), (b), (c), 0, 0, 0)
; template <int NDT, class F>
; __device__ __forceinline__ void softmax_body(f32x16& s, const F& f, int k0, int hh, f32x16 (&o)[NDT], float& m, float& l, bf16x8& pf0, bf16x8& pf1, const int MASK) {
;     ...
;     const float me = fmaxf(m, -1e29f);
;     const float off = on ? f.tadd - me : NEG_BIG;
;     const f32x2_t sc2 = {QK_SCL, QK_SCL}, of2 = {off, off}; f32x2_t ps2 = {0.f, 0.f};
; #pragma unroll
;     for (int r = 0; r < 16; r += 2) { f32x2_t a = {s[r], s[r + 1]}; a = __builtin_elementwise_fma(a, sc2, of2);
;         f32x2_t p; p.x = __builtin_amdgcn_exp2f(a.x); p.y = __builtin_amdgcn_exp2f(a.y); s[r] = p.x; s[r + 1] = p.y; ps2 += p; }
;     l += ps2.x + ps2.y;
;     v4u p0, p1;
;     p0.x = cvtpk(s[0], s[1]); p0.y = cvtpk(s[2], s[3]); p0.z = cvtpk(s[4], s[5]); p0.w = cvtpk(s[6], s[7]);
;     p1.x = cvtpk(s[8], s[9]); p1.y = cvtpk(s[10], s[11]); p1.z = cvtpk(s[12], s[13]); p1.w = cvtpk(s[14], s[15]);
;     pf0 = __builtin_bit_cast(bf16x8, p0); pf1 = __builtin_bit_cast(bf16x8, p1);
; template <int NDT, bool MASK, class F>
; __device__ __forceinline__ void att_compute_lds(const bf16x8 (&qf)[4], const LAS unsigned char* cur, int fk, int fv, const F& f, int k0, int hh, f32x16 (&o)[NDT], float& m, float& l) {
;     ...
; #pragma unroll
;     for (int dt = 0; dt < NDT; ++dt) { bf16x8 vb0 = va0, vb1 = va1;
;         if (dt + 1 < NDT) { vb0 = *(const LAS bf16x8*)(cur + (dt + 1) * 2048 + fv); vb1 = *(const LAS bf16x8*)(cur + (dt + 1) * 2048 + (fv ^ 32)); __builtin_amdgcn_sched_barrier(0); }
;         o[dt] = MFMA32(va0, pf0, o[dt]); o[dt] = MFMA32(va1, pf1, o[dt]); va0 = vb0; va1 = vb1; }
.LBB0_575:
	v_max_f32_e32 v156, v202, v202
	v_max_f32_e32 v156, 0xefa18f08, v156
	v_sub_f32_e32 v156, v204, v156
	v_fma_f32 v84, v84, s34, v156
	v_fma_f32 v85, v85, s34, v156
	v_fma_f32 v86, v86, s34, v156
	v_fma_f32 v87, v87, s34, v156
	v_exp_f32_e32 v84, v84
	v_exp_f32_e32 v85, v85
	v_exp_f32_e32 v86, v86
	v_exp_f32_e32 v87, v87
	v_fma_f32 v88, v88, s34, v156
	v_fma_f32 v89, v89, s34, v156
	v_fma_f32 v90, v90, s34, v156
	v_fma_f32 v91, v91, s34, v156
	v_exp_f32_e32 v88, v88
	v_exp_f32_e32 v89, v89
	v_exp_f32_e32 v90, v90
	v_exp_f32_e32 v91, v91
	v_fma_f32 v92, v92, s34, v156
	v_fma_f32 v93, v93, s34, v156
	v_pk_add_f32 v[158:159], v[84:85], 0 op_sel_hi:[1,0]
	v_exp_f32_e32 v160, v92
	v_exp_f32_e32 v161, v93
	v_fma_f32 v92, v94, s34, v156
	v_fma_f32 v93, v95, s34, v156
	v_add_f32_e32 v158, v86, v158
	v_add_f32_e32 v159, v87, v159
	v_exp_f32_e32 v162, v92
	v_exp_f32_e32 v163, v93
	v_fma_f32 v92, v96, s34, v156
	v_fma_f32 v93, v97, s34, v156
	v_add_f32_e32 v158, v88, v158
	v_add_f32_e32 v159, v89, v159
	v_exp_f32_e32 v164, v92
	v_exp_f32_e32 v165, v93
	v_fma_f32 v92, v98, s34, v156
	v_fma_f32 v93, v99, s34, v156
	v_add_f32_e32 v158, v90, v158
	v_add_f32_e32 v159, v91, v159
	v_exp_f32_e32 v156, v92
	v_exp_f32_e32 v157, v93
	v_add_f32_e32 v92, v160, v158
	v_add_f32_e32 v93, v161, v159
	v_cvt_pk_bf16_f32 v84, v84, v85
	v_add_f32_e32 v92, v162, v92
	v_add_f32_e32 v93, v163, v93
	v_cvt_pk_bf16_f32 v85, v86, v87
	v_add_f32_e32 v92, v164, v92
	v_add_f32_e32 v93, v165, v93
	v_cvt_pk_bf16_f32 v86, v88, v89
	v_add_f32_e32 v92, v156, v92
	v_add_f32_e32 v93, v157, v93
	v_cvt_pk_bf16_f32 v87, v90, v91
	v_add_f32_e32 v92, v92, v93
	v_add_f32_e32 v187, v187, v92
	ds_read_b128 v[88:91], v196 offset:18432
	ds_read_b128 v[92:95], v175 offset:18432
	v_cvt_pk_bf16_f32 v96, v160, v161
	v_cvt_pk_bf16_f32 v97, v162, v163
	v_cvt_pk_bf16_f32 v98, v164, v165
	v_cvt_pk_bf16_f32 v99, v156, v157
	s_waitcnt lgkmcnt(3)
	v_mfma_f32_32x32x16_bf16 v[52:67], v[148:151], v[84:87], v[52:67]
	s_waitcnt lgkmcnt(2)
	v_mfma_f32_32x32x16_bf16 v[52:67], v[152:155], v[96:99], v[52:67]
	ds_read_b128 v[148:151], v196 offset:20480
	ds_read_b128 v[152:155], v175 offset:20480
	s_waitcnt lgkmcnt(3)
	v_mfma_f32_32x32x16_bf16 v[36:51], v[88:91], v[84:87], v[36:51]
	s_waitcnt lgkmcnt(2)
	v_mfma_f32_32x32x16_bf16 v[36:51], v[92:95], v[96:99], v[36:51]
	ds_read_b128 v[88:91], v196 offset:22528
	ds_read_b128 v[92:95], v175 offset:22528
	s_waitcnt lgkmcnt(3)
	v_mfma_f32_32x32x16_bf16 v[20:35], v[148:151], v[84:87], v[20:35]
	s_waitcnt lgkmcnt(1)
	v_mfma_f32_32x32x16_bf16 v[4:19], v[88:91], v[84:87], v[4:19]
	v_mfma_f32_32x32x16_bf16 v[20:35], v[152:155], v[96:99], v[20:35]
	s_waitcnt lgkmcnt(0)
	v_mfma_f32_32x32x16_bf16 v[4:19], v[92:95], v[96:99], v[4:19]

; #define LAS __attribute__((address_space(3)))
; __device__ __forceinline__ unsigned cvtpk(float lo, float hi) { f32x2_t v = {lo, hi}; bf16x2_t b = __builtin_convertvector(v, bf16x2_t); return __builtin_bit_cast(unsigned, b); }
; #define MFMA32(a, b, c) __builtin_amdgcn_mfma_f32_32x32x16_bf16((a), (b), (c), 0, 0, 0)
; template <int NDT, class F>
; __device__ __forceinline__ void softmax_body(f32x16& s, const F& f, int k0, int hh, f32x16 (&o)[NDT], float& m, float& l, bf16x8& pf0, bf16x8& pf1, const int MASK) {
;     ...
;     const float me = fmaxf(m, -1e29f);
;     const float off = on ? f.tadd - me : NEG_BIG;
;     const f32x2_t sc2 = {QK_SCL, QK_SCL}, of2 = {off, off}; f32x2_t ps2 = {0.f, 0.f};
; #pragma unroll
;     for (int r = 0; r < 16; r += 2) { f32x2_t a = {s[r], s[r + 1]}; a = __builtin_elementwise_fma(a, sc2, of2);
;         f32x2_t p; p.x = __builtin_amdgcn_exp2f(a.x); p.y = __builtin_amdgcn_exp2f(a.y); s[r] = p.x; s[r + 1] = p.y; ps2 += p; }
;     l += ps2.x + ps2.y;
;     v4u p0, p1;
;     p0.x = cvtpk(s[0], s[1]); p0.y = cvtpk(s[2], s[3]); p0.z = cvtpk(s[4], s[5]); p0.w = cvtpk(s[6], s[7]);
;     p1.x = cvtpk(s[8], s[9]); p1.y = cvtpk(s[10], s[11]); p1.z = cvtpk(s[12], s[13]); p1.w = cvtpk(s[14], s[15]);
;     pf0 = __builtin_bit_cast(bf16x8, p0); pf1 = __builtin_bit_cast(bf16x8, p1);
; template <int NDT, bool MASK, class F>
; __device__ __forceinline__ void att_compute_lds(const bf16x8 (&qf)[4], const LAS unsigned char* cur, int fk, int fv, const F& f, int k0, int hh, f32x16 (&o)[NDT], float& m, float& l) {
;     ...
; #pragma unroll
;     for (int dt = 0; dt < NDT; ++dt) { bf16x8 vb0 = va0, vb1 = va1;
;         if (dt + 1 < NDT) { vb0 = *(const LAS bf16x8*)(cur + (dt + 1) * 2048 + fv); vb1 = *(const LAS bf16x8*)(cur + (dt + 1) * 2048 + (fv ^ 32)); __builtin_amdgcn_sched_barrier(0); }
;         o[dt] = MFMA32(va0, pf0, o[dt]); o[dt] = MFMA32(va1, pf1, o[dt]); va0 = vb0; va1 = vb1; }
.LBB0_579:
	v_max_f32_e32 v92, v202, v202
	v_max_f32_e32 v92, 0xefa18f08, v92
	v_sub_f32_e32 v92, v204, v92
	v_fma_f32 v94, v162, s34, v92
	v_fma_f32 v95, v163, s34, v92
	v_fma_f32 v98, v160, s34, v92
	v_fma_f32 v99, v161, s34, v92
	v_exp_f32_e32 v94, v94
	v_exp_f32_e32 v95, v95
	v_exp_f32_e32 v98, v98
	v_exp_f32_e32 v99, v99
	v_fma_f32 v158, v158, s34, v92
	v_fma_f32 v159, v159, s34, v92
	v_fma_f32 v156, v156, s34, v92
	v_fma_f32 v157, v157, s34, v92
	v_exp_f32_e32 v158, v158
	v_exp_f32_e32 v159, v159
	v_exp_f32_e32 v156, v156
	v_exp_f32_e32 v157, v157
	v_fma_f32 v90, v90, s34, v92
	v_fma_f32 v91, v91, s34, v92
	v_pk_add_f32 v[96:97], v[94:95], 0 op_sel_hi:[1,0]
	v_exp_f32_e32 v90, v90
	v_exp_f32_e32 v91, v91
	v_fma_f32 v88, v88, s34, v92
	v_fma_f32 v89, v89, s34, v92
	v_add_f32_e32 v96, v98, v96
	v_add_f32_e32 v97, v99, v97
	v_exp_f32_e32 v160, v88
	v_exp_f32_e32 v161, v89
	v_add_f32_e32 v96, v158, v96
	v_add_f32_e32 v97, v159, v97
	v_fma_f32 v86, v86, s34, v92
	v_fma_f32 v87, v87, s34, v92
	v_add_f32_e32 v96, v156, v96
	v_add_f32_e32 v97, v157, v97
	v_fma_f32 v84, v84, s34, v92
	v_fma_f32 v85, v85, s34, v92
	v_add_f32_e32 v96, v90, v96
	v_add_f32_e32 v97, v91, v97
	v_exp_f32_e32 v92, v84
	v_add_f32_e32 v88, v160, v96
	v_add_f32_e32 v89, v161, v97
	v_exp_f32_e32 v96, v86
	v_exp_f32_e32 v97, v87
	v_exp_f32_e32 v93, v85
	v_add_f32_e32 v86, v96, v88
	v_add_f32_e32 v87, v97, v89
	s_nop 0
	v_add_f32_e32 v84, v92, v86
	v_add_f32_e32 v85, v93, v87
	v_cvt_pk_bf16_f32 v88, v90, v91
	v_add_f32_e32 v84, v84, v85
	v_add_f32_e32 v187, v187, v84
	v_cvt_pk_bf16_f32 v84, v94, v95
	v_cvt_pk_bf16_f32 v85, v98, v99
	v_cvt_pk_bf16_f32 v90, v96, v97
	v_cvt_pk_bf16_f32 v91, v92, v93
	ds_read_b128 v[92:95], v196 offset:18432
	ds_read_b128 v[96:99], v175 offset:18432
	v_cvt_pk_bf16_f32 v86, v158, v159
	v_cvt_pk_bf16_f32 v87, v156, v157
	v_cvt_pk_bf16_f32 v89, v160, v161
	s_waitcnt lgkmcnt(3)
	v_mfma_f32_32x32x16_bf16 v[52:67], v[148:151], v[84:87], v[52:67]
	s_waitcnt lgkmcnt(2)
	v_mfma_f32_32x32x16_bf16 v[52:67], v[152:155], v[88:91], v[52:67]
	ds_read_b128 v[148:151], v196 offset:20480
	ds_read_b128 v[152:155], v175 offset:20480
	s_waitcnt lgkmcnt(3)
	v_mfma_f32_32x32x16_bf16 v[36:51], v[92:95], v[84:87], v[36:51]
	s_waitcnt lgkmcnt(2)
	v_mfma_f32_32x32x16_bf16 v[36:51], v[96:99], v[88:91], v[36:51]
	ds_read_b128 v[92:95], v196 offset:22528
	ds_read_b128 v[96:99], v175 offset:22528
	s_waitcnt lgkmcnt(3)
	v_mfma_f32_32x32x16_bf16 v[20:35], v[148:151], v[84:87], v[20:35]
	s_waitcnt lgkmcnt(1)
	v_mfma_f32_32x32x16_bf16 v[4:19], v[92:95], v[84:87], v[4:19]
	v_mfma_f32_32x32x16_bf16 v[20:35], v[152:155], v[88:91], v[20:35]
	s_waitcnt lgkmcnt(0)
	v_mfma_f32_32x32x16_bf16 v[4:19], v[96:99], v[88:91], v[4:19]

; #define LAS __attribute__((address_space(3)))
; __device__ __forceinline__ unsigned cvtpk(float lo, float hi) { f32x2_t v = {lo, hi}; bf16x2_t b = __builtin_convertvector(v, bf16x2_t); return __builtin_bit_cast(unsigned, b); }
; #define MFMA32(a, b, c) __builtin_amdgcn_mfma_f32_32x32x16_bf16((a), (b), (c), 0, 0, 0)
; template <int NDT, class F>
; __device__ __forceinline__ void softmax_body(f32x16& s, const F& f, int k0, int hh, f32x16 (&o)[NDT], float& m, float& l, bf16x8& pf0, bf16x8& pf1, const int MASK) {
;     ...
;     const float me = fmaxf(m, -1e29f);
;     const float off = on ? f.tadd - me : NEG_BIG;
;     const f32x2_t sc2 = {QK_SCL, QK_SCL}, of2 = {off, off}; f32x2_t ps2 = {0.f, 0.f};
; #pragma unroll
;     for (int r = 0; r < 16; r += 2) { f32x2_t a = {s[r], s[r + 1]}; a = __builtin_elementwise_fma(a, sc2, of2);
;         f32x2_t p; p.x = __builtin_amdgcn_exp2f(a.x); p.y = __builtin_amdgcn_exp2f(a.y); s[r] = p.x; s[r + 1] = p.y; ps2 += p; }
;     l += ps2.x + ps2.y;
;     v4u p0, p1;
;     p0.x = cvtpk(s[0], s[1]); p0.y = cvtpk(s[2], s[3]); p0.z = cvtpk(s[4], s[5]); p0.w = cvtpk(s[6], s[7]);
;     p1.x = cvtpk(s[8], s[9]); p1.y = cvtpk(s[10], s[11]); p1.z = cvtpk(s[12], s[13]); p1.w = cvtpk(s[14], s[15]);
;     pf0 = __builtin_bit_cast(bf16x8, p0); pf1 = __builtin_bit_cast(bf16x8, p1);
; template <int NDT, bool MASK, class F>
; __device__ __forceinline__ void att_compute_lds(const bf16x8 (&qf)[4], const LAS unsigned char* cur, int fk, int fv, const F& f, int k0, int hh, f32x16 (&o)[NDT], float& m, float& l) {
;     ...
; #pragma unroll
;     for (int dt = 0; dt < NDT; ++dt) { bf16x8 vb0 = va0, vb1 = va1;
;         if (dt + 1 < NDT) { vb0 = *(const LAS bf16x8*)(cur + (dt + 1) * 2048 + fv); vb1 = *(const LAS bf16x8*)(cur + (dt + 1) * 2048 + (fv ^ 32)); __builtin_amdgcn_sched_barrier(0); }
;         o[dt] = MFMA32(va0, pf0, o[dt]); o[dt] = MFMA32(va1, pf1, o[dt]); va0 = vb0; va1 = vb1; }
.LBB0_590:
	v_max_f32_e32 v156, v202, v202
	v_max_f32_e32 v156, 0xefa18f08, v156
	v_sub_f32_e32 v156, v204, v156
	v_fma_f32 v84, v84, s34, v156
	v_fma_f32 v85, v85, s34, v156
	v_fma_f32 v86, v86, s34, v156
	v_fma_f32 v87, v87, s34, v156
	v_exp_f32_e32 v84, v84
	v_exp_f32_e32 v85, v85
	v_exp_f32_e32 v86, v86
	v_exp_f32_e32 v87, v87
	v_fma_f32 v88, v88, s34, v156
	v_fma_f32 v89, v89, s34, v156
	v_fma_f32 v90, v90, s34, v156
	v_fma_f32 v91, v91, s34, v156
	v_exp_f32_e32 v88, v88
	v_exp_f32_e32 v89, v89
	v_exp_f32_e32 v90, v90
	v_exp_f32_e32 v91, v91
	v_fma_f32 v92, v92, s34, v156
	v_fma_f32 v93, v93, s34, v156
	v_pk_add_f32 v[158:159], v[84:85], 0 op_sel_hi:[1,0]
	v_exp_f32_e32 v160, v92
	v_exp_f32_e32 v161, v93
	v_fma_f32 v92, v94, s34, v156
	v_fma_f32 v93, v95, s34, v156
	v_add_f32_e32 v158, v86, v158
	v_add_f32_e32 v159, v87, v159
	v_exp_f32_e32 v162, v92
	v_exp_f32_e32 v163, v93
	v_fma_f32 v92, v96, s34, v156
	v_fma_f32 v93, v97, s34, v156
	v_add_f32_e32 v158, v88, v158
	v_add_f32_e32 v159, v89, v159
	v_exp_f32_e32 v164, v92
	v_exp_f32_e32 v165, v93
	v_fma_f32 v92, v98, s34, v156
	v_fma_f32 v93, v99, s34, v156
	v_add_f32_e32 v158, v90, v158
	v_add_f32_e32 v159, v91, v159
	v_exp_f32_e32 v156, v92
	v_exp_f32_e32 v157, v93
	v_add_f32_e32 v92, v160, v158
	v_add_f32_e32 v93, v161, v159
	v_cvt_pk_bf16_f32 v84, v84, v85
	v_add_f32_e32 v92, v162, v92
	v_add_f32_e32 v93, v163, v93
	v_cvt_pk_bf16_f32 v85, v86, v87
	v_add_f32_e32 v92, v164, v92
	v_add_f32_e32 v93, v165, v93
	v_cvt_pk_bf16_f32 v86, v88, v89
	v_add_f32_e32 v92, v156, v92
	v_add_f32_e32 v93, v157, v93
	v_cvt_pk_bf16_f32 v87, v90, v91
	v_add_f32_e32 v92, v92, v93
	v_add_f32_e32 v187, v187, v92
	ds_read_b128 v[88:91], v196 offset:59392
	ds_read_b128 v[92:95], v175 offset:59392
	v_cvt_pk_bf16_f32 v96, v160, v161
	v_cvt_pk_bf16_f32 v97, v162, v163
	v_cvt_pk_bf16_f32 v98, v164, v165
	v_cvt_pk_bf16_f32 v99, v156, v157
	s_waitcnt lgkmcnt(3)
	v_mfma_f32_32x32x16_bf16 v[52:67], v[148:151], v[84:87], v[52:67]
	s_waitcnt lgkmcnt(2)
	v_mfma_f32_32x32x16_bf16 v[52:67], v[152:155], v[96:99], v[52:67]
	ds_read_b128 v[148:151], v196 offset:61440
	ds_read_b128 v[152:155], v175 offset:61440
	s_waitcnt lgkmcnt(3)
	v_mfma_f32_32x32x16_bf16 v[36:51], v[88:91], v[84:87], v[36:51]
	s_waitcnt lgkmcnt(2)
	v_mfma_f32_32x32x16_bf16 v[36:51], v[92:95], v[96:99], v[36:51]
	ds_read_b128 v[88:91], v196 offset:63488
	ds_read_b128 v[92:95], v175 offset:63488
	s_waitcnt lgkmcnt(3)
	v_mfma_f32_32x32x16_bf16 v[20:35], v[148:151], v[84:87], v[20:35]
	s_waitcnt lgkmcnt(1)
	v_mfma_f32_32x32x16_bf16 v[4:19], v[88:91], v[84:87], v[4:19]
	v_mfma_f32_32x32x16_bf16 v[20:35], v[152:155], v[96:99], v[20:35]
	s_waitcnt lgkmcnt(0)
	v_mfma_f32_32x32x16_bf16 v[4:19], v[92:95], v[96:99], v[4:19]

; #define LAS __attribute__((address_space(3)))
; __device__ __forceinline__ unsigned cvtpk(float lo, float hi) { f32x2_t v = {lo, hi}; bf16x2_t b = __builtin_convertvector(v, bf16x2_t); return __builtin_bit_cast(unsigned, b); }
; #define MFMA32(a, b, c) __builtin_amdgcn_mfma_f32_32x32x16_bf16((a), (b), (c), 0, 0, 0)
; template <int NDT, class F>
; __device__ __forceinline__ void softmax_body(f32x16& s, const F& f, int k0, int hh, f32x16 (&o)[NDT], float& m, float& l, bf16x8& pf0, bf16x8& pf1, const int MASK) {
;     ...
;     const float me = fmaxf(m, -1e29f);
;     const float off = on ? f.tadd - me : NEG_BIG;
;     const f32x2_t sc2 = {QK_SCL, QK_SCL}, of2 = {off, off}; f32x2_t ps2 = {0.f, 0.f};
; #pragma unroll
;     for (int r = 0; r < 16; r += 2) { f32x2_t a = {s[r], s[r + 1]}; a = __builtin_elementwise_fma(a, sc2, of2);
;         f32x2_t p; p.x = __builtin_amdgcn_exp2f(a.x); p.y = __builtin_amdgcn_exp2f(a.y); s[r] = p.x; s[r + 1] = p.y; ps2 += p; }
;     l += ps2.x + ps2.y;
;     v4u p0, p1;
;     p0.x = cvtpk(s[0], s[1]); p0.y = cvtpk(s[2], s[3]); p0.z = cvtpk(s[4], s[5]); p0.w = cvtpk(s[6], s[7]);
;     p1.x = cvtpk(s[8], s[9]); p1.y = cvtpk(s[10], s[11]); p1.z = cvtpk(s[12], s[13]); p1.w = cvtpk(s[14], s[15]);
;     pf0 = __builtin_bit_cast(bf16x8, p0); pf1 = __builtin_bit_cast(bf16x8, p1);
; template <int NDT, bool MASK, class F>
; __device__ __forceinline__ void att_compute_lds(const bf16x8 (&qf)[4], const LAS unsigned char* cur, int fk, int fv, const F& f, int k0, int hh, f32x16 (&o)[NDT], float& m, float& l) {
;     ...
; #pragma unroll
;     for (int dt = 0; dt < NDT; ++dt) { bf16x8 vb0 = va0, vb1 = va1;
;         if (dt + 1 < NDT) { vb0 = *(const LAS bf16x8*)(cur + (dt + 1) * 2048 + fv); vb1 = *(const LAS bf16x8*)(cur + (dt + 1) * 2048 + (fv ^ 32)); __builtin_amdgcn_sched_barrier(0); }
;         o[dt] = MFMA32(va0, pf0, o[dt]); o[dt] = MFMA32(va1, pf1, o[dt]); va0 = vb0; va1 = vb1; }
.LBB0_594:
	v_max_f32_e32 v92, v202, v202
	v_max_f32_e32 v92, 0xefa18f08, v92
	v_sub_f32_e32 v92, v204, v92
	v_fma_f32 v94, v162, s34, v92
	v_fma_f32 v95, v163, s34, v92
	v_fma_f32 v98, v160, s34, v92
	v_fma_f32 v99, v161, s34, v92
	v_exp_f32_e32 v94, v94
	v_exp_f32_e32 v95, v95
	v_exp_f32_e32 v98, v98
	v_exp_f32_e32 v99, v99
	v_fma_f32 v158, v158, s34, v92
	v_fma_f32 v159, v159, s34, v92
	v_fma_f32 v156, v156, s34, v92
	v_fma_f32 v157, v157, s34, v92
	v_exp_f32_e32 v158, v158
	v_exp_f32_e32 v159, v159
	v_exp_f32_e32 v156, v156
	v_exp_f32_e32 v157, v157
	v_fma_f32 v90, v90, s34, v92
	v_fma_f32 v91, v91, s34, v92
	v_pk_add_f32 v[96:97], v[94:95], 0 op_sel_hi:[1,0]
	v_exp_f32_e32 v90, v90
	v_exp_f32_e32 v91, v91
	v_fma_f32 v88, v88, s34, v92
	v_fma_f32 v89, v89, s34, v92
	v_add_f32_e32 v96, v98, v96
	v_add_f32_e32 v97, v99, v97
	v_exp_f32_e32 v160, v88
	v_exp_f32_e32 v161, v89
	v_add_f32_e32 v96, v158, v96
	v_add_f32_e32 v97, v159, v97
	v_fma_f32 v86, v86, s34, v92
	v_fma_f32 v87, v87, s34, v92
	v_add_f32_e32 v96, v156, v96
	v_add_f32_e32 v97, v157, v97
	v_fma_f32 v84, v84, s34, v92
	v_fma_f32 v85, v85, s34, v92
	v_add_f32_e32 v96, v90, v96
	v_add_f32_e32 v97, v91, v97
	v_exp_f32_e32 v92, v84
	v_add_f32_e32 v88, v160, v96
	v_add_f32_e32 v89, v161, v97
	v_exp_f32_e32 v96, v86
	v_exp_f32_e32 v97, v87
	v_exp_f32_e32 v93, v85
	v_add_f32_e32 v86, v96, v88
	v_add_f32_e32 v87, v97, v89
	s_nop 0
	v_add_f32_e32 v84, v92, v86
	v_add_f32_e32 v85, v93, v87
	v_cvt_pk_bf16_f32 v88, v90, v91
	v_add_f32_e32 v84, v84, v85
	v_add_f32_e32 v187, v187, v84
	v_cvt_pk_bf16_f32 v84, v94, v95
	v_cvt_pk_bf16_f32 v85, v98, v99
	v_cvt_pk_bf16_f32 v90, v96, v97
	v_cvt_pk_bf16_f32 v91, v92, v93
	ds_read_b128 v[92:95], v196 offset:59392
	ds_read_b128 v[96:99], v175 offset:59392
	v_cvt_pk_bf16_f32 v86, v158, v159
	v_cvt_pk_bf16_f32 v87, v156, v157
	v_cvt_pk_bf16_f32 v89, v160, v161
	s_waitcnt lgkmcnt(3)
	v_mfma_f32_32x32x16_bf16 v[52:67], v[148:151], v[84:87], v[52:67]
	s_waitcnt lgkmcnt(2)
	v_mfma_f32_32x32x16_bf16 v[52:67], v[152:155], v[88:91], v[52:67]
	ds_read_b128 v[148:151], v196 offset:61440
	ds_read_b128 v[152:155], v175 offset:61440
	s_waitcnt lgkmcnt(3)
	v_mfma_f32_32x32x16_bf16 v[36:51], v[92:95], v[84:87], v[36:51]
	s_waitcnt lgkmcnt(2)
	v_mfma_f32_32x32x16_bf16 v[36:51], v[96:99], v[88:91], v[36:51]
	ds_read_b128 v[92:95], v196 offset:63488
	ds_read_b128 v[96:99], v175 offset:63488
	s_waitcnt lgkmcnt(3)
	v_mfma_f32_32x32x16_bf16 v[20:35], v[148:151], v[84:87], v[20:35]
	s_waitcnt lgkmcnt(1)
	v_mfma_f32_32x32x16_bf16 v[4:19], v[92:95], v[84:87], v[4:19]
	v_mfma_f32_32x32x16_bf16 v[20:35], v[152:155], v[88:91], v[20:35]
	s_waitcnt lgkmcnt(0)
	v_mfma_f32_32x32x16_bf16 v[4:19], v[96:99], v[88:91], v[4:19]

; #define LAS __attribute__((address_space(3)))
; __device__ __forceinline__ unsigned cvtpk(float lo, float hi) { f32x2_t v = {lo, hi}; bf16x2_t b = __builtin_convertvector(v, bf16x2_t); return __builtin_bit_cast(unsigned, b); }
; #define MFMA32(a, b, c) __builtin_amdgcn_mfma_f32_32x32x16_bf16((a), (b), (c), 0, 0, 0)
; template <int NDT, class F>
; __device__ __forceinline__ void softmax_body(f32x16& s, const F& f, int k0, int hh, f32x16 (&o)[NDT], float& m, float& l, bf16x8& pf0, bf16x8& pf1, const int MASK) {
;     ...
;     const float me = fmaxf(m, -1e29f);
;     const float off = on ? f.tadd - me : NEG_BIG;
;     const f32x2_t sc2 = {QK_SCL, QK_SCL}, of2 = {off, off}; f32x2_t ps2 = {0.f, 0.f};
; #pragma unroll
;     for (int r = 0; r < 16; r += 2) { f32x2_t a = {s[r], s[r + 1]}; a = __builtin_elementwise_fma(a, sc2, of2);
;         f32x2_t p; p.x = __builtin_amdgcn_exp2f(a.x); p.y = __builtin_amdgcn_exp2f(a.y); s[r] = p.x; s[r + 1] = p.y; ps2 += p; }
;     l += ps2.x + ps2.y;
;     v4u p0, p1;
;     p0.x = cvtpk(s[0], s[1]); p0.y = cvtpk(s[2], s[3]); p0.z = cvtpk(s[4], s[5]); p0.w = cvtpk(s[6], s[7]);
;     p1.x = cvtpk(s[8], s[9]); p1.y = cvtpk(s[10], s[11]); p1.z = cvtpk(s[12], s[13]); p1.w = cvtpk(s[14], s[15]);
;     pf0 = __builtin_bit_cast(bf16x8, p0); pf1 = __builtin_bit_cast(bf16x8, p1);
; template <int NDT, bool MASK, class F>
; __device__ __forceinline__ void att_compute_lds(const bf16x8 (&qf)[4], const LAS unsigned char* cur, int fk, int fv, const F& f, int k0, int hh, f32x16 (&o)[NDT], float& m, float& l) {
;     ...
; #pragma unroll
;     for (int dt = 0; dt < NDT; ++dt) { bf16x8 vb0 = va0, vb1 = va1;
;         if (dt + 1 < NDT) { vb0 = *(const LAS bf16x8*)(cur + (dt + 1) * 2048 + fv); vb1 = *(const LAS bf16x8*)(cur + (dt + 1) * 2048 + (fv ^ 32)); __builtin_amdgcn_sched_barrier(0); }
;         o[dt] = MFMA32(va0, pf0, o[dt]); o[dt] = MFMA32(va1, pf1, o[dt]); va0 = vb0; va1 = vb1; }
.LBB0_600:
	v_max_f32_e32 v156, v202, v202
	v_max_f32_e32 v156, 0xefa18f08, v156
	v_sub_f32_e32 v156, v204, v156
	v_fma_f32 v84, v84, s34, v156
	v_fma_f32 v85, v85, s34, v156
	v_fma_f32 v86, v86, s34, v156
	v_fma_f32 v87, v87, s34, v156
	v_exp_f32_e32 v84, v84
	v_exp_f32_e32 v85, v85
	v_exp_f32_e32 v86, v86
	v_exp_f32_e32 v87, v87
	v_fma_f32 v88, v88, s34, v156
	v_fma_f32 v89, v89, s34, v156
	v_fma_f32 v90, v90, s34, v156
	v_fma_f32 v91, v91, s34, v156
	v_exp_f32_e32 v88, v88
	v_exp_f32_e32 v89, v89
	v_exp_f32_e32 v90, v90
	v_exp_f32_e32 v91, v91
	v_fma_f32 v92, v92, s34, v156
	v_fma_f32 v93, v93, s34, v156
	v_pk_add_f32 v[158:159], v[84:85], 0 op_sel_hi:[1,0]
	v_exp_f32_e32 v160, v92
	v_exp_f32_e32 v161, v93
	v_fma_f32 v92, v94, s34, v156
	v_fma_f32 v93, v95, s34, v156
	v_add_f32_e32 v158, v86, v158
	v_add_f32_e32 v159, v87, v159
	v_exp_f32_e32 v162, v92
	v_exp_f32_e32 v163, v93
	v_fma_f32 v92, v96, s34, v156
	v_fma_f32 v93, v97, s34, v156
	v_add_f32_e32 v158, v88, v158
	v_add_f32_e32 v159, v89, v159
	v_exp_f32_e32 v164, v92
	v_exp_f32_e32 v165, v93
	v_fma_f32 v92, v98, s34, v156
	v_fma_f32 v93, v99, s34, v156
	v_add_f32_e32 v158, v90, v158
	v_add_f32_e32 v159, v91, v159
	v_exp_f32_e32 v156, v92
	v_exp_f32_e32 v157, v93
	v_add_f32_e32 v92, v160, v158
	v_add_f32_e32 v93, v161, v159
	v_cvt_pk_bf16_f32 v84, v84, v85
	v_add_f32_e32 v92, v162, v92
	v_add_f32_e32 v93, v163, v93
	v_cvt_pk_bf16_f32 v85, v86, v87
	v_add_f32_e32 v92, v164, v92
	v_add_f32_e32 v93, v165, v93
	v_cvt_pk_bf16_f32 v86, v88, v89
	v_add_f32_e32 v92, v156, v92
	v_add_f32_e32 v93, v157, v93
	v_cvt_pk_bf16_f32 v87, v90, v91
	v_add_f32_e32 v92, v92, v93
	v_add_f32_e32 v187, v187, v92
	ds_read_b128 v[88:91], v196 offset:51200
	ds_read_b128 v[92:95], v175 offset:51200
	v_cvt_pk_bf16_f32 v96, v160, v161
	v_cvt_pk_bf16_f32 v97, v162, v163
	v_cvt_pk_bf16_f32 v98, v164, v165
	v_cvt_pk_bf16_f32 v99, v156, v157
	s_waitcnt lgkmcnt(3)
	v_mfma_f32_32x32x16_bf16 v[52:67], v[148:151], v[84:87], v[52:67]
	s_waitcnt lgkmcnt(2)
	v_mfma_f32_32x32x16_bf16 v[52:67], v[152:155], v[96:99], v[52:67]
	ds_read_b128 v[148:151], v196 offset:53248
	ds_read_b128 v[152:155], v175 offset:53248
	s_waitcnt lgkmcnt(3)
	v_mfma_f32_32x32x16_bf16 v[36:51], v[88:91], v[84:87], v[36:51]
	s_waitcnt lgkmcnt(2)
	v_mfma_f32_32x32x16_bf16 v[36:51], v[92:95], v[96:99], v[36:51]
	ds_read_b128 v[88:91], v196 offset:55296
	ds_read_b128 v[92:95], v175 offset:55296
	s_waitcnt lgkmcnt(3)
	v_mfma_f32_32x32x16_bf16 v[20:35], v[148:151], v[84:87], v[20:35]
	s_waitcnt lgkmcnt(1)
	v_mfma_f32_32x32x16_bf16 v[4:19], v[88:91], v[84:87], v[4:19]
	v_mfma_f32_32x32x16_bf16 v[20:35], v[152:155], v[96:99], v[20:35]
	s_waitcnt lgkmcnt(0)
	v_mfma_f32_32x32x16_bf16 v[4:19], v[92:95], v[96:99], v[4:19]

; #define LAS __attribute__((address_space(3)))
; __device__ __forceinline__ unsigned cvtpk(float lo, float hi) { f32x2_t v = {lo, hi}; bf16x2_t b = __builtin_convertvector(v, bf16x2_t); return __builtin_bit_cast(unsigned, b); }
; #define MFMA32(a, b, c) __builtin_amdgcn_mfma_f32_32x32x16_bf16((a), (b), (c), 0, 0, 0)
; template <int NDT, class F>
; __device__ __forceinline__ void softmax_body(f32x16& s, const F& f, int k0, int hh, f32x16 (&o)[NDT], float& m, float& l, bf16x8& pf0, bf16x8& pf1, const int MASK) {
;     ...
;     const float me = fmaxf(m, -1e29f);
;     const float off = on ? f.tadd - me : NEG_BIG;
;     const f32x2_t sc2 = {QK_SCL, QK_SCL}, of2 = {off, off}; f32x2_t ps2 = {0.f, 0.f};
; #pragma unroll
;     for (int r = 0; r < 16; r += 2) { f32x2_t a = {s[r], s[r + 1]}; a = __builtin_elementwise_fma(a, sc2, of2);
;         f32x2_t p; p.x = __builtin_amdgcn_exp2f(a.x); p.y = __builtin_amdgcn_exp2f(a.y); s[r] = p.x; s[r + 1] = p.y; ps2 += p; }
;     l += ps2.x + ps2.y;
;     v4u p0, p1;
;     p0.x = cvtpk(s[0], s[1]); p0.y = cvtpk(s[2], s[3]); p0.z = cvtpk(s[4], s[5]); p0.w = cvtpk(s[6], s[7]);
;     p1.x = cvtpk(s[8], s[9]); p1.y = cvtpk(s[10], s[11]); p1.z = cvtpk(s[12], s[13]); p1.w = cvtpk(s[14], s[15]);
;     pf0 = __builtin_bit_cast(bf16x8, p0); pf1 = __builtin_bit_cast(bf16x8, p1);
; template <int NDT, bool MASK, class F>
; __device__ __forceinline__ void att_compute_lds(const bf16x8 (&qf)[4], const LAS unsigned char* cur, int fk, int fv, const F& f, int k0, int hh, f32x16 (&o)[NDT], float& m, float& l) {
;     ...
; #pragma unroll
;     for (int dt = 0; dt < NDT; ++dt) { bf16x8 vb0 = va0, vb1 = va1;
;         if (dt + 1 < NDT) { vb0 = *(const LAS bf16x8*)(cur + (dt + 1) * 2048 + fv); vb1 = *(const LAS bf16x8*)(cur + (dt + 1) * 2048 + (fv ^ 32)); __builtin_amdgcn_sched_barrier(0); }
;         o[dt] = MFMA32(va0, pf0, o[dt]); o[dt] = MFMA32(va1, pf1, o[dt]); va0 = vb0; va1 = vb1; }
.LBB0_604:
	v_max_f32_e32 v92, v202, v202
	v_max_f32_e32 v92, 0xefa18f08, v92
	v_sub_f32_e32 v92, v204, v92
	v_fma_f32 v94, v162, s34, v92
	v_fma_f32 v95, v163, s34, v92
	v_fma_f32 v98, v160, s34, v92
	v_fma_f32 v99, v161, s34, v92
	v_exp_f32_e32 v94, v94
	v_exp_f32_e32 v95, v95
	v_exp_f32_e32 v98, v98
	v_exp_f32_e32 v99, v99
	v_fma_f32 v158, v158, s34, v92
	v_fma_f32 v159, v159, s34, v92
	v_fma_f32 v156, v156, s34, v92
	v_fma_f32 v157, v157, s34, v92
	v_exp_f32_e32 v158, v158
	v_exp_f32_e32 v159, v159
	v_exp_f32_e32 v156, v156
	v_exp_f32_e32 v157, v157
	v_fma_f32 v90, v90, s34, v92
	v_fma_f32 v91, v91, s34, v92
	v_pk_add_f32 v[96:97], v[94:95], 0 op_sel_hi:[1,0]
	v_exp_f32_e32 v90, v90
	v_exp_f32_e32 v91, v91
	v_fma_f32 v88, v88, s34, v92
	v_fma_f32 v89, v89, s34, v92
	v_add_f32_e32 v96, v98, v96
	v_add_f32_e32 v97, v99, v97
	v_exp_f32_e32 v160, v88
	v_exp_f32_e32 v161, v89
	v_add_f32_e32 v96, v158, v96
	v_add_f32_e32 v97, v159, v97
	v_fma_f32 v86, v86, s34, v92
	v_fma_f32 v87, v87, s34, v92
	v_add_f32_e32 v96, v156, v96
	v_add_f32_e32 v97, v157, v97
	v_fma_f32 v84, v84, s34, v92
	v_fma_f32 v85, v85, s34, v92
	v_add_f32_e32 v96, v90, v96
	v_add_f32_e32 v97, v91, v97
	v_exp_f32_e32 v92, v84
	v_add_f32_e32 v88, v160, v96
	v_add_f32_e32 v89, v161, v97
	v_exp_f32_e32 v96, v86
	v_exp_f32_e32 v97, v87
	v_exp_f32_e32 v93, v85
	v_add_f32_e32 v86, v96, v88
	v_add_f32_e32 v87, v97, v89
	s_nop 0
	v_add_f32_e32 v84, v92, v86
	v_add_f32_e32 v85, v93, v87
	v_cvt_pk_bf16_f32 v88, v90, v91
	v_add_f32_e32 v84, v84, v85
	v_add_f32_e32 v187, v187, v84
	v_cvt_pk_bf16_f32 v84, v94, v95
	v_cvt_pk_bf16_f32 v85, v98, v99
	v_cvt_pk_bf16_f32 v90, v96, v97
	v_cvt_pk_bf16_f32 v91, v92, v93
	ds_read_b128 v[92:95], v196 offset:51200
	ds_read_b128 v[96:99], v175 offset:51200
	v_cvt_pk_bf16_f32 v86, v158, v159
	v_cvt_pk_bf16_f32 v87, v156, v157
	v_cvt_pk_bf16_f32 v89, v160, v161
	s_waitcnt lgkmcnt(3)
	v_mfma_f32_32x32x16_bf16 v[52:67], v[148:151], v[84:87], v[52:67]
	s_waitcnt lgkmcnt(2)
	v_mfma_f32_32x32x16_bf16 v[52:67], v[152:155], v[88:91], v[52:67]
	ds_read_b128 v[148:151], v196 offset:53248
	ds_read_b128 v[152:155], v175 offset:53248
	s_waitcnt lgkmcnt(3)
	v_mfma_f32_32x32x16_bf16 v[36:51], v[92:95], v[84:87], v[36:51]
	s_waitcnt lgkmcnt(2)
	v_mfma_f32_32x32x16_bf16 v[36:51], v[96:99], v[88:91], v[36:51]
	ds_read_b128 v[92:95], v196 offset:55296
	ds_read_b128 v[96:99], v175 offset:55296
	s_waitcnt lgkmcnt(3)
	v_mfma_f32_32x32x16_bf16 v[20:35], v[148:151], v[84:87], v[20:35]
	s_waitcnt lgkmcnt(1)
	v_mfma_f32_32x32x16_bf16 v[4:19], v[92:95], v[84:87], v[4:19]
	v_mfma_f32_32x32x16_bf16 v[20:35], v[152:155], v[88:91], v[20:35]
	s_waitcnt lgkmcnt(0)
	v_mfma_f32_32x32x16_bf16 v[4:19], v[96:99], v[88:91], v[4:19]

; #define LAS __attribute__((address_space(3)))
; __device__ __forceinline__ float half_sum(float v) { unsigned a, b; half_swap(__builtin_bit_cast(unsigned, v), a, b); return __builtin_bit_cast(float, a) + __builtin_bit_cast(float, b); }
; __device__ __forceinline__ void dif_coop(const bf16* PROJ, const unsigned char* VTB, bf16* O, float lam, const float* subg, float oscale, int bh, int c, LAS unsigned char* sbuf, int tid) {
;     ...
;     LAS float* xb = (LAS float*)(sbuf + (wave & 3) * 16384) + lane;
;     if (mp) {
; #pragma unroll
;         for (int dt = 0; dt < 4; ++dt)
; #pragma unroll
;             for (int r = 0; r < 16; ++r) xb[(dt * 16 + r) * 64] = o[dt][r] * sc; }
;     __syncthreads();
;     if (!mp) { float ss = 0.f;
; #pragma unroll
;         for (int dt = 0; dt < 4; ++dt)
; #pragma unroll
;             for (int r = 0; r < 16; ++r) { const float v = o[dt][r] * sc - xb[(dt * 16 + r) * 64]; o[dt][r] = v; ss = fmaf(v, v, ss); }
;         ss = half_sum(ss);
.LBB0_611:
	s_or_b64 exec, exec, s[14:15]
	s_waitcnt lgkmcnt(0)
	s_barrier
	s_and_saveexec_b64 s[14:15], s[38:39]
	s_cbranch_execz .LBB0_550
	ds_read2st64_b32 v[86:87], v69 offset1:1
	ds_read2st64_b32 v[88:89], v69 offset0:2 offset1:3
	ds_read2st64_b32 v[90:91], v69 offset0:4 offset1:5
	ds_read2st64_b32 v[92:93], v69 offset0:6 offset1:7
	ds_read2st64_b32 v[94:95], v69 offset0:8 offset1:9
	ds_read2st64_b32 v[96:97], v69 offset0:10 offset1:11
	ds_read2st64_b32 v[98:99], v69 offset0:12 offset1:13
	s_waitcnt vmcnt(7)
	ds_read2st64_b32 v[100:101], v69 offset0:14 offset1:15
	ds_read2st64_b32 v[102:103], v69 offset0:16 offset1:17
	s_waitcnt vmcnt(6)
	ds_read2st64_b32 v[104:105], v69 offset0:18 offset1:19
	ds_read2st64_b32 v[106:107], v69 offset0:20 offset1:21
	s_waitcnt vmcnt(5)
	ds_read2st64_b32 v[108:109], v69 offset0:22 offset1:23
	ds_read2st64_b32 v[110:111], v69 offset0:24 offset1:25
	s_waitcnt vmcnt(4)
	ds_read2st64_b32 v[112:113], v69 offset0:26 offset1:27
	ds_read2st64_b32 v[114:115], v69 offset0:28 offset1:29
	s_waitcnt vmcnt(3)
	ds_read2st64_b32 v[116:117], v69 offset0:30 offset1:31
	ds_read2st64_b32 v[118:119], v69 offset0:32 offset1:33
	s_waitcnt vmcnt(2)
	ds_read2st64_b32 v[120:121], v69 offset0:34 offset1:35
	ds_read2st64_b32 v[122:123], v69 offset0:36 offset1:37
	s_waitcnt vmcnt(1)
	ds_read2st64_b32 v[124:125], v69 offset0:38 offset1:39
	ds_read2st64_b32 v[126:127], v69 offset0:40 offset1:41
	s_waitcnt vmcnt(0)
	ds_read2st64_b32 v[128:129], v69 offset0:42 offset1:43
	ds_read2st64_b32 v[130:131], v69 offset0:44 offset1:45
	ds_read2st64_b32 v[132:133], v69 offset0:46 offset1:47
	ds_read2st64_b32 v[84:85], v69 offset0:48 offset1:49
	ds_read2st64_b32 v[134:135], v69 offset0:50 offset1:51
	ds_read2st64_b32 v[80:81], v69 offset0:52 offset1:53
	ds_read2st64_b32 v[82:83], v69 offset0:54 offset1:55
	ds_read2st64_b32 v[76:77], v69 offset0:56 offset1:57
	ds_read2st64_b32 v[78:79], v69 offset0:58 offset1:59
	ds_read2st64_b32 v[72:73], v69 offset0:60 offset1:61
	ds_read2st64_b32 v[74:75], v69 offset0:62 offset1:63
	s_waitcnt lgkmcnt(14)
	v_fma_f32 v52, v52, v68, -v86
	v_fma_f32 v53, v53, v68, -v87
	v_fma_f32 v54, v54, v68, -v88
	v_fma_f32 v55, v55, v68, -v89
	v_fma_f32 v136, v52, v52, 0
	v_fmac_f32_e32 v136, v53, v53
	v_fmac_f32_e32 v136, v54, v54
	v_fmac_f32_e32 v136, v55, v55
	v_fma_f32 v56, v56, v68, -v90
	v_fma_f32 v57, v57, v68, -v91
	v_fma_f32 v58, v58, v68, -v92
	v_fma_f32 v59, v59, v68, -v93
	v_fmac_f32_e32 v136, v56, v56
	v_fmac_f32_e32 v136, v57, v57
	v_fmac_f32_e32 v136, v58, v58
	v_fmac_f32_e32 v136, v59, v59
	v_fma_f32 v60, v60, v68, -v94
	v_fma_f32 v61, v61, v68, -v95
	v_fma_f32 v62, v62, v68, -v96
	v_fma_f32 v63, v63, v68, -v97
	v_fmac_f32_e32 v136, v60, v60
	v_fmac_f32_e32 v136, v61, v61
	v_fmac_f32_e32 v136, v62, v62
	v_fmac_f32_e32 v136, v63, v63
	v_fma_f32 v64, v64, v68, -v98
	v_fma_f32 v65, v65, v68, -v99
	v_fma_f32 v66, v66, v68, -v100
	v_fma_f32 v67, v67, v68, -v101
	v_fmac_f32_e32 v136, v64, v64
	v_fmac_f32_e32 v136, v65, v65
	v_fmac_f32_e32 v136, v66, v66
	v_fmac_f32_e32 v136, v67, v67
	v_fma_f32 v36, v36, v68, -v102
	v_fma_f32 v37, v37, v68, -v103
	v_fma_f32 v38, v38, v68, -v104
	v_fma_f32 v39, v39, v68, -v105
	v_fmac_f32_e32 v136, v36, v36
	v_fmac_f32_e32 v136, v37, v37
	v_fmac_f32_e32 v136, v38, v38
	v_fmac_f32_e32 v136, v39, v39
	v_fma_f32 v40, v40, v68, -v106
	v_fma_f32 v41, v41, v68, -v107
	v_fma_f32 v42, v42, v68, -v108
	v_fma_f32 v43, v43, v68, -v109
	v_fmac_f32_e32 v136, v40, v40
	v_fmac_f32_e32 v136, v41, v41
	v_fmac_f32_e32 v136, v42, v42
	v_fmac_f32_e32 v136, v43, v43
	v_fma_f32 v44, v44, v68, -v110
	v_fma_f32 v45, v45, v68, -v111
	v_fma_f32 v46, v46, v68, -v112
	v_fma_f32 v47, v47, v68, -v113
	v_fmac_f32_e32 v136, v44, v44
	v_fmac_f32_e32 v136, v45, v45
	v_fmac_f32_e32 v136, v46, v46
	v_fmac_f32_e32 v136, v47, v47
	v_fma_f32 v48, v48, v68, -v114
	v_fma_f32 v49, v49, v68, -v115
	v_fma_f32 v50, v50, v68, -v116
	v_fma_f32 v51, v51, v68, -v117
	v_fmac_f32_e32 v136, v48, v48
	v_fmac_f32_e32 v136, v49, v49
	v_fmac_f32_e32 v136, v50, v50
	v_fmac_f32_e32 v136, v51, v51
	v_fma_f32 v20, v20, v68, -v118
	v_fma_f32 v21, v21, v68, -v119
	v_fma_f32 v22, v22, v68, -v120
	v_fma_f32 v23, v23, v68, -v121
	v_fmac_f32_e32 v136, v20, v20
	v_fmac_f32_e32 v136, v21, v21
	v_fmac_f32_e32 v136, v22, v22
	v_fmac_f32_e32 v136, v23, v23
	s_waitcnt lgkmcnt(13)
	v_fma_f32 v106, v24, v68, -v122
	v_fma_f32 v107, v25, v68, -v123
	s_waitcnt lgkmcnt(12)
	v_fma_f32 v104, v26, v68, -v124
	v_fma_f32 v105, v27, v68, -v125
	v_fmac_f32_e32 v136, v106, v106
	v_fmac_f32_e32 v136, v107, v107
	v_fmac_f32_e32 v136, v104, v104
	v_fmac_f32_e32 v136, v105, v105
	s_waitcnt lgkmcnt(11)
	v_fma_f32 v110, v28, v68, -v126
	v_fma_f32 v111, v29, v68, -v127
	s_waitcnt lgkmcnt(10)
	v_fma_f32 v108, v30, v68, -v128
	v_fma_f32 v109, v31, v68, -v129
	v_fmac_f32_e32 v136, v110, v110
	v_fmac_f32_e32 v136, v111, v111
	v_fmac_f32_e32 v136, v108, v108
	v_fmac_f32_e32 v136, v109, v109
	s_waitcnt lgkmcnt(9)
	v_fma_f32 v114, v32, v68, -v130
	v_fma_f32 v115, v33, v68, -v131
	s_waitcnt lgkmcnt(8)
	v_fma_f32 v112, v34, v68, -v132
	v_fma_f32 v113, v35, v68, -v133
	v_fmac_f32_e32 v136, v114, v114
	v_fmac_f32_e32 v136, v115, v115
	v_fmac_f32_e32 v136, v112, v112
	v_fmac_f32_e32 v136, v113, v113
	s_waitcnt lgkmcnt(7)
	v_fma_f32 v118, v4, v68, -v84
	v_fma_f32 v119, v5, v68, -v85
	s_waitcnt lgkmcnt(6)
	v_fma_f32 v116, v6, v68, -v134
	v_fma_f32 v117, v7, v68, -v135
	v_fmac_f32_e32 v136, v118, v118
	v_fmac_f32_e32 v136, v119, v119
	v_fmac_f32_e32 v136, v116, v116
	v_fmac_f32_e32 v136, v117, v117
	s_waitcnt lgkmcnt(5)
	v_fma_f32 v122, v8, v68, -v80
	v_fma_f32 v123, v9, v68, -v81
	s_waitcnt lgkmcnt(4)
; __device__ __forceinline__ float half_sum(float v) { unsigned a, b; half_swap(__builtin_bit_cast(unsigned, v), a, b); return __builtin_bit_cast(float, a) + __builtin_bit_cast(float, b); }
; __device__ __forceinline__ void dif_coop(const bf16* PROJ, const unsigned char* VTB, bf16* O, float lam, const float* subg, float oscale, int bh, int c, LAS unsigned char* sbuf, int tid) {
;     ...
;             for (int r = 0; r < 16; ++r) { const float v = o[dt][r] * sc - xb[(dt * 16 + r) * 64]; o[dt][r] = v; ss = fmaf(v, v, ss); }
;         ss = half_sum(ss);
;         const float rs = rsqrtf(ss * (1.f / 128.f) + 1e-6f) * oscale;
; #pragma unroll
;         for (int dt = 0; dt < 4; ++dt) {
; #pragma unroll
;             for (int g = 0; g < 4; ++g) { const f32x4 gg = *(const f32x4*)(subg + 32 * dt + 8 * g + 4 * hh);
;                 o[dt][4 * g] *= gg.x; o[dt][4 * g + 1] *= gg.y; o[dt][4 * g + 2] *= gg.z; o[dt][4 * g + 3] *= gg.w; }
;             asm volatile("" ::: "memory"); }
;         store_ot<4>(O + row * DM + O_DIF + hd * 128, o, rs, hh); }
	v_fma_f32 v120, v10, v68, -v82
	v_fma_f32 v121, v11, v68, -v83
	v_fmac_f32_e32 v136, v122, v122
	v_fmac_f32_e32 v136, v123, v123
	v_fmac_f32_e32 v136, v120, v120
	v_fmac_f32_e32 v136, v121, v121
	s_waitcnt lgkmcnt(3)
	v_fma_f32 v126, v12, v68, -v76
	v_fma_f32 v127, v13, v68, -v77
	s_waitcnt lgkmcnt(2)
	v_fma_f32 v124, v14, v68, -v78
	v_fma_f32 v125, v15, v68, -v79
	v_fmac_f32_e32 v136, v126, v126
	v_fmac_f32_e32 v136, v127, v127
	v_fmac_f32_e32 v136, v124, v124
	v_fmac_f32_e32 v136, v125, v125
	s_waitcnt lgkmcnt(1)
	v_fma_f32 v130, v16, v68, -v72
	v_fma_f32 v131, v17, v68, -v73
	s_waitcnt lgkmcnt(0)
	v_fma_f32 v128, v18, v68, -v74
	v_fma_f32 v129, v19, v68, -v75
	v_fmac_f32_e32 v136, v130, v130
	v_fmac_f32_e32 v136, v131, v131
	s_add_u32 s16, s16, s72
	v_fmac_f32_e32 v136, v128, v128
	s_addc_u32 s17, s17, s73
	v_lshlrev_b32_e32 v70, 2, v173
	v_mov_b32_e32 v71, v3
	v_fmac_f32_e32 v136, v129, v129
	v_lshl_add_u64 v[70:71], s[16:17], 0, v[70:71]
	v_mov_b32_e32 v134, v136
	flat_load_dwordx4 v[4:7], v[70:71]
	flat_load_dwordx4 v[8:11], v[70:71] offset:32
	flat_load_dwordx4 v[12:15], v[70:71] offset:64
	flat_load_dwordx4 v[16:19], v[70:71] offset:96
	flat_load_dwordx4 v[24:27], v[70:71] offset:128
	flat_load_dwordx4 v[28:31], v[70:71] offset:160
	flat_load_dwordx4 v[32:35], v[70:71] offset:192
	flat_load_dwordx4 v[72:75], v[70:71] offset:224
	flat_load_dwordx4 v[76:79], v[70:71] offset:256
	flat_load_dwordx4 v[80:83], v[70:71] offset:288
	flat_load_dwordx4 v[84:87], v[70:71] offset:320
	flat_load_dwordx4 v[88:91], v[70:71] offset:352
	flat_load_dwordx4 v[92:95], v[70:71] offset:384
	flat_load_dwordx4 v[96:99], v[70:71] offset:416
	flat_load_dwordx4 v[100:103], v[70:71] offset:448
	s_nop 0
	flat_load_dwordx4 v[68:71], v[70:71] offset:480
	v_permlane32_swap_b32_e32 v136, v134
	v_lshlrev_b64 v[132:133], 12, v[2:3]
	v_add_f32_e32 v2, v136, v134
	v_fmamk_f32 v2, v2, 0x3c000000, v228
	s_mov_b32 s4, 0x800000
	v_mul_f32_e32 v134, 0x4b800000, v2
	v_cmp_gt_f32_e32 vcc, s4, v2
	v_lshl_add_u64 v[132:133], s[36:37], 0, v[132:133]
	s_mov_b32 s25, s19
	v_cndmask_b32_e32 v2, v2, v134, vcc
	v_rsq_f32_e32 v136, v2
	v_lshl_add_u64 v[132:133], v[132:133], 0, s[24:25]
	v_lshlrev_b32_e32 v2, 1, v173
	v_lshl_add_u64 v[132:133], v[132:133], 0, v[2:3]
	v_mul_f32_e32 v2, 0x45800000, v136
	v_cndmask_b32_e32 v2, v136, v2, vcc
	v_mul_f32_e32 v2, v182, v2
	s_mov_b64 s[4:5], 0x2800c00
	v_lshl_add_u64 v[134:135], v[132:133], 0, s[4:5]
	s_waitcnt vmcnt(0) lgkmcnt(0)
; __device__ __forceinline__ unsigned cvtpk(float lo, float hi) { f32x2_t v = {lo, hi}; bf16x2_t b = __builtin_convertvector(v, bf16x2_t); return __builtin_bit_cast(unsigned, b); }
; template <int NDT>
; __device__ __forceinline__ void store_ot(bf16* orow  , const f32x16 (&o)[NDT], float scale, int hh) {
; #pragma unroll
;     for (int dt = 0; dt < NDT; ++dt)
; #pragma unroll
;         for (int g = 0; g < 4; ++g) { v2u w; w.x = cvtpk(o[dt][4 * g] * scale, o[dt][4 * g + 1] * scale); w.y = cvtpk(o[dt][4 * g + 2] * scale, o[dt][4 * g + 3] * scale);
;             *(v2u*)(orow + 32 * dt + 8 * g + 4 * hh) = w; }
; __device__ __forceinline__ void dif_coop(const bf16* PROJ, const unsigned char* VTB, bf16* O, float lam, const float* subg, float oscale, int bh, int c, LAS unsigned char* sbuf, int tid) {
;     ...
;         for (int dt = 0; dt < 4; ++dt) {
; #pragma unroll
;             for (int g = 0; g < 4; ++g) { const f32x4 gg = *(const f32x4*)(subg + 32 * dt + 8 * g + 4 * hh);
;                 o[dt][4 * g] *= gg.x; o[dt][4 * g + 1] *= gg.y; o[dt][4 * g + 2] *= gg.z; o[dt][4 * g + 3] *= gg.w; }
;             asm volatile("" ::: "memory"); }
;         store_ot<4>(O + row * DM + O_DIF + hd * 128, o, rs, hh); }
	v_mul_f32_e32 v4, v52, v4
	v_mul_f32_e32 v5, v53, v5
	v_mul_f32_e32 v6, v54, v6
	v_mul_f32_e32 v7, v55, v7
	v_mul_f32_e32 v4, v4, v2
	v_mul_f32_e32 v5, v5, v2
	v_mul_f32_e32 v6, v6, v2
	v_mul_f32_e32 v7, v7, v2
	v_cvt_pk_bf16_f32 v4, v4, v5
	v_cvt_pk_bf16_f32 v5, v6, v7
	v_add_co_u32_e32 v6, vcc, s88, v132
	v_mul_f32_e32 v8, v56, v8
	v_mul_f32_e32 v9, v57, v9
	v_mul_f32_e32 v10, v58, v10
	v_mul_f32_e32 v11, v59, v11
	v_addc_co_u32_e32 v7, vcc, 0, v133, vcc
	flat_store_dwordx2 v[6:7], v[4:5] offset:3072
	v_mul_f32_e32 v4, v8, v2
	v_mul_f32_e32 v5, v9, v2
	v_mul_f32_e32 v6, v10, v2
	v_mul_f32_e32 v7, v11, v2
	v_mul_f32_e32 v12, v60, v12
	v_mul_f32_e32 v13, v61, v13
	v_mul_f32_e32 v14, v62, v14
	v_mul_f32_e32 v15, v63, v15
	v_cvt_pk_bf16_f32 v4, v4, v5
	v_cvt_pk_bf16_f32 v5, v6, v7
	flat_store_dwordx2 v[134:135], v[4:5] offset:16
	v_mul_f32_e32 v4, v12, v2
	v_mul_f32_e32 v5, v13, v2
	v_mul_f32_e32 v6, v14, v2
	v_mul_f32_e32 v7, v15, v2
	v_mul_f32_e32 v16, v64, v16
	v_mul_f32_e32 v17, v65, v17
	v_mul_f32_e32 v18, v66, v18
	v_mul_f32_e32 v19, v67, v19
	v_cvt_pk_bf16_f32 v4, v4, v5
	v_cvt_pk_bf16_f32 v5, v6, v7
	flat_store_dwordx2 v[134:135], v[4:5] offset:32
	v_mul_f32_e32 v4, v16, v2
	v_mul_f32_e32 v5, v17, v2
	v_mul_f32_e32 v6, v18, v2
	v_mul_f32_e32 v7, v19, v2
	v_mul_f32_e32 v24, v36, v24
	v_mul_f32_e32 v25, v37, v25
	v_mul_f32_e32 v26, v38, v26
	v_mul_f32_e32 v27, v39, v27
	v_cvt_pk_bf16_f32 v4, v4, v5
	v_cvt_pk_bf16_f32 v5, v6, v7
	flat_store_dwordx2 v[134:135], v[4:5] offset:48
	v_mul_f32_e32 v4, v24, v2
	v_mul_f32_e32 v5, v25, v2
	v_mul_f32_e32 v6, v26, v2
	v_mul_f32_e32 v7, v27, v2
	v_mul_f32_e32 v28, v40, v28
	v_mul_f32_e32 v29, v41, v29
	v_mul_f32_e32 v30, v42, v30
	v_mul_f32_e32 v31, v43, v31
	v_cvt_pk_bf16_f32 v4, v4, v5
	v_cvt_pk_bf16_f32 v5, v6, v7
	flat_store_dwordx2 v[134:135], v[4:5] offset:64
	v_mul_f32_e32 v4, v28, v2
	v_mul_f32_e32 v5, v29, v2
	v_mul_f32_e32 v6, v30, v2
	v_mul_f32_e32 v7, v31, v2
	v_mul_f32_e32 v32, v44, v32
	v_mul_f32_e32 v33, v45, v33
	v_mul_f32_e32 v34, v46, v34
	v_mul_f32_e32 v35, v47, v35
	v_cvt_pk_bf16_f32 v4, v4, v5
	v_cvt_pk_bf16_f32 v5, v6, v7
	flat_store_dwordx2 v[134:135], v[4:5] offset:80
	v_mul_f32_e32 v4, v32, v2
	v_mul_f32_e32 v5, v33, v2
	v_mul_f32_e32 v6, v34, v2
	v_mul_f32_e32 v7, v35, v2
	v_mul_f32_e32 v36, v48, v72
	v_mul_f32_e32 v37, v49, v73
	v_mul_f32_e32 v38, v50, v74
	v_mul_f32_e32 v39, v51, v75
	v_cvt_pk_bf16_f32 v4, v4, v5
	v_cvt_pk_bf16_f32 v5, v6, v7
	flat_store_dwordx2 v[134:135], v[4:5] offset:96
	v_mul_f32_e32 v4, v2, v36
	v_mul_f32_e32 v5, v2, v37
	v_mul_f32_e32 v6, v2, v38
	v_mul_f32_e32 v7, v2, v39
	v_mul_f32_e32 v20, v20, v76
	v_mul_f32_e32 v21, v21, v77
	v_mul_f32_e32 v22, v22, v78
	v_mul_f32_e32 v23, v23, v79
	v_cvt_pk_bf16_f32 v4, v4, v5
	v_cvt_pk_bf16_f32 v5, v6, v7
	flat_store_dwordx2 v[134:135], v[4:5] offset:112
	v_mul_f32_e32 v4, v2, v20
	v_mul_f32_e32 v5, v2, v21
	v_mul_f32_e32 v6, v2, v22
	v_mul_f32_e32 v7, v2, v23
	v_mul_f32_e32 v40, v106, v80
	v_mul_f32_e32 v41, v107, v81
	v_mul_f32_e32 v42, v104, v82
	v_mul_f32_e32 v43, v105, v83
	v_cvt_pk_bf16_f32 v4, v4, v5
	v_cvt_pk_bf16_f32 v5, v6, v7
	flat_store_dwordx2 v[134:135], v[4:5] offset:128
	v_mul_f32_e32 v4, v2, v40
	v_mul_f32_e32 v5, v2, v41
	v_mul_f32_e32 v6, v2, v42
	v_mul_f32_e32 v7, v2, v43
	v_mul_f32_e32 v44, v110, v84
	v_mul_f32_e32 v45, v111, v85
	v_mul_f32_e32 v46, v108, v86
	v_mul_f32_e32 v47, v109, v87
	v_cvt_pk_bf16_f32 v4, v4, v5
	v_cvt_pk_bf16_f32 v5, v6, v7
	flat_store_dwordx2 v[134:135], v[4:5] offset:144
	v_mul_f32_e32 v4, v2, v44
	v_mul_f32_e32 v5, v2, v45
	v_mul_f32_e32 v6, v2, v46
	v_mul_f32_e32 v7, v2, v47
	v_mul_f32_e32 v48, v114, v88
	v_mul_f32_e32 v49, v115, v89
	v_mul_f32_e32 v50, v112, v90
	v_mul_f32_e32 v51, v113, v91
	v_cvt_pk_bf16_f32 v4, v4, v5
	v_cvt_pk_bf16_f32 v5, v6, v7
	flat_store_dwordx2 v[134:135], v[4:5] offset:160
	v_mul_f32_e32 v4, v2, v48
	v_mul_f32_e32 v5, v2, v49
	v_mul_f32_e32 v6, v2, v50
	v_mul_f32_e32 v7, v2, v51
	v_mul_f32_e32 v52, v118, v92
	v_mul_f32_e32 v53, v119, v93
	v_mul_f32_e32 v54, v116, v94
	v_mul_f32_e32 v55, v117, v95
	v_cvt_pk_bf16_f32 v4, v4, v5
	v_cvt_pk_bf16_f32 v5, v6, v7
	flat_store_dwordx2 v[134:135], v[4:5] offset:176
	v_mul_f32_e32 v4, v2, v52
	v_mul_f32_e32 v5, v2, v53
	v_mul_f32_e32 v6, v2, v54
	v_mul_f32_e32 v7, v2, v55
	v_mul_f32_e32 v56, v122, v96
	v_mul_f32_e32 v57, v123, v97
	v_mul_f32_e32 v58, v120, v98
	v_mul_f32_e32 v59, v121, v99
	v_cvt_pk_bf16_f32 v4, v4, v5
	v_cvt_pk_bf16_f32 v5, v6, v7
	flat_store_dwordx2 v[134:135], v[4:5] offset:192
	v_mul_f32_e32 v4, v2, v56
	v_mul_f32_e32 v5, v2, v57
	v_mul_f32_e32 v6, v2, v58
	v_mul_f32_e32 v7, v2, v59
	v_mul_f32_e32 v60, v126, v100
	v_mul_f32_e32 v61, v127, v101
	v_mul_f32_e32 v62, v124, v102
	v_mul_f32_e32 v63, v125, v103
	v_cvt_pk_bf16_f32 v4, v4, v5
	v_cvt_pk_bf16_f32 v5, v6, v7
	flat_store_dwordx2 v[134:135], v[4:5] offset:208
	v_mul_f32_e32 v4, v2, v60
	v_mul_f32_e32 v5, v2, v61
	v_mul_f32_e32 v6, v2, v62
	v_mul_f32_e32 v7, v2, v63
	v_mul_f32_e32 v64, v130, v68
	v_mul_f32_e32 v65, v131, v69
	v_mul_f32_e32 v66, v128, v70
	v_mul_f32_e32 v67, v129, v71
	v_cvt_pk_bf16_f32 v4, v4, v5
	v_cvt_pk_bf16_f32 v5, v6, v7
	flat_store_dwordx2 v[134:135], v[4:5] offset:224
	v_mul_f32_e32 v4, v2, v64
	v_mul_f32_e32 v5, v2, v65
	v_mul_f32_e32 v6, v2, v66
	v_mul_f32_e32 v7, v2, v67
	v_cvt_pk_bf16_f32 v4, v4, v5
	v_cvt_pk_bf16_f32 v5, v6, v7
	flat_store_dwordx2 v[134:135], v[4:5] offset:240
	s_branch .LBB0_550

; __device__ __forceinline__ float half_sum(float v) { unsigned a, b; half_swap(__builtin_bit_cast(unsigned, v), a, b); return __builtin_bit_cast(float, a) + __builtin_bit_cast(float, b); }
; __device__ __forceinline__ unsigned cvtpk(float lo, float hi) { f32x2_t v = {lo, hi}; bf16x2_t b = __builtin_convertvector(v, bf16x2_t); return __builtin_bit_cast(unsigned, b); }
; template <int NDT>
; __device__ __forceinline__ void store_ot(bf16* orow  , const f32x16 (&o)[NDT], float scale, int hh) {
; #pragma unroll
;     for (int dt = 0; dt < NDT; ++dt)
; #pragma unroll
;         for (int g = 0; g < 4; ++g) { v2u w; w.x = cvtpk(o[dt][4 * g] * scale, o[dt][4 * g + 1] * scale); w.y = cvtpk(o[dt][4 * g + 2] * scale, o[dt][4 * g + 3] * scale);
;             *(v2u*)(orow + 32 * dt + 8 * g + 4 * hh) = w; }
; __device__ __forceinline__ void fox_coop(const bf16* PROJ, const float* CUM, const unsigned char* VTB, bf16* O, int bh, int c, LAS unsigned char* sbuf, int tid) {
;     ...
;     l = half_sum(l);
;     store_ot<2>(O + row * DM + O_FOX + hd * 64, o, 1.f / l, hh);
.LBB0_617:
	v_mov_b32_e32 v2, v229
	s_waitcnt lgkmcnt(0)
	s_barrier
	s_lshl_b32 s4, s11, 6
	v_permlane32_swap_b32_e32 v229, v2
	v_add_f32_e32 v2, v229, v2
	s_lshl_b32 s18, s4, 1
	v_div_scale_f32 v6, s[4:5], v2, v2, 1.0
	v_rcp_f32_e32 v7, v6
	v_lshlrev_b64 v[4:5], 12, v[218:219]
	v_lshl_add_u64 v[4:5], s[26:27], 0, v[4:5]
	v_lshl_add_u64 v[4:5], v[4:5], 0, s[18:19]
	v_fma_f32 v8, -v6, v7, 1.0
	v_fmac_f32_e32 v7, v8, v7
	v_div_scale_f32 v8, vcc, 1.0, v2, 1.0
	v_mul_f32_e32 v9, v8, v7
	v_fma_f32 v10, -v6, v9, v8
	v_fmac_f32_e32 v9, v10, v7
	v_fma_f32 v6, -v6, v9, v8
	v_div_fmas_f32 v6, v6, v7, v9
	v_div_fixup_f32 v6, v6, v2, 1.0
	v_lshlrev_b32_e32 v2, 1, v1
	v_lshl_add_u64 v[4:5], v[4:5], 0, v[2:3]
	s_mov_b64 s[4:5], 0x2800000
	v_lshl_add_u64 v[8:9], v[4:5], 0, s[4:5]
	v_mul_f32_e32 v10, v34, v6
	v_mul_f32_e32 v11, v35, v6
	v_mul_f32_e32 v12, v36, v6
	v_mul_f32_e32 v13, v37, v6
	v_add_co_u32_e32 v4, vcc, s88, v4
	v_cvt_pk_bf16_f32 v10, v10, v11
	v_cvt_pk_bf16_f32 v11, v12, v13
	v_addc_co_u32_e32 v5, vcc, 0, v5, vcc
	flat_store_dwordx2 v[4:5], v[10:11]
	v_mul_f32_e32 v4, v38, v6
	v_mul_f32_e32 v5, v39, v6
	v_mul_f32_e32 v10, v40, v6
	v_mul_f32_e32 v11, v41, v6
	v_cvt_pk_bf16_f32 v4, v4, v5
	v_cvt_pk_bf16_f32 v5, v10, v11
	flat_store_dwordx2 v[8:9], v[4:5] offset:16
	v_mul_f32_e32 v4, v42, v6
	v_mul_f32_e32 v5, v43, v6
	v_mul_f32_e32 v10, v44, v6
	v_mul_f32_e32 v11, v45, v6
	v_cvt_pk_bf16_f32 v4, v4, v5
	v_cvt_pk_bf16_f32 v5, v10, v11
	flat_store_dwordx2 v[8:9], v[4:5] offset:32
	v_mul_f32_e32 v4, v46, v6
	v_mul_f32_e32 v5, v47, v6
	v_mul_f32_e32 v10, v48, v6
	v_mul_f32_e32 v11, v49, v6
	v_cvt_pk_bf16_f32 v4, v4, v5
	v_cvt_pk_bf16_f32 v5, v10, v11
	flat_store_dwordx2 v[8:9], v[4:5] offset:48
	v_mul_f32_e32 v4, v18, v6
	v_mul_f32_e32 v5, v19, v6
	v_mul_f32_e32 v10, v20, v6
	v_mul_f32_e32 v11, v21, v6
	v_cvt_pk_bf16_f32 v4, v4, v5
	v_cvt_pk_bf16_f32 v5, v10, v11
	flat_store_dwordx2 v[8:9], v[4:5] offset:64
	v_mul_f32_e32 v4, v22, v6
	v_mul_f32_e32 v5, v23, v6
	v_mul_f32_e32 v10, v24, v6
	v_mul_f32_e32 v11, v25, v6
	v_cvt_pk_bf16_f32 v4, v4, v5
	v_cvt_pk_bf16_f32 v5, v10, v11
	flat_store_dwordx2 v[8:9], v[4:5] offset:80
	v_mul_f32_e32 v4, v26, v6
	v_mul_f32_e32 v5, v27, v6
	v_mul_f32_e32 v10, v28, v6
	v_mul_f32_e32 v11, v29, v6
	v_cvt_pk_bf16_f32 v4, v4, v5
	v_cvt_pk_bf16_f32 v5, v10, v11
	flat_store_dwordx2 v[8:9], v[4:5] offset:96
	v_mul_f32_e32 v4, v30, v6
	v_mul_f32_e32 v5, v31, v6
	v_mul_f32_e32 v7, v33, v6
	v_mul_f32_e32 v6, v32, v6
	v_cvt_pk_bf16_f32 v4, v4, v5
	v_cvt_pk_bf16_f32 v5, v6, v7
	s_mov_b64 s[16:17], 0
	flat_store_dwordx2 v[8:9], v[4:5] offset:112

; #define LAS __attribute__((address_space(3)))
; template <int NDT, class F>
; __device__ __forceinline__ void softmax_body(f32x16& s, const F& f, int k0, int hh, f32x16 (&o)[NDT], float& m, float& l, bf16x8& pf0, bf16x8& pf1, const int MASK) {
;     float mx = NEG_BIG;
;     if (MASK == 1) {
; #pragma unroll
;         for (int r = 0; r < 16; ++r) s[r] = f.valid(k0 + CR(r) + 4 * hh) ? s[r] : NEG_BIG; }
; #pragma unroll
;     for (int r = 0; r < 16; ++r) mx = fmaxf(mx, s[r]);
;     mx = fmaf(mx, QK_SCL, f.tadd);
;     const bool on = MASK != 2 || f.lane_on();
;     mx = on ? mx : NEG_BIG;
;     mx = half_max(mx);
; template <int NDT, class F>
; __device__ __forceinline__ void coop_step(const bf16x8 (&qf)[4], const LAS unsigned char* buf, int fk, int fv, int vsub  , F& f, int st, int t0_mine, int hh, f32x16 (&o)[NDT], float& m, float& l) {
;     ...
;     if (k1 <= t0_mine) {
;         f32x16 sA, sB;
; #pragma unroll
;         for (int ks = 0; ks < 4; ++ks) { const bf16x8 kf = *(const LAS bf16x8*)(buf + 4096 + (fk ^ (ks << 5))); sA = MFMA32(kf, qf[ks], ks == 0 ? f.c1() : sA); }
;         if (NDT == 2) {
; #pragma unroll
;             for (int ks = 0; ks < 4; ++ks) { const bf16x8 kf = *(const LAS bf16x8*)(buf + (fk ^ (ks << 5))); sB = MFMA32(kf, qf[ks], ks == 0 ? f.c0() : sB); }
;             if (st > 0) f.fetch2(st - 1);
;             __builtin_amdgcn_sched_barrier(0); }
;         f.begin(k1); softmax_body<NDT>(sA, f, k1, hh, o, m, l, pf0, pf1, k1 == t0_mine ? 1 : 0);
; #pragma unroll
;         for (int dt = 0; dt < NDT; ++dt) { const bf16x8 vf0 = *(const LAS bf16x8*)(buf + 4096 + dt * 2048 + fv + vsub), vf1 = *(const LAS bf16x8*)(buf + 4096 + dt * 2048 + ((fv + vsub) ^ 32));
;             o[dt] = MFMA32(vf0, pf0, o[dt]); o[dt] = MFMA32(vf1, pf1, o[dt]); }
;         if (NDT != 2) {
; #pragma unroll
;             for (int ks = 0; ks < 4; ++ks) { const bf16x8 kf = *(const LAS bf16x8*)(buf + (fk ^ (ks << 5))); sB = MFMA32(kf, qf[ks], ks == 0 ? f.c0() : sB); }
;             if (st > 0) f.fetch2(st - 1); }
;         f.begin(k0); softmax_body<NDT>(sB, f, k0, hh, o, m, l, pf0, pf1, 0);
; #pragma unroll
;         for (int dt = 0; dt < NDT; ++dt) { const bf16x8 vf0 = *(const LAS bf16x8*)(buf + dt * 2048 + fv), vf1 = *(const LAS bf16x8*)(buf + dt * 2048 + (fv ^ 32));
;             o[dt] = MFMA32(vf0, pf0, o[dt]); o[dt] = MFMA32(vf1, pf1, o[dt]); }
.LBB0_637:
	v_max_f32_e32 v5, v2, v2
	v_max_f32_e32 v4, 0xefa18f08, v5
	v_sub_f32_e32 v4, v241, v4
	v_fma_f32 v8, v82, s34, v4
	v_fma_f32 v9, v83, s34, v4
	v_fma_f32 v12, v84, s34, v4
	v_fma_f32 v13, v85, s34, v4
	v_exp_f32_e32 v10, v8
	v_exp_f32_e32 v11, v9
	v_exp_f32_e32 v12, v12
	v_exp_f32_e32 v13, v13
	v_fma_f32 v14, v86, s34, v4
	v_fma_f32 v15, v87, s34, v4
	v_fma_f32 v16, v88, s34, v4
	v_fma_f32 v17, v89, s34, v4
	v_exp_f32_e32 v14, v14
	v_exp_f32_e32 v15, v15
	v_exp_f32_e32 v16, v16
	v_exp_f32_e32 v17, v17
	v_fma_f32 v82, v90, s34, v4
	v_fma_f32 v83, v91, s34, v4
	v_pk_add_f32 v[8:9], v[10:11], 0 op_sel_hi:[1,0]
	v_exp_f32_e32 v82, v82
	v_exp_f32_e32 v83, v83
	v_fma_f32 v84, v92, s34, v4
	v_fma_f32 v85, v93, s34, v4
	v_add_f32_e32 v8, v12, v8
	v_add_f32_e32 v9, v13, v9
	v_exp_f32_e32 v84, v84
	v_exp_f32_e32 v85, v85
	v_fma_f32 v86, v94, s34, v4
	v_fma_f32 v87, v95, s34, v4
	v_add_f32_e32 v8, v14, v8
	v_add_f32_e32 v9, v15, v9
	v_exp_f32_e32 v86, v86
	v_exp_f32_e32 v87, v87
	v_fma_f32 v88, v96, s34, v4
	v_fma_f32 v89, v97, s34, v4
	v_add_f32_e32 v8, v16, v8
	v_add_f32_e32 v9, v17, v9
	v_exp_f32_e32 v88, v88
	v_exp_f32_e32 v89, v89
	v_add_f32_e32 v8, v82, v8
	v_add_f32_e32 v9, v83, v9
	v_cvt_pk_bf16_f32 v10, v10, v11
	v_add_f32_e32 v8, v84, v8
	v_add_f32_e32 v9, v85, v9
	v_cvt_pk_bf16_f32 v11, v12, v13
	v_add_f32_e32 v8, v86, v8
	v_add_f32_e32 v9, v87, v9
	v_cvt_pk_bf16_f32 v12, v14, v15
	v_add_f32_e32 v8, v88, v8
	v_add_f32_e32 v9, v89, v9
	v_cvt_pk_bf16_f32 v14, v82, v83
	v_add_f32_e32 v7, v8, v9
	v_add_f32_e32 v8, v6, v7
	v_add_u32_e32 v7, 0, v243
	v_cvt_pk_bf16_f32 v15, v84, v85
	ds_read_b128 v[82:85], v7 offset:12288
	v_add_u32_e32 v6, 0, v247
	v_cvt_pk_bf16_f32 v13, v16, v17
	v_cvt_pk_bf16_f32 v16, v86, v87
	v_cvt_pk_bf16_f32 v17, v88, v89
	ds_read_b128 v[86:89], v6 offset:12288
	s_waitcnt lgkmcnt(1)
	v_mfma_f32_32x32x16_bf16 v[114:129], v[82:85], v[10:13], v[114:129]
	v_max3_f32 v9, v146, s86, v147
	v_max3_f32 v9, v9, v148, v149
	v_max3_f32 v9, v9, v150, v151
	v_max3_f32 v9, v9, v152, v153
	v_max3_f32 v9, v9, v154, v155
	v_max3_f32 v9, v9, v156, v157
	v_max3_f32 v9, v9, v158, v159
	s_waitcnt lgkmcnt(0)
	v_mfma_f32_32x32x16_bf16 v[114:129], v[86:89], v[14:17], v[114:129]
	ds_read_b128 v[82:85], v7 offset:14336
	ds_read_b128 v[86:89], v6 offset:14336
	v_max3_f32 v9, v9, v160, v161
	v_fmamk_f32 v9, v9, 0x3e38aa3b, v241
	s_waitcnt lgkmcnt(1)
	v_mfma_f32_32x32x16_bf16 v[130:145], v[82:85], v[10:13], v[130:145]
	v_mov_b32_e32 v10, v9
	s_nop 1
	v_permlane32_swap_b32_e32 v9, v10
	v_max_f32_e32 v10, v10, v10
	v_max_f32_e32 v9, v9, v9
	s_waitcnt lgkmcnt(0)
	v_mfma_f32_32x32x16_bf16 v[130:145], v[86:89], v[14:17], v[130:145]
	v_max_f32_e32 v9, v9, v10
	v_cmp_gt_f32_e32 vcc, v9, v2
	s_cbranch_vccz .LBB0_639
	v_max_f32_e32 v4, v9, v9
	v_max_f32_e32 v5, v5, v4
	v_sub_f32_e32 v2, v2, v5
	v_exp_f32_e32 v2, v2
	s_nop 0
	v_mul_f32_e32 v8, v2, v8
	v_pk_mul_f32 v[128:129], v[128:129], v[2:3] op_sel_hi:[1,0]
	v_pk_mul_f32 v[126:127], v[126:127], v[2:3] op_sel_hi:[1,0]
	v_pk_mul_f32 v[124:125], v[124:125], v[2:3] op_sel_hi:[1,0]
	v_pk_mul_f32 v[122:123], v[122:123], v[2:3] op_sel_hi:[1,0]
	v_pk_mul_f32 v[120:121], v[120:121], v[2:3] op_sel_hi:[1,0]
	v_pk_mul_f32 v[118:119], v[118:119], v[2:3] op_sel_hi:[1,0]
	v_pk_mul_f32 v[116:117], v[116:117], v[2:3] op_sel_hi:[1,0]
	v_pk_mul_f32 v[114:115], v[114:115], v[2:3] op_sel_hi:[1,0]
	v_pk_mul_f32 v[144:145], v[144:145], v[2:3] op_sel_hi:[1,0]
	v_pk_mul_f32 v[142:143], v[142:143], v[2:3] op_sel_hi:[1,0]
	v_pk_mul_f32 v[140:141], v[140:141], v[2:3] op_sel_hi:[1,0]
	v_pk_mul_f32 v[138:139], v[138:139], v[2:3] op_sel_hi:[1,0]
	v_pk_mul_f32 v[136:137], v[136:137], v[2:3] op_sel_hi:[1,0]
	v_pk_mul_f32 v[134:135], v[134:135], v[2:3] op_sel_hi:[1,0]
	v_pk_mul_f32 v[132:133], v[132:133], v[2:3] op_sel_hi:[1,0]
	v_pk_mul_f32 v[130:131], v[130:131], v[2:3] op_sel_hi:[1,0]
	v_max_f32_e32 v2, 0xefa18f08, v5
	v_sub_f32_e32 v4, v241, v2
	v_mov_b32_e32 v2, v5
.LBB0_639:
	v_mov_b32_e32 v5, v4
	v_fma_f32 v10, v146, s34, v4
	v_fma_f32 v11, v147, s34, v5
	v_fma_f32 v14, v148, s34, v4
	v_fma_f32 v15, v149, s34, v5
	v_exp_f32_e32 v10, v10
	v_exp_f32_e32 v11, v11
	v_exp_f32_e32 v14, v14
	v_exp_f32_e32 v15, v15
	v_fma_f32 v16, v150, s34, v4
	v_fma_f32 v17, v151, s34, v5
	v_fma_f32 v82, v152, s34, v4
	v_fma_f32 v83, v153, s34, v5
	v_exp_f32_e32 v16, v16
	v_exp_f32_e32 v17, v17
	v_exp_f32_e32 v82, v82
	v_exp_f32_e32 v83, v83
	v_fma_f32 v84, v154, s34, v4
	v_fma_f32 v85, v155, s34, v5
	v_pk_add_f32 v[12:13], v[10:11], 0 op_sel_hi:[1,0]
	v_exp_f32_e32 v84, v84
	v_exp_f32_e32 v85, v85
	v_fma_f32 v86, v156, s34, v4
	v_fma_f32 v87, v157, s34, v5
	v_add_f32_e32 v12, v14, v12
	v_add_f32_e32 v13, v15, v13
	v_exp_f32_e32 v86, v86
	v_exp_f32_e32 v87, v87
	v_fma_f32 v88, v158, s34, v4
	v_fma_f32 v89, v159, s34, v5
	v_add_f32_e32 v12, v16, v12
	v_add_f32_e32 v13, v17, v13
	v_exp_f32_e32 v88, v88
	v_exp_f32_e32 v89, v89
	v_fmac_f32_e32 v4, s34, v160
	v_fmac_f32_e32 v5, s34, v161
	v_add_f32_e32 v12, v82, v12
	v_add_f32_e32 v13, v83, v13
	v_exp_f32_e32 v90, v4
	v_exp_f32_e32 v91, v5
	v_add_f32_e32 v12, v84, v12
	v_add_f32_e32 v13, v85, v13
	v_cvt_pk_bf16_f32 v9, v14, v15
	v_add_f32_e32 v12, v86, v12
	v_add_f32_e32 v13, v87, v13
	v_cvt_pk_bf16_f32 v14, v88, v89
	v_add_f32_e32 v12, v88, v12
	v_add_f32_e32 v13, v89, v13
	v_cvt_pk_bf16_f32 v15, v90, v91
	v_add_f32_e32 v4, v90, v12
	v_add_f32_e32 v5, v91, v13
	v_cvt_pk_bf16_f32 v12, v84, v85
	v_add_f32_e32 v4, v4, v5
	v_add_f32_e32 v4, v8, v4
	v_cvt_pk_bf16_f32 v8, v10, v11
	v_cvt_pk_bf16_f32 v11, v82, v83
	v_cvt_pk_bf16_f32 v13, v86, v87
	ds_read_b128 v[82:85], v7 offset:8192
	ds_read_b128 v[86:89], v6 offset:8192
	v_cvt_pk_bf16_f32 v10, v16, v17
	s_mov_b64 s[16:17], 0
	s_waitcnt lgkmcnt(1)
	v_mfma_f32_32x32x16_bf16 v[114:129], v[82:85], v[8:11], v[114:129]
	s_waitcnt lgkmcnt(0)
	v_mfma_f32_32x32x16_bf16 v[114:129], v[86:89], v[12:15], v[114:129]
	ds_read_b128 v[82:85], v7 offset:10240
	ds_read_b128 v[86:89], v6 offset:10240
	s_waitcnt lgkmcnt(1)
	v_mfma_f32_32x32x16_bf16 v[130:145], v[82:85], v[8:11], v[130:145]
	s_waitcnt lgkmcnt(0)
	v_mfma_f32_32x32x16_bf16 v[130:145], v[86:89], v[12:15], v[130:145]

; #define LAS __attribute__((address_space(3)))
; template <int NDT, class F>
; __device__ __forceinline__ void softmax_body(f32x16& s, const F& f, int k0, int hh, f32x16 (&o)[NDT], float& m, float& l, bf16x8& pf0, bf16x8& pf1, const int MASK) {
;     float mx = NEG_BIG;
;     if (MASK == 1) {
; #pragma unroll
;         for (int r = 0; r < 16; ++r) s[r] = f.valid(k0 + CR(r) + 4 * hh) ? s[r] : NEG_BIG; }
; #pragma unroll
;     for (int r = 0; r < 16; ++r) mx = fmaxf(mx, s[r]);
;     mx = fmaf(mx, QK_SCL, f.tadd);
;     const bool on = MASK != 2 || f.lane_on();
;     mx = on ? mx : NEG_BIG;
;     mx = half_max(mx);
;     if (__ballot(mx > m) != 0ull) { const float mn = fmaxf(m, mx), alpha = __builtin_amdgcn_exp2f(m - mn); m = mn; l *= alpha;
; #pragma unroll
;         for (int dt = 0; dt < NDT; ++dt) o[dt] = o[dt] * alpha; }
;     const float me = fmaxf(m, -1e29f);
;     const float off = on ? f.tadd - me : NEG_BIG;
;     const f32x2_t sc2 = {QK_SCL, QK_SCL}, of2 = {off, off}; f32x2_t ps2 = {0.f, 0.f};
; #pragma unroll
;     for (int r = 0; r < 16; r += 2) { f32x2_t a = {s[r], s[r + 1]}; a = __builtin_elementwise_fma(a, sc2, of2);
;         f32x2_t p; p.x = __builtin_amdgcn_exp2f(a.x); p.y = __builtin_amdgcn_exp2f(a.y); s[r] = p.x; s[r + 1] = p.y; ps2 += p; }
;     l += ps2.x + ps2.y;
;     v4u p0, p1;
;     p0.x = cvtpk(s[0], s[1]); p0.y = cvtpk(s[2], s[3]); p0.z = cvtpk(s[4], s[5]); p0.w = cvtpk(s[6], s[7]);
;     p1.x = cvtpk(s[8], s[9]); p1.y = cvtpk(s[10], s[11]); p1.z = cvtpk(s[12], s[13]); p1.w = cvtpk(s[14], s[15]);
; template <int NDT, class F>
; __device__ __forceinline__ void coop_step(const bf16x8 (&qf)[4], const LAS unsigned char* buf, int fk, int fv, int vsub  , F& f, int st, int t0_mine, int hh, f32x16 (&o)[NDT], float& m, float& l) {
;     ...
;     } else {
;         f32x16 sB;
; #pragma unroll
;         for (int ks = 0; ks < 4; ++ks) { const bf16x8 kf = *(const LAS bf16x8*)(buf + (fk ^ (ks << 5))); sB = MFMA32(kf, qf[ks], ks == 0 ? f.c0() : sB); }
;         if (st > 0) f.fetch2(st - 1);
;         f.begin(k0); softmax_body<NDT>(sB, f, k0, hh, o, m, l, pf0, pf1, 1);
; #pragma unroll
;         for (int dt = 0; dt < NDT; ++dt) { const bf16x8 vf0 = *(const LAS bf16x8*)(buf + dt * 2048 + fv), vf1 = *(const LAS bf16x8*)(buf + dt * 2048 + (fv ^ 32));
;             o[dt] = MFMA32(vf0, pf0, o[dt]); o[dt] = MFMA32(vf1, pf1, o[dt]); }
;     }
.LBB0_643:
	v_max_f32_e32 v2, v248, v248
	v_max_f32_e32 v2, 0xefa18f08, v2
	v_sub_f32_e32 v2, v241, v2
	v_fma_f32 v4, v4, s34, v2
	v_fma_f32 v5, v5, s34, v2
	v_fma_f32 v6, v6, s34, v2
	v_fma_f32 v7, v7, s34, v2
	v_exp_f32_e32 v52, v4
	v_exp_f32_e32 v53, v5
	v_exp_f32_e32 v54, v6
	v_exp_f32_e32 v55, v7
	v_fma_f32 v6, v8, s34, v2
	v_fma_f32 v7, v9, s34, v2
	v_pk_add_f32 v[4:5], v[52:53], 0 op_sel_hi:[1,0]
	v_exp_f32_e32 v8, v6
	v_exp_f32_e32 v9, v7
	v_fma_f32 v6, v50, s34, v2
	v_fma_f32 v7, v51, s34, v2
	v_add_f32_e32 v4, v54, v4
	v_add_f32_e32 v5, v55, v5
	v_exp_f32_e32 v50, v6
	v_exp_f32_e32 v51, v7
	v_fma_f32 v6, v16, s34, v2
	v_fma_f32 v7, v17, s34, v2
	v_add_f32_e32 v4, v8, v4
	v_add_f32_e32 v5, v9, v5
	v_exp_f32_e32 v16, v6
	v_exp_f32_e32 v17, v7
	v_fma_f32 v6, v14, s34, v2
	v_fma_f32 v7, v15, s34, v2
	v_add_f32_e32 v4, v50, v4
	v_add_f32_e32 v5, v51, v5
	v_exp_f32_e32 v14, v6
	v_exp_f32_e32 v15, v7
	v_fma_f32 v6, v10, s34, v2
	v_fma_f32 v7, v11, s34, v2
	v_add_f32_e32 v4, v16, v4
	v_add_f32_e32 v5, v17, v5
	v_exp_f32_e32 v56, v6
	v_exp_f32_e32 v57, v7
	v_fma_f32 v6, v12, s34, v2
	v_fma_f32 v7, v13, s34, v2
	v_add_f32_e32 v4, v14, v4
	v_add_f32_e32 v5, v15, v5
	v_exp_f32_e32 v58, v6
	v_exp_f32_e32 v59, v7
	v_add_f32_e32 v4, v56, v4
	v_add_f32_e32 v5, v57, v5
	v_cvt_pk_bf16_f32 v10, v16, v17
	v_cvt_pk_bf16_f32 v11, v14, v15
	v_add_f32_e32 v4, v58, v4
	v_add_f32_e32 v5, v59, v5
	v_cvt_pk_bf16_f32 v6, v52, v53
	v_add_f32_e32 v2, v4, v5
	v_add_f32_e32 v4, v229, v2
	v_add_u32_e32 v2, 0, v243
	ds_read_b128 v[14:17], v2 offset:8192
	v_add_u32_e32 v5, 0, v247
	v_cvt_pk_bf16_f32 v7, v54, v55
	v_cvt_pk_bf16_f32 v8, v8, v9
	v_cvt_pk_bf16_f32 v9, v50, v51
	ds_read_b128 v[50:53], v5 offset:8192
	v_cvt_pk_bf16_f32 v12, v56, v57
	s_waitcnt lgkmcnt(1)
	v_mfma_f32_32x32x16_bf16 v[34:49], v[14:17], v[6:9], v[34:49]
	v_cvt_pk_bf16_f32 v13, v58, v59
	s_waitcnt lgkmcnt(0)
	s_nop 0
	v_mfma_f32_32x32x16_bf16 v[34:49], v[50:53], v[10:13], v[34:49]
	ds_read_b128 v[14:17], v2 offset:10240
	ds_read_b128 v[50:53], v5 offset:10240
	v_mov_b32_e32 v2, v248
	s_waitcnt lgkmcnt(1)
	v_mfma_f32_32x32x16_bf16 v[18:33], v[14:17], v[6:9], v[18:33]
	s_nop 6
	v_mov_b64_e32 v[128:129], v[48:49]
	v_mov_b64_e32 v[126:127], v[46:47]
	v_mov_b64_e32 v[124:125], v[44:45]
	v_mov_b64_e32 v[122:123], v[42:43]
	v_mov_b64_e32 v[120:121], v[40:41]
	v_mov_b64_e32 v[118:119], v[38:39]
	v_mov_b64_e32 v[116:117], v[36:37]
	s_waitcnt lgkmcnt(0)
	v_mfma_f32_32x32x16_bf16 v[18:33], v[50:53], v[10:13], v[18:33]
	v_mov_b64_e32 v[114:115], v[34:35]
	s_nop 10
	v_mov_b64_e32 v[144:145], v[32:33]
	v_mov_b64_e32 v[142:143], v[30:31]
	v_mov_b64_e32 v[140:141], v[28:29]
	v_mov_b64_e32 v[138:139], v[26:27]
	v_mov_b64_e32 v[136:137], v[24:25]
	v_mov_b64_e32 v[134:135], v[22:23]
	v_mov_b64_e32 v[132:133], v[20:21]
	v_mov_b64_e32 v[130:131], v[18:19]

; #define LAS __attribute__((address_space(3)))
; template <int NDT, class F>
; __device__ __forceinline__ void softmax_body(f32x16& s, const F& f, int k0, int hh, f32x16 (&o)[NDT], float& m, float& l, bf16x8& pf0, bf16x8& pf1, const int MASK) {
;     float mx = NEG_BIG;
;     if (MASK == 1) {
; #pragma unroll
;         for (int r = 0; r < 16; ++r) s[r] = f.valid(k0 + CR(r) + 4 * hh) ? s[r] : NEG_BIG; }
; #pragma unroll
;     for (int r = 0; r < 16; ++r) mx = fmaxf(mx, s[r]);
;     mx = fmaf(mx, QK_SCL, f.tadd);
;     const bool on = MASK != 2 || f.lane_on();
;     mx = on ? mx : NEG_BIG;
;     mx = half_max(mx);
; template <int NDT, class F>
; __device__ __forceinline__ void coop_step(const bf16x8 (&qf)[4], const LAS unsigned char* buf, int fk, int fv, int vsub  , F& f, int st, int t0_mine, int hh, f32x16 (&o)[NDT], float& m, float& l) {
;     ...
;     if (k1 <= t0_mine) {
;         f32x16 sA, sB;
; #pragma unroll
;         for (int ks = 0; ks < 4; ++ks) { const bf16x8 kf = *(const LAS bf16x8*)(buf + 4096 + (fk ^ (ks << 5))); sA = MFMA32(kf, qf[ks], ks == 0 ? f.c1() : sA); }
;         if (NDT == 2) {
; #pragma unroll
;             for (int ks = 0; ks < 4; ++ks) { const bf16x8 kf = *(const LAS bf16x8*)(buf + (fk ^ (ks << 5))); sB = MFMA32(kf, qf[ks], ks == 0 ? f.c0() : sB); }
;             if (st > 0) f.fetch2(st - 1);
;             __builtin_amdgcn_sched_barrier(0); }
;         f.begin(k1); softmax_body<NDT>(sA, f, k1, hh, o, m, l, pf0, pf1, k1 == t0_mine ? 1 : 0);
; #pragma unroll
;         for (int dt = 0; dt < NDT; ++dt) { const bf16x8 vf0 = *(const LAS bf16x8*)(buf + 4096 + dt * 2048 + fv + vsub), vf1 = *(const LAS bf16x8*)(buf + 4096 + dt * 2048 + ((fv + vsub) ^ 32));
;             o[dt] = MFMA32(vf0, pf0, o[dt]); o[dt] = MFMA32(vf1, pf1, o[dt]); }
;         if (NDT != 2) {
; #pragma unroll
;             for (int ks = 0; ks < 4; ++ks) { const bf16x8 kf = *(const LAS bf16x8*)(buf + (fk ^ (ks << 5))); sB = MFMA32(kf, qf[ks], ks == 0 ? f.c0() : sB); }
;             if (st > 0) f.fetch2(st - 1); }
;         f.begin(k0); softmax_body<NDT>(sB, f, k0, hh, o, m, l, pf0, pf1, 0);
; #pragma unroll
;         for (int dt = 0; dt < NDT; ++dt) { const bf16x8 vf0 = *(const LAS bf16x8*)(buf + dt * 2048 + fv), vf1 = *(const LAS bf16x8*)(buf + dt * 2048 + (fv ^ 32));
;             o[dt] = MFMA32(vf0, pf0, o[dt]); o[dt] = MFMA32(vf1, pf1, o[dt]); }
.LBB0_656:
	v_max_f32_e32 v17, v253, v253
	v_max_f32_e32 v16, 0xefa18f08, v17
	v_sub_f32_e32 v16, v241, v16
	v_fma_f32 v98, v98, s34, v16
	v_fma_f32 v99, v99, s34, v16
	v_fma_f32 v100, v100, s34, v16
	v_fma_f32 v101, v101, s34, v16
	v_exp_f32_e32 v98, v98
	v_exp_f32_e32 v99, v99
	v_exp_f32_e32 v216, v100
	v_exp_f32_e32 v217, v101
	v_fma_f32 v102, v102, s34, v16
	v_fma_f32 v103, v103, s34, v16
	v_pk_add_f32 v[214:215], v[98:99], 0 op_sel_hi:[1,0]
	s_nop 0
	v_add_f32_e32 v100, v216, v214
	v_add_f32_e32 v101, v217, v215
	v_exp_f32_e32 v214, v102
	v_exp_f32_e32 v215, v103
	v_fma_f32 v102, v104, s34, v16
	v_fma_f32 v103, v105, s34, v16
	v_add_f32_e32 v100, v214, v100
	v_add_f32_e32 v101, v215, v101
	v_exp_f32_e32 v232, v102
	v_exp_f32_e32 v233, v103
	v_fma_f32 v102, v106, s34, v16
	v_fma_f32 v103, v107, s34, v16
	v_cvt_pk_bf16_f32 v104, v214, v215
	v_exp_f32_e32 v106, v102
	v_exp_f32_e32 v107, v103
	v_fma_f32 v102, v108, s34, v16
	v_fma_f32 v103, v109, s34, v16
	v_add_f32_e32 v100, v232, v100
	v_add_f32_e32 v101, v233, v101
	v_exp_f32_e32 v108, v102
	v_exp_f32_e32 v109, v103
	v_fma_f32 v102, v110, s34, v16
	v_fma_f32 v103, v111, s34, v16
	v_add_f32_e32 v100, v106, v100
	v_add_f32_e32 v101, v107, v101
	v_exp_f32_e32 v110, v102
	v_exp_f32_e32 v111, v103
	v_fma_f32 v102, v112, s34, v16
	v_fma_f32 v103, v113, s34, v16
	v_add_f32_e32 v100, v108, v100
	v_add_f32_e32 v101, v109, v101
	v_exp_f32_e32 v112, v102
	v_exp_f32_e32 v113, v103
	v_add_f32_e32 v100, v110, v100
	v_add_f32_e32 v101, v111, v101
	v_cvt_pk_bf16_f32 v102, v98, v99
	v_add_u32_e32 v99, 0, v243
	v_add_f32_e32 v100, v112, v100
	v_add_f32_e32 v101, v113, v101
	v_cvt_pk_bf16_f32 v106, v106, v107
	v_cvt_pk_bf16_f32 v107, v108, v109
	v_cvt_pk_bf16_f32 v108, v110, v111
	v_cvt_pk_bf16_f32 v109, v112, v113
	ds_read_b128 v[110:113], v99 offset:28672
	v_add_u32_e32 v98, 0, v247
	v_cvt_pk_bf16_f32 v103, v216, v217
	v_cvt_pk_bf16_f32 v105, v232, v233
	ds_read_b128 v[214:217], v98 offset:28672
	v_add_f32_e32 v100, v100, v101
	s_waitcnt lgkmcnt(1)
	v_mfma_f32_32x32x16_bf16 v[114:129], v[110:113], v[102:105], v[114:129]
	v_max3_f32 v101, v146, s86, v147
	v_max3_f32 v101, v101, v148, v149
	v_max3_f32 v101, v101, v150, v151
	v_max3_f32 v101, v101, v152, v153
	v_max3_f32 v101, v101, v154, v155
	v_max3_f32 v101, v101, v156, v157
	v_max3_f32 v101, v101, v158, v159
	s_waitcnt lgkmcnt(0)
	v_mfma_f32_32x32x16_bf16 v[114:129], v[214:217], v[106:109], v[114:129]
	ds_read_b128 v[110:113], v99 offset:30720
	ds_read_b128 v[214:217], v98 offset:30720
	v_max3_f32 v101, v101, v160, v161
	v_fmamk_f32 v101, v101, 0x3e38aa3b, v241
	v_add_f32_e32 v100, v249, v100
	s_waitcnt lgkmcnt(1)
	v_mfma_f32_32x32x16_bf16 v[130:145], v[110:113], v[102:105], v[130:145]
	v_mov_b32_e32 v102, v101
	s_nop 1
	v_permlane32_swap_b32_e32 v101, v102
	v_max_f32_e32 v102, v102, v102
	v_max_f32_e32 v101, v101, v101
	s_waitcnt lgkmcnt(0)
	v_mfma_f32_32x32x16_bf16 v[130:145], v[214:217], v[106:109], v[130:145]
	v_max_f32_e32 v101, v101, v102
	v_cmp_gt_f32_e32 vcc, v101, v253
	s_cbranch_vccz .LBB0_658
	v_max_f32_e32 v16, v101, v101
	v_max_f32_e32 v17, v17, v16
	v_sub_f32_e32 v16, v253, v17
	v_exp_f32_e32 v16, v16
	v_mov_b32_e32 v253, v17
	v_mul_f32_e32 v100, v16, v100
	v_pk_mul_f32 v[128:129], v[128:129], v[16:17] op_sel_hi:[1,0]
	v_pk_mul_f32 v[126:127], v[126:127], v[16:17] op_sel_hi:[1,0]
	v_pk_mul_f32 v[124:125], v[124:125], v[16:17] op_sel_hi:[1,0]
	v_pk_mul_f32 v[122:123], v[122:123], v[16:17] op_sel_hi:[1,0]
	v_pk_mul_f32 v[120:121], v[120:121], v[16:17] op_sel_hi:[1,0]
	v_pk_mul_f32 v[118:119], v[118:119], v[16:17] op_sel_hi:[1,0]
	v_pk_mul_f32 v[116:117], v[116:117], v[16:17] op_sel_hi:[1,0]
	v_pk_mul_f32 v[114:115], v[114:115], v[16:17] op_sel_hi:[1,0]
	v_pk_mul_f32 v[144:145], v[144:145], v[16:17] op_sel_hi:[1,0]
	v_pk_mul_f32 v[142:143], v[142:143], v[16:17] op_sel_hi:[1,0]
	v_pk_mul_f32 v[140:141], v[140:141], v[16:17] op_sel_hi:[1,0]
	v_pk_mul_f32 v[138:139], v[138:139], v[16:17] op_sel_hi:[1,0]
	v_pk_mul_f32 v[136:137], v[136:137], v[16:17] op_sel_hi:[1,0]
	v_pk_mul_f32 v[134:135], v[134:135], v[16:17] op_sel_hi:[1,0]
	v_pk_mul_f32 v[132:133], v[132:133], v[16:17] op_sel_hi:[1,0]
	v_pk_mul_f32 v[130:131], v[130:131], v[16:17] op_sel_hi:[1,0]
	v_max_f32_e32 v16, 0xefa18f08, v17
	v_sub_f32_e32 v16, v241, v16
.LBB0_658:
	v_mov_b32_e32 v17, v16
	v_fma_f32 v102, v146, s34, v16
	v_fma_f32 v103, v147, s34, v17
	v_fma_f32 v106, v148, s34, v16
	v_fma_f32 v107, v149, s34, v17
	v_exp_f32_e32 v102, v102
	v_exp_f32_e32 v103, v103
	v_exp_f32_e32 v106, v106
	v_exp_f32_e32 v107, v107
	v_fma_f32 v108, v150, s34, v16
	v_fma_f32 v109, v151, s34, v17
	v_fma_f32 v110, v152, s34, v16
	v_fma_f32 v111, v153, s34, v17
	v_exp_f32_e32 v108, v108
	v_exp_f32_e32 v109, v109
	v_exp_f32_e32 v110, v110
	v_exp_f32_e32 v111, v111
	v_fma_f32 v112, v154, s34, v16
	v_fma_f32 v113, v155, s34, v17
	v_pk_add_f32 v[104:105], v[102:103], 0 op_sel_hi:[1,0]
	v_exp_f32_e32 v112, v112
	v_exp_f32_e32 v113, v113
	v_fma_f32 v146, v156, s34, v16
	v_fma_f32 v147, v157, s34, v17
	v_add_f32_e32 v104, v106, v104
	v_add_f32_e32 v105, v107, v105
	v_exp_f32_e32 v146, v146
	v_exp_f32_e32 v147, v147
	v_fma_f32 v148, v158, s34, v16
	v_fma_f32 v149, v159, s34, v17
	v_add_f32_e32 v104, v108, v104
	v_add_f32_e32 v105, v109, v105
	v_exp_f32_e32 v148, v148
	v_exp_f32_e32 v149, v149
	v_fmac_f32_e32 v16, s34, v160
	v_fmac_f32_e32 v17, s34, v161
	v_add_f32_e32 v104, v110, v104
	v_add_f32_e32 v105, v111, v105
	v_exp_f32_e32 v150, v16
	v_exp_f32_e32 v151, v17
	v_add_f32_e32 v104, v112, v104
	v_add_f32_e32 v105, v113, v105
	v_cvt_pk_bf16_f32 v101, v106, v107
	v_add_f32_e32 v104, v146, v104
	v_add_f32_e32 v105, v147, v105
	v_cvt_pk_bf16_f32 v106, v148, v149
	v_add_f32_e32 v104, v148, v104
	v_add_f32_e32 v105, v149, v105
	v_cvt_pk_bf16_f32 v107, v150, v151
	v_add_f32_e32 v16, v150, v104
	v_add_f32_e32 v17, v151, v105
	v_cvt_pk_bf16_f32 v105, v146, v147
	v_add_f32_e32 v16, v16, v17
	v_add_f32_e32 v16, v100, v16
	v_cvt_pk_bf16_f32 v100, v102, v103
	v_cvt_pk_bf16_f32 v102, v108, v109
	v_cvt_pk_bf16_f32 v103, v110, v111
	ds_read_b128 v[108:111], v99 offset:24576
	ds_read_b128 v[146:149], v98 offset:24576
	s_waitcnt lgkmcnt(1)
	v_mfma_f32_32x32x16_bf16 v[114:129], v[108:111], v[100:103], v[114:129]
	v_cvt_pk_bf16_f32 v104, v112, v113
	s_mov_b64 s[16:17], 0
	s_waitcnt lgkmcnt(0)
	v_mfma_f32_32x32x16_bf16 v[114:129], v[146:149], v[104:107], v[114:129]
	ds_read_b128 v[108:111], v99 offset:26624
	ds_read_b128 v[146:149], v98 offset:26624
	s_waitcnt lgkmcnt(1)
	v_mfma_f32_32x32x16_bf16 v[130:145], v[108:111], v[100:103], v[130:145]
	s_waitcnt lgkmcnt(0)
	v_mfma_f32_32x32x16_bf16 v[130:145], v[146:149], v[104:107], v[130:145]

; #define LAS __attribute__((address_space(3)))
; #define MFMA32(a, b, c) __builtin_amdgcn_mfma_f32_32x32x16_bf16((a), (b), (c), 0, 0, 0)
;     __device__ __forceinline__ void begin(int k0) { set_base((float)(tq - k0)); }
;     __device__ __forceinline__ void begin(int k0) { set_base((float)(tq - k0)); }
;     __device__ __forceinline__ void begin(int k0) { set_base((float)(tq - k0)); }
;     __device__ __forceinline__ void begin(int k0) { set_base((float)(tq - 31 - 16 * k0) * (1.f / 16.f)); }
;     __device__ __forceinline__ void begin(int k0) { set_base((float)(iq - k0)); }
; #define CP_LOAD(S, st_) do { const size_t ko = ksoff + (size_t)(64 * (st_)) * NINP; const size_t vo = (size_t)(2 * (st_)) * 4096; \
;         kr0[S] = *(const GAS v4u*)(kcol0 + ko); if (NMAP == 2) kr1[S] = *(const GAS v4u*)(kcol1 + ko); \
;         vr0[S] = *(const GAS v4u*)(vsrc + vo); if (NDT == 4) vr1[S] = *(const GAS v4u*)(vsrc + vo + 4096); } while (0)
; #define CP_PARK(S, buf) do { *(LAS v4u*)((buf) + kdst) = kr0[S]; if (NMAP == 2) *(LAS v4u*)((buf) + 8192 + kdst) = kr1[S]; \
;         *(LAS v4u*)((buf) + vdst) = vr0[S]; if (NDT == 4) *(LAS v4u*)((buf) + vdst + Gm::VS) = vr1[S]; } while (0)
; template <int NDT, class F>
; __device__ __forceinline__ void coop_step(const bf16x8 (&qf)[4], const LAS unsigned char* buf, int fk, int fv, int vsub  , F& f, int st, int t0_mine, int hh, f32x16 (&o)[NDT], float& m, float& l) {
;     ...
;     } else {
;         f32x16 sB;
; #pragma unroll
;         for (int ks = 0; ks < 4; ++ks) { const bf16x8 kf = *(const LAS bf16x8*)(buf + (fk ^ (ks << 5))); sB = MFMA32(kf, qf[ks], ks == 0 ? f.c0() : sB); }
;         if (st > 0) f.fetch2(st - 1);
;         f.begin(k0); softmax_body<NDT>(sB, f, k0, hh, o, m, l, pf0, pf1, 1);
; #pragma unroll
;         for (int dt = 0; dt < NDT; ++dt) { const bf16x8 vf0 = *(const LAS bf16x8*)(buf + dt * 2048 + fv), vf1 = *(const LAS bf16x8*)(buf + dt * 2048 + (fv ^ 32));
;             o[dt] = MFMA32(vf0, pf0, o[dt]); o[dt] = MFMA32(vf1, pf1, o[dt]); }
;     }
; template <int NDT, int NMAP, class F> ...
;     ...
;         if (st - 1 >= 0) CP_PARK(1, b1);
;         CP_BAR();
;         if (st - 1 < 0) break;
;         if (st - 3 >= 0) CP_LOAD(1, st - 3);
;         __builtin_amdgcn_sched_barrier(0);
;         CP_COMPUTE(st - 1, b1);
;         if (st - 2 >= 0) CP_PARK(0, b0);
.LBB0_664:
	v_max_f32_e32 v2, v248, v248
	v_max_f32_e32 v2, 0xefa18f08, v2
	v_sub_f32_e32 v2, v241, v2
	v_fma_f32 v66, v66, s34, v2
	v_fma_f32 v67, v67, s34, v2
	v_fma_f32 v16, v16, s34, v2
	v_fma_f32 v17, v17, s34, v2
	v_exp_f32_e32 v66, v66
	v_exp_f32_e32 v67, v67
	v_exp_f32_e32 v70, v16
	v_exp_f32_e32 v71, v17
	v_fma_f32 v14, v14, s34, v2
	v_fma_f32 v15, v15, s34, v2
	v_fma_f32 v12, v12, s34, v2
	v_fma_f32 v13, v13, s34, v2
	v_exp_f32_e32 v14, v14
	v_exp_f32_e32 v15, v15
	v_exp_f32_e32 v12, v12
	v_exp_f32_e32 v13, v13
	v_fma_f32 v10, v10, s34, v2
	v_fma_f32 v11, v11, s34, v2
	v_pk_add_f32 v[68:69], v[66:67], 0 op_sel_hi:[1,0]
	v_exp_f32_e32 v10, v10
	v_exp_f32_e32 v11, v11
	v_fma_f32 v8, v8, s34, v2
	v_fma_f32 v9, v9, s34, v2
	v_add_f32_e32 v16, v70, v68
	v_add_f32_e32 v17, v71, v69
	v_exp_f32_e32 v68, v8
	v_exp_f32_e32 v69, v9
	v_fma_f32 v4, v4, s34, v2
	v_fma_f32 v5, v5, s34, v2
	v_add_f32_e32 v16, v14, v16
	v_add_f32_e32 v17, v15, v17
	v_exp_f32_e32 v72, v4
	v_exp_f32_e32 v73, v5
	v_fma_f32 v6, v6, s34, v2
	v_fma_f32 v7, v7, s34, v2
	v_add_f32_e32 v16, v12, v16
	v_add_f32_e32 v17, v13, v17
	v_exp_f32_e32 v74, v6
	v_exp_f32_e32 v75, v7
	v_add_f32_e32 v16, v10, v16
	v_add_f32_e32 v17, v11, v17
	v_cvt_pk_bf16_f32 v6, v14, v15
	v_add_f32_e32 v8, v68, v16
	v_add_f32_e32 v9, v69, v17
	v_cvt_pk_bf16_f32 v7, v12, v13
	v_add_f32_e32 v4, v72, v8
	v_add_f32_e32 v5, v73, v9
	v_add_u32_e32 v17, 0, v247
	v_add_f32_e32 v4, v74, v4
	v_add_f32_e32 v5, v75, v5
	v_cvt_pk_bf16_f32 v9, v68, v69
	v_add_f32_e32 v2, v4, v5
	v_add_f32_e32 v16, v229, v2
	v_add_u32_e32 v2, 0, v243
	ds_read_b128 v[12:15], v2 offset:24576
	v_cvt_pk_bf16_f32 v4, v66, v67
	v_cvt_pk_bf16_f32 v5, v70, v71
	ds_read_b128 v[66:69], v17 offset:24576
	v_cvt_pk_bf16_f32 v8, v10, v11
	s_waitcnt lgkmcnt(1)
	v_mfma_f32_32x32x16_bf16 v[34:49], v[12:15], v[4:7], v[34:49]
	v_cvt_pk_bf16_f32 v10, v72, v73
	v_cvt_pk_bf16_f32 v11, v74, v75
	s_waitcnt vmcnt(5)
	v_mov_b32_e32 v197, v53
	v_mov_b32_e32 v196, v52
	v_mov_b32_e32 v195, v51
	v_mov_b32_e32 v194, v50
	s_waitcnt vmcnt(2)
	v_mov_b32_e32 v201, v97
	s_waitcnt lgkmcnt(0)
	v_mfma_f32_32x32x16_bf16 v[34:49], v[66:69], v[8:11], v[34:49]
	ds_read_b128 v[12:15], v2 offset:26624
	ds_read_b128 v[66:69], v17 offset:26624
	v_mov_b32_e32 v200, v96
	v_mov_b32_e32 v199, v95
	v_mov_b32_e32 v198, v94
	v_mov_b32_e32 v205, v93
	v_mov_b32_e32 v204, v92
	v_mov_b32_e32 v203, v91
	s_waitcnt lgkmcnt(1)
	v_mfma_f32_32x32x16_bf16 v[18:33], v[12:15], v[4:7], v[18:33]
	s_nop 1
	v_mov_b64_e32 v[128:129], v[48:49]
	s_waitcnt vmcnt(0)
	v_mov_b32_e32 v7, v65
	v_mov_b32_e32 v6, v64
	v_mov_b32_e32 v5, v63
	v_mov_b32_e32 v4, v62
	v_mov_b32_e32 v15, v61
	v_mov_b32_e32 v14, v60
	s_waitcnt lgkmcnt(0)
	v_mfma_f32_32x32x16_bf16 v[18:33], v[66:69], v[8:11], v[18:33]
	v_mov_b32_e32 v13, v59
	v_mov_b32_e32 v12, v58
	v_mov_b32_e32 v11, v57
	v_mov_b32_e32 v10, v56
	v_mov_b32_e32 v9, v55
	v_mov_b32_e32 v8, v54
	v_mov_b32_e32 v202, v90
	s_nop 4
	v_mov_b64_e32 v[144:145], v[32:33]
	v_mov_b32_e32 v209, v89
	v_mov_b32_e32 v208, v88
	v_mov_b32_e32 v207, v87
	v_mov_b32_e32 v206, v86
	v_mov_b32_e32 v213, v85
	v_mov_b32_e32 v212, v84
	v_mov_b32_e32 v211, v83
	v_mov_b32_e32 v210, v82
	v_mov_b32_e32 v253, v248
	v_mov_b64_e32 v[126:127], v[46:47]
	v_mov_b64_e32 v[124:125], v[44:45]
	v_mov_b64_e32 v[122:123], v[42:43]
	v_mov_b64_e32 v[120:121], v[40:41]
	v_mov_b64_e32 v[118:119], v[38:39]
	v_mov_b64_e32 v[116:117], v[36:37]
	v_mov_b64_e32 v[114:115], v[34:35]
	v_mov_b64_e32 v[142:143], v[30:31]
	v_mov_b64_e32 v[140:141], v[28:29]
	v_mov_b64_e32 v[138:139], v[26:27]
	v_mov_b64_e32 v[136:137], v[24:25]
	v_mov_b64_e32 v[134:135], v[22:23]
	v_mov_b64_e32 v[132:133], v[20:21]
	v_mov_b64_e32 v[130:131], v[18:19]

; __device__ __forceinline__ void nsa_quad_item(const bf16* PROJ, const bf16* KC, const unsigned char* VCB, const unsigned char* VTB, const unsigned long long* SEL, bf16* O, LAS unsigned char* lds, int bg, int jp, int wave) {
;     ...
;         l = half_sum(l); const float g1 = sigmoidf_(bf2f(PROJ[NSA_ROW() * NINP + C_GATE + hd * 3 + 1])); const float w = l > 0.f ? g1 / l : 0.f;
; #pragma unroll
;         for (int dt = 0; dt < 2; ++dt)
; #pragma unroll
;             for (int r = 0; r < 16; r += 2) res[dt * 8 + (r >> 1)] = cvtpk(o[dt][r] * w, o[dt][r + 1] * w);
;     }
;     {
;         WinBias f; f.setup(slope2, hh); f.tq = tq; f.t0 = t0;
;         QuadStream st; st.setup(PROJ + (size_t)b * SEQ * NINP + C_WINK + g * 64, (size_t)NINP * 2, VTB + vtb_off(b, 9 + g, 0), lane, wi);
;         zero_ot<2>(o); float m = NEG_BIG, l = 0.f;
;         RangeIt it; it.kt = qt; it.kt0 = t0 >= 512 ? (t0 - 512) >> 5 : 0; RangePre<WinBias> pre{f};
;         const int n_own = win_tiles(qt), n_oth = win_tiles(qto);
;         quad_stream(qf, st, ring, f, it, it, pre, n_own, n_own > n_oth ? n_own : n_oth, hh, o, m, l);
;         l = half_sum(l); const float g2 = sigmoidf_(bf2f(PROJ[NSA_ROW() * NINP + C_GATE + hd * 3 + 2])); const float w = l > 0.f ? g2 / l : 0.f;
; #pragma unroll
;         for (int dt = 0; dt < 2; ++dt)
; #pragma unroll
;             for (int r = 0; r < 16; r += 2) { const unsigned pr = res[dt * 8 + (r >> 1)]; res[dt * 8 + (r >> 1)] = cvtpk(fmaf(o[dt][r], w, lo16(pr)), fmaf(o[dt][r + 1], w, hi16(pr))); }
;     }
;     {
;         CmpBias f; f.setup(16.f * slope2, hh); f.tq = tq; f.ncv = tq >= 31 ? ((tq - 31) >> 4) + 1 : 0; f.ncv = f.ncv > 255 ? 255 : f.ncv;
;         f.ncv_min = t0 >= 31 ? ((t0 - 31) >> 4) + 1 : 0; f.ncv_min = f.ncv_min > 255 ? 255 : f.ncv_min;
;         QuadStream st; st.setup(KC + (size_t)((0 * BATCH + b) * 2 + g) * 256 * 64, 128, VCB + (size_t)(b * 2 + g) * 8 * 4096, lane, wi);
;         zero_ot<2>(o); float m = NEG_BIG, l = 0.f;
;         const int n_own = cmp_tiles(qt), n_oth = cmp_tiles(qto);
;         RangeIt it; it.kt = n_own - 1; it.kt0 = 0; RangePre<CmpBias> pre{f};
;         quad_stream(qf, st, ring, f, it, it, pre, n_own, n_own > n_oth ? n_own : n_oth, hh, o, m, l);
;         l = half_sum(l); const float g0 = sigmoidf_(bf2f(PROJ[NSA_ROW() * NINP + C_GATE + hd * 3 + 0])); const float w = l > 0.f ? g0 / l : 0.f;
; #pragma unroll
.LBB0_672:
	v_mov_b32_e32 v158, v156
	v_mov_b32_e32 v2, v239
	v_mov_b64_e32 v[100:101], s[14:15]
	v_and_or_b32 v2, v2, 31, s6
	v_mad_u64_u32 v[100:101], s[4:5], v2, s83, v[100:101]
	v_mad_i32_i24 v101, s7, v238, v101
	s_mov_b32 s17, s19
	v_lshl_add_u64 v[100:101], v[100:101], 0, s[16:17]
	v_add_co_u32_e32 v100, vcc, s35, v100
	v_add_f32_e32 v2, v149, v164
	s_nop 0
	v_addc_co_u32_e32 v101, vcc, 0, v101, vcc
	flat_load_ushort v103, v[100:101] offset:3600
	s_waitcnt vmcnt(0) lgkmcnt(0)
	v_lshlrev_b32_e32 v100, 16, v165
	v_lshlrev_b32_e32 v101, 16, v163
	v_mul_f32_e32 v100, 0xbfb8aa3b, v100
	v_mul_f32_e32 v101, 0xbfb8aa3b, v101
	v_exp_f32_e32 v102, v100
	v_exp_f32_e32 v104, v101
	v_permlane32_swap_b32_e32 v156, v158
	v_add_f32_e32 v102, 1.0, v102
	v_rcp_f32_e32 v102, v102
	v_add_f32_e32 v104, 1.0, v104
	v_rcp_f32_e32 v104, v104
	v_add_f32_e32 v100, v156, v158
	v_add_f32_e32 v101, v157, v159
	v_div_scale_f32 v105, s[4:5], v2, v2, v102
	v_div_scale_f32 v107, s[4:5], v101, v101, v104
	v_rcp_f32_e32 v108, v105
	v_rcp_f32_e32 v109, v107
	v_div_scale_f32 v106, vcc, v102, v2, v102
	v_fma_f32 v111, -v105, v108, 1.0
	v_fma_f32 v112, -v107, v109, 1.0
	v_fmac_f32_e32 v108, v111, v108
	v_div_scale_f32 v110, s[38:39], v104, v101, v104
	v_fmac_f32_e32 v109, v112, v109
	v_mul_f32_e32 v111, v106, v108
	v_mul_f32_e32 v112, v110, v109
	v_fma_f32 v113, -v105, v111, v106
	v_fma_f32 v114, -v107, v112, v110
	v_fmac_f32_e32 v111, v113, v108
	v_fmac_f32_e32 v112, v114, v109
	v_fma_f32 v105, -v105, v111, v106
	v_fma_f32 v106, -v107, v112, v110
	v_div_fmas_f32 v105, v105, v108, v111
	s_mov_b64 vcc, s[38:39]
	v_div_fixup_f32 v102, v105, v2, v102
	v_div_fmas_f32 v105, v106, v109, v112
	v_cmp_lt_f32_e32 vcc, 0, v2
	s_mov_b32 s45, s19
	s_mov_b64 s[14:15], 0
	v_cndmask_b32_e32 v2, 0, v102, vcc
	v_div_fixup_f32 v102, v105, v101, v104
	v_cmp_lt_f32_e32 vcc, 0, v101
	s_nop 1
	v_cndmask_b32_e32 v102, 0, v102, vcc
	v_mul_f32_e32 v34, v34, v102
	v_mul_f32_e32 v35, v35, v102
	v_mul_f32_e32 v32, v32, v102
	v_mul_f32_e32 v33, v33, v102
	v_mul_f32_e32 v28, v28, v102
	v_mul_f32_e32 v29, v29, v102
	v_mul_f32_e32 v26, v26, v102
	v_mul_f32_e32 v27, v27, v102
	v_cvt_pk_bf16_f32 v34, v34, v35
	v_cvt_pk_bf16_f32 v32, v32, v33
	v_cvt_pk_bf16_f32 v33, v28, v29
	v_cvt_pk_bf16_f32 v35, v26, v27
	v_lshlrev_b32_e32 v26, 16, v34
	v_and_b32_e32 v27, 0xffff0000, v34
	v_lshlrev_b32_e32 v28, 16, v32
	v_and_b32_e32 v29, 0xffff0000, v32
	v_lshlrev_b32_e32 v32, 16, v33
	v_and_b32_e32 v33, 0xffff0000, v33
	v_fmac_f32_e32 v26, v66, v2
	v_fmac_f32_e32 v27, v67, v2
	v_fmac_f32_e32 v32, v60, v2
	v_fmac_f32_e32 v33, v61, v2
	v_cvt_pk_bf16_f32 v60, v26, v27
	v_lshlrev_b32_e32 v26, 16, v103
	v_mul_f32_e32 v26, 0xbfb8aa3b, v26
	v_exp_f32_e32 v26, v26
	v_fmac_f32_e32 v28, v64, v2
	v_fmac_f32_e32 v29, v65, v2
	v_mul_f32_e32 v6, v6, v102
	v_mul_f32_e32 v7, v7, v102
	v_cvt_pk_bf16_f32 v61, v28, v29
	v_add_f32_e32 v26, 1.0, v26
	v_rcp_f32_e32 v28, v26
	v_mul_f32_e32 v8, v8, v102
	v_mul_f32_e32 v9, v9, v102
	v_cvt_pk_bf16_f32 v7, v6, v7
	v_cvt_pk_bf16_f32 v9, v8, v9
	v_lshlrev_b32_e32 v6, 16, v7
	v_and_b32_e32 v7, 0xffff0000, v7
	v_lshlrev_b32_e32 v8, 16, v9
	v_and_b32_e32 v9, 0xffff0000, v9
	v_fmac_f32_e32 v6, v38, v2
	v_fmac_f32_e32 v7, v39, v2
	v_fmac_f32_e32 v8, v40, v2
	v_fmac_f32_e32 v9, v41, v2
	v_cvt_pk_bf16_f32 v7, v6, v7
	v_div_scale_f32 v6, s[4:5], v100, v100, v28
	v_cvt_pk_bf16_f32 v9, v8, v9
	v_rcp_f32_e32 v8, v6
	v_mul_f32_e32 v30, v30, v102
	v_mul_f32_e32 v31, v31, v102
	v_mul_f32_e32 v24, v24, v102
	v_mul_f32_e32 v25, v25, v102
	v_mul_f32_e32 v22, v22, v102
	v_mul_f32_e32 v23, v23, v102
	v_mul_f32_e32 v20, v20, v102
	v_mul_f32_e32 v21, v21, v102
	v_mul_f32_e32 v18, v18, v102
	v_mul_f32_e32 v19, v19, v102
	v_mul_f32_e32 v16, v16, v102
	v_mul_f32_e32 v17, v17, v102
	v_mul_f32_e32 v14, v14, v102
	v_mul_f32_e32 v15, v15, v102
	v_mul_f32_e32 v12, v12, v102
	v_mul_f32_e32 v13, v13, v102
	v_mul_f32_e32 v10, v10, v102
	v_mul_f32_e32 v11, v11, v102
	v_mul_f32_e32 v4, v4, v102
	v_mul_f32_e32 v5, v5, v102
	v_cvt_pk_bf16_f32 v31, v30, v31
	v_cvt_pk_bf16_f32 v25, v24, v25
	v_cvt_pk_bf16_f32 v23, v22, v23
	v_cvt_pk_bf16_f32 v21, v20, v21
	v_cvt_pk_bf16_f32 v19, v18, v19
	v_cvt_pk_bf16_f32 v17, v16, v17
	v_cvt_pk_bf16_f32 v15, v14, v15
	v_cvt_pk_bf16_f32 v13, v12, v13
	v_cvt_pk_bf16_f32 v11, v10, v11
	v_cvt_pk_bf16_f32 v5, v4, v5
	v_lshlrev_b32_e32 v30, 16, v31
	v_and_b32_e32 v31, 0xffff0000, v31
	v_lshlrev_b32_e32 v34, 16, v35
	v_and_b32_e32 v35, 0xffff0000, v35
	v_lshlrev_b32_e32 v24, 16, v25
	v_and_b32_e32 v25, 0xffff0000, v25
	v_lshlrev_b32_e32 v22, 16, v23
	v_and_b32_e32 v23, 0xffff0000, v23
	v_lshlrev_b32_e32 v20, 16, v21
	v_and_b32_e32 v21, 0xffff0000, v21
	v_lshlrev_b32_e32 v18, 16, v19
	v_and_b32_e32 v19, 0xffff0000, v19
	v_lshlrev_b32_e32 v16, 16, v17
	v_and_b32_e32 v17, 0xffff0000, v17
	v_lshlrev_b32_e32 v14, 16, v15
	v_and_b32_e32 v15, 0xffff0000, v15
	v_lshlrev_b32_e32 v12, 16, v13
	v_and_b32_e32 v13, 0xffff0000, v13
; __device__ __forceinline__ float half_sum(float v) { unsigned a, b; half_swap(__builtin_bit_cast(unsigned, v), a, b); return __builtin_bit_cast(float, a) + __builtin_bit_cast(float, b); }
; __device__ __forceinline__ float sigmoidf_(float x) { return __builtin_amdgcn_rcpf(1.f + __builtin_amdgcn_exp2f(-1.4426950408889634f * x)); }
; __device__ __forceinline__ unsigned cvtpk(float lo, float hi) { f32x2_t v = {lo, hi}; bf16x2_t b = __builtin_convertvector(v, bf16x2_t); return __builtin_bit_cast(unsigned, b); }
; __device__ __forceinline__ int fresh_lane() { int l = (int)__builtin_amdgcn_mbcnt_hi(~0u, __builtin_amdgcn_mbcnt_lo(~0u, 0u)); asm volatile("" : "+v"(l)); return l; }
; #define NSA_ROW() ((size_t)b * SEQ + t0 + (fresh_lane() & 31))
; #define NSA_ROW() ((size_t)b * SEQ + t0 + (fresh_lane() & 31))
; template <int NDT>
; __device__ __forceinline__ void store_ot(bf16* orow  , const f32x16 (&o)[NDT], float scale, int hh) {
; #pragma unroll
;     for (int dt = 0; dt < NDT; ++dt)
; #pragma unroll
;         for (int g = 0; g < 4; ++g) { v2u w; w.x = cvtpk(o[dt][4 * g] * scale, o[dt][4 * g + 1] * scale); w.y = cvtpk(o[dt][4 * g + 2] * scale, o[dt][4 * g + 3] * scale);
;             *(v2u*)(orow + 32 * dt + 8 * g + 4 * hh) = w; }
; __device__ __forceinline__ void nsa_quad_item(const bf16* PROJ, const bf16* KC, const unsigned char* VCB, const unsigned char* VTB, const unsigned long long* SEL, bf16* O, LAS unsigned char* lds, int bg, int jp, int wave) {
;     ...
;         l = half_sum(l); const float g0 = sigmoidf_(bf2f(PROJ[NSA_ROW() * NINP + C_GATE + hd * 3 + 0])); const float w = l > 0.f ? g0 / l : 0.f;
; #pragma unroll
;         for (int dt = 0; dt < 2; ++dt)
; #pragma unroll
;             for (int r = 0; r < 16; r += 2) { const unsigned pr = res[dt * 8 + (r >> 1)]; o[dt][r] = fmaf(o[dt][r], w, lo16(pr)); o[dt][r + 1] = fmaf(o[dt][r + 1], w, hi16(pr)); }
;     }
;     store_ot<2>(O + NSA_ROW() * DM + O_NSA + hd * 64, o, 1.f, fresh_lane() >> 5);
;     ...
;     asm volatile("s_waitcnt vmcnt(0) lgkmcnt(0)" ::: "memory"); __builtin_amdgcn_s_barrier(); asm volatile("" ::: "memory");
	v_lshlrev_b32_e32 v10, 16, v11
	v_and_b32_e32 v11, 0xffff0000, v11
	v_lshlrev_b32_e32 v4, 16, v5
	v_and_b32_e32 v5, 0xffff0000, v5
	v_fmac_f32_e32 v30, v62, v2
	v_fmac_f32_e32 v31, v63, v2
	v_fma_f32 v26, v58, v2, v34
	v_fma_f32 v27, v59, v2, v35
	v_fmac_f32_e32 v24, v56, v2
	v_fmac_f32_e32 v25, v57, v2
	v_fmac_f32_e32 v22, v54, v2
	v_fmac_f32_e32 v23, v55, v2
	v_fmac_f32_e32 v20, v52, v2
	v_fmac_f32_e32 v21, v53, v2
	v_fmac_f32_e32 v18, v50, v2
	v_fmac_f32_e32 v19, v51, v2
	v_fmac_f32_e32 v16, v48, v2
	v_fmac_f32_e32 v17, v49, v2
	v_fmac_f32_e32 v14, v46, v2
	v_fmac_f32_e32 v15, v47, v2
	v_fmac_f32_e32 v12, v44, v2
	v_fmac_f32_e32 v13, v45, v2
	v_fmac_f32_e32 v10, v42, v2
	v_fmac_f32_e32 v11, v43, v2
	v_fmac_f32_e32 v4, v36, v2
	v_fmac_f32_e32 v5, v37, v2
	v_fma_f32 v2, -v6, v8, 1.0
	v_fmac_f32_e32 v8, v2, v8
	v_div_scale_f32 v2, vcc, v28, v100, v28
	v_cvt_pk_bf16_f32 v5, v4, v5
	v_mul_f32_e32 v4, v2, v8
	v_cvt_pk_bf16_f32 v11, v10, v11
	v_fma_f32 v10, -v6, v4, v2
	v_fmac_f32_e32 v4, v10, v8
	v_fma_f32 v2, -v6, v4, v2
	v_div_fmas_f32 v2, v2, v8, v4
	v_cvt_pk_bf16_f32 v31, v30, v31
	v_cvt_pk_bf16_f32 v29, v32, v33
	v_cvt_pk_bf16_f32 v27, v26, v27
	v_cvt_pk_bf16_f32 v25, v24, v25
	v_cvt_pk_bf16_f32 v23, v22, v23
	v_cvt_pk_bf16_f32 v21, v20, v21
	v_cvt_pk_bf16_f32 v19, v18, v19
	v_cvt_pk_bf16_f32 v17, v16, v17
	v_cvt_pk_bf16_f32 v15, v14, v15
	v_cvt_pk_bf16_f32 v13, v12, v13
	v_div_fixup_f32 v2, v2, v100, v28
	v_cmp_lt_f32_e32 vcc, 0, v100
	v_lshlrev_b32_e32 v4, 16, v5
	v_and_b32_e32 v5, 0xffff0000, v5
	v_cndmask_b32_e32 v2, 0, v2, vcc
	v_lshlrev_b32_e32 v6, 16, v7
	v_and_b32_e32 v7, 0xffff0000, v7
	v_lshlrev_b32_e32 v8, 16, v9
	v_and_b32_e32 v9, 0xffff0000, v9
	v_lshlrev_b32_e32 v10, 16, v11
	v_and_b32_e32 v11, 0xffff0000, v11
	v_lshlrev_b32_e32 v12, 16, v13
	v_and_b32_e32 v13, 0xffff0000, v13
	v_lshlrev_b32_e32 v14, 16, v15
	v_and_b32_e32 v15, 0xffff0000, v15
	v_lshlrev_b32_e32 v16, 16, v17
	v_and_b32_e32 v17, 0xffff0000, v17
	v_lshlrev_b32_e32 v18, 16, v19
	v_and_b32_e32 v19, 0xffff0000, v19
	v_lshlrev_b32_e32 v20, 16, v21
	v_and_b32_e32 v21, 0xffff0000, v21
	v_lshlrev_b32_e32 v22, 16, v23
	v_and_b32_e32 v23, 0xffff0000, v23
	v_lshlrev_b32_e32 v24, 16, v25
	v_and_b32_e32 v25, 0xffff0000, v25
	v_lshlrev_b32_e32 v26, 16, v27
	v_and_b32_e32 v27, 0xffff0000, v27
	v_lshlrev_b32_e32 v28, 16, v29
	v_and_b32_e32 v29, 0xffff0000, v29
	v_lshlrev_b32_e32 v30, 16, v31
	v_and_b32_e32 v31, 0xffff0000, v31
	v_lshlrev_b32_e32 v32, 16, v61
	v_and_b32_e32 v33, 0xffff0000, v61
	v_lshlrev_b32_e32 v34, 16, v60
	v_and_b32_e32 v35, 0xffff0000, v60
	v_fmac_f32_e32 v4, v84, v2
	v_fmac_f32_e32 v5, v85, v2
	v_fmac_f32_e32 v6, v86, v2
	v_fmac_f32_e32 v7, v87, v2
	v_fmac_f32_e32 v8, v88, v2
	v_fmac_f32_e32 v9, v89, v2
	v_fmac_f32_e32 v10, v90, v2
	v_fmac_f32_e32 v11, v91, v2
	v_fmac_f32_e32 v12, v92, v2
	v_fmac_f32_e32 v13, v93, v2
	v_fmac_f32_e32 v14, v94, v2
	v_fmac_f32_e32 v15, v95, v2
	v_fmac_f32_e32 v16, v96, v2
	v_fmac_f32_e32 v17, v97, v2
	v_fmac_f32_e32 v18, v98, v2
	v_fmac_f32_e32 v19, v99, v2
	v_fmac_f32_e32 v20, v68, v2
	v_fmac_f32_e32 v21, v69, v2
	v_fmac_f32_e32 v22, v70, v2
	v_fmac_f32_e32 v23, v71, v2
	v_fmac_f32_e32 v24, v72, v2
	v_fmac_f32_e32 v25, v73, v2
	v_fmac_f32_e32 v26, v74, v2
	v_fmac_f32_e32 v27, v75, v2
	v_fmac_f32_e32 v28, v76, v2
	v_fmac_f32_e32 v29, v77, v2
	v_fmac_f32_e32 v30, v78, v2
	v_fmac_f32_e32 v31, v79, v2
	v_fmac_f32_e32 v32, v80, v2
	v_fmac_f32_e32 v33, v81, v2
	v_fmac_f32_e32 v34, v82, v2
	v_fmac_f32_e32 v35, v83, v2
	v_mov_b32_e32 v2, v239
	v_mov_b32_e32 v37, s7
	v_and_or_b32 v36, v2, 31, s6
	v_mov_b32_e32 v2, v239
	v_lshlrev_b64 v[36:37], 12, v[36:37]
	v_ashrrev_i32_e32 v2, 3, v2
	v_lshl_add_u64 v[36:37], s[26:27], 0, v[36:37]
	v_and_b32_e32 v38, -4, v2
	v_lshl_add_u64 v[36:37], v[36:37], 0, s[44:45]
	v_ashrrev_i32_e32 v39, 31, v38
	v_lshl_add_u64 v[36:37], v[38:39], 1, v[36:37]
	v_cvt_pk_bf16_f32 v4, v4, v5
	v_cvt_pk_bf16_f32 v5, v6, v7
	v_add_co_u32_e32 v6, vcc, s88, v36
	s_mov_b64 s[4:5], 0x2800380
	s_nop 0
	v_addc_co_u32_e32 v7, vcc, 0, v37, vcc
	v_lshl_add_u64 v[38:39], v[36:37], 0, s[4:5]
	flat_store_dwordx2 v[6:7], v[4:5] offset:896
	v_cvt_pk_bf16_f32 v4, v8, v9
	v_cvt_pk_bf16_f32 v5, v10, v11
	flat_store_dwordx2 v[38:39], v[4:5] offset:16
	v_cvt_pk_bf16_f32 v4, v12, v13
	v_cvt_pk_bf16_f32 v5, v14, v15
	flat_store_dwordx2 v[38:39], v[4:5] offset:32
	v_cvt_pk_bf16_f32 v4, v16, v17
	v_cvt_pk_bf16_f32 v5, v18, v19
	flat_store_dwordx2 v[38:39], v[4:5] offset:48
	v_cvt_pk_bf16_f32 v4, v20, v21
	v_cvt_pk_bf16_f32 v5, v22, v23
	flat_store_dwordx2 v[38:39], v[4:5] offset:64
	v_cvt_pk_bf16_f32 v4, v24, v25
	v_cvt_pk_bf16_f32 v5, v26, v27
	flat_store_dwordx2 v[38:39], v[4:5] offset:80
	v_cvt_pk_bf16_f32 v4, v28, v29
	v_cvt_pk_bf16_f32 v5, v30, v31
	flat_store_dwordx2 v[38:39], v[4:5] offset:96
	v_cvt_pk_bf16_f32 v4, v32, v33
	v_cvt_pk_bf16_f32 v5, v34, v35
	flat_store_dwordx2 v[38:39], v[4:5] offset:112
	s_waitcnt vmcnt(0) lgkmcnt(0)
	s_barrier

; __device__ __forceinline__ size_t vtb_off(int b, int hs, int kb) { return ((size_t)(b * NHS + hs) * VTB_KB + kb) * 4096; }
; __device__ __forceinline__ int slc_tiles(unsigned long long um, int t0) { return um == 0ull ? 0 : 2 * __builtin_popcountll(um) - ((t0 & 32) ? 0 : 1); }
;     __device__ __forceinline__ void setup(float g_, int hh_) { g = g_; hh = hh_; asm volatile("" : "+v"(hh_));
; #pragma unroll
;         for (int r = 0; r < 16; ++r) cv[r] = g_ * (1.f / QK_SCL) * (float)(CR(r) + 4 * hh_); }
; __device__ __forceinline__ void nsa_quad_item(const bf16* PROJ, const bf16* KC, const unsigned char* VCB, const unsigned char* VTB, const unsigned long long* SEL, bf16* O, LAS unsigned char* lds, int bg, int jp, int wave) {
;     ...
;         const unsigned long long mask = SEL[(size_t)(b * 2 + g) * SEQ + tq], masko = SEL[(size_t)(b * 2 + g) * SEQ + 32 * qto + q];
;         const unsigned long long um = tile_union(mask), umo = tile_union(masko);
;         const int n_own = slc_tiles(um, t0), n_oth = slc_tiles(umo, 32 * qto);
;         SlcBias f; f.setup(slope2, hh); f.tq = tq;
;         QuadStream st; st.setup(PROJ + (size_t)b * SEQ * NINP + C_SLCK + g * 64, (size_t)NINP * 2, VTB + vtb_off(b, 7 + g, 0), lane, wi);
;         zero_ot<2>(o); float m = NEG_BIG, l = 0.f;
;         SlcIt it; it.um = um; it.pend = -1; it.tmax = tmax; SlcPre pre{f, mask, t0};
;         quad_stream(qf, st, ring, f, it, it, pre, n_own, n_own > n_oth ? n_own : n_oth, hh, o, m, l);
.LBB0_708:
	s_bcnt1_i32_b64 s13, s[16:17]
	s_lshl_b32 s13, s13, 1
	s_sub_i32 s13, s13, s52
	s_and_b64 s[36:37], s[36:37], exec
	s_cselect_b32 s36, 0, s13
	s_bcnt1_i32_b64 s13, s[20:21]
	s_lshl_b32 s13, s13, 1
	s_sub_i32 s13, s13, s51
	s_max_u32 s13, s36, s13
	s_cmp_eq_u64 s[20:21], 0
	s_cselect_b32 s37, s36, s13
	s_cmp_lt_i32 s30, 0
	s_cselect_b32 s18, s18, s30
	s_mul_i32 s20, s18, 0x60000
	s_mul_hi_u32 s13, s18, 0x60000
	s_add_u32 s20, s46, s20
	s_addc_u32 s21, s5, s13
	s_add_i32 s13, s56, 0xa000
	v_lshl_add_u64 v[6:7], s[20:21], 0, v[2:3]
	s_lshl_b64 s[20:21], s[18:19], 12
	s_add_u32 s20, s57, s20
	s_mov_b32 m0, s13
	s_addc_u32 s21, s58, s21
	global_load_lds_dwordx4 v[6:7], off
	s_mov_b32 m0, s63
	v_lshl_add_u64 v[6:7], s[20:21], 0, v[70:71]
	global_load_lds_dwordx4 v[6:7], off
	s_mov_b32 s47, 0
	s_cmp_lg_u32 s37, 0
	v_lshlrev_b32_e32 v158, 2, v102
	s_cbranch_scc0 .LBB0_729
	v_lshlrev_b32_e32 v5, 2, v5
	v_or_b32_e32 v9, 1, v5
	v_or_b32_e32 v6, 3, v5
	v_or_b32_e32 v8, 2, v5
	v_cvt_f32_i32_e32 v7, v6
	v_cvt_f32_i32_e32 v6, v8
	v_cvt_f32_i32_e32 v8, v5
	v_cvt_f32_i32_e32 v9, v9
	v_mov_b32_e32 v149, v148
	v_add_u32_e32 v10, 8, v5
	v_add_u32_e32 v11, 9, v5
	v_add_u32_e32 v12, 10, v5
	v_add_u32_e32 v13, 11, v5
	v_add_u32_e32 v14, 16, v5
	v_add_u32_e32 v15, 17, v5
	v_add_u32_e32 v16, 18, v5
	v_add_u32_e32 v17, 19, v5
	v_add_u32_e32 v18, 24, v5
	v_add_u32_e32 v19, 25, v5
	v_add_u32_e32 v20, 26, v5
	v_add_u32_e32 v21, 27, v5
	v_mul_f32_e32 v38, v148, v6
	v_mul_f32_e32 v39, v149, v7
	v_mul_f32_e32 v36, v152, v8
	v_mul_f32_e32 v37, v153, v9
	v_and_b32_e32 v5, 31, v4
	v_ashrrev_i32_e32 v6, 5, v4
	v_lshrrev_b32_e32 v8, 1, v4
	v_lshrrev_b32_e32 v4, 2, v4
	v_cvt_f32_i32_e32 v11, v11
	v_cvt_f32_i32_e32 v10, v10
	v_cvt_f32_i32_e32 v13, v13
	v_cvt_f32_i32_e32 v12, v12
	v_cvt_f32_i32_e32 v15, v15
	v_cvt_f32_i32_e32 v14, v14
	v_cvt_f32_i32_e32 v17, v17
	v_cvt_f32_i32_e32 v16, v16
	v_cvt_f32_i32_e32 v19, v19
	v_cvt_f32_i32_e32 v21, v21
	v_cvt_f32_i32_e32 v20, v20
	v_cvt_f32_i32_e32 v18, v18
	v_bitop3_b32 v4, v4, v6, 3 bitop3:0x6c
	v_lshlrev_b32_e32 v4, 4, v4
	v_lshlrev_b32_e32 v7, 7, v5
	v_bitop3_b32 v8, v8, v6, 7 bitop3:0x6c
	v_lshl_add_u32 v73, v5, 6, v4
	v_lshl_add_u32 v72, v8, 4, v7
	v_add_u32_e32 v4, 0x1000, v73
	v_mov_b32_e32 v157, 0
	v_mul_f32_e32 v50, v148, v20
	v_mul_f32_e32 v51, v149, v21
	v_mul_f32_e32 v48, v148, v18
	v_mul_f32_e32 v49, v149, v19
	v_mul_f32_e32 v46, v148, v16
	v_mul_f32_e32 v47, v149, v17
	v_mul_f32_e32 v44, v148, v14
	v_mul_f32_e32 v45, v149, v15
	v_mul_f32_e32 v42, v148, v12
	v_mul_f32_e32 v43, v149, v13
	v_mul_f32_e32 v40, v148, v10
	v_mul_f32_e32 v41, v149, v11
	v_xor_b32_e32 v74, 32, v72
	v_xor_b32_e32 v75, 64, v72
	v_xor_b32_e32 v76, 0x60, v72
	v_xor_b32_e32 v77, 32, v4
	s_mov_b32 s38, -1
	v_mov_b32_e32 v78, 0xf149f2ca
	s_mov_b32 s80, 0
	v_mov_b32_e32 v4, 0
	v_mov_b32_e32 v5, v157
	v_mov_b32_e32 v6, v157
	v_mov_b32_e32 v7, v157
	v_mov_b32_e32 v8, v157
	v_mov_b32_e32 v9, v157
	v_mov_b32_e32 v10, v157
	v_mov_b32_e32 v11, v157
	v_mov_b32_e32 v12, v157
	v_mov_b32_e32 v13, v157
	v_mov_b32_e32 v14, v157
	v_mov_b32_e32 v15, v157
	v_mov_b32_e32 v16, v157
	v_mov_b32_e32 v17, v157
	v_mov_b32_e32 v18, v157
	v_mov_b32_e32 v19, v157
	v_mov_b32_e32 v20, v157
	v_mov_b32_e32 v21, v157
	v_mov_b32_e32 v22, v157
	v_mov_b32_e32 v23, v157
	v_mov_b32_e32 v24, v157
	v_mov_b32_e32 v25, v157
	v_mov_b32_e32 v26, v157
	v_mov_b32_e32 v27, v157
	v_mov_b32_e32 v28, v157
	v_mov_b32_e32 v29, v157
	v_mov_b32_e32 v30, v157
	v_mov_b32_e32 v31, v157
	v_mov_b32_e32 v32, v157
	v_mov_b32_e32 v33, v157
	v_mov_b32_e32 v34, v157
	v_mov_b32_e32 v35, v157

; #define LAS __attribute__((address_space(3)))
; __device__ __forceinline__ unsigned cvtpk(float lo, float hi) { f32x2_t v = {lo, hi}; bf16x2_t b = __builtin_convertvector(v, bf16x2_t); return __builtin_bit_cast(unsigned, b); }
; #define MFMA32(a, b, c) __builtin_amdgcn_mfma_f32_32x32x16_bf16((a), (b), (c), 0, 0, 0)
; template <int NDT, class F>
; __device__ __forceinline__ void softmax_body(f32x16& s, const F& f, int k0, int hh, f32x16 (&o)[NDT], float& m, float& l, bf16x8& pf0, bf16x8& pf1, const int MASK) {
;     ...
;     const float me = fmaxf(m, -1e29f);
;     const float off = on ? f.tadd - me : NEG_BIG;
;     const f32x2_t sc2 = {QK_SCL, QK_SCL}, of2 = {off, off}; f32x2_t ps2 = {0.f, 0.f};
; #pragma unroll
;     for (int r = 0; r < 16; r += 2) { f32x2_t a = {s[r], s[r + 1]}; a = __builtin_elementwise_fma(a, sc2, of2);
;         f32x2_t p; p.x = __builtin_amdgcn_exp2f(a.x); p.y = __builtin_amdgcn_exp2f(a.y); s[r] = p.x; s[r + 1] = p.y; ps2 += p; }
;     l += ps2.x + ps2.y;
;     v4u p0, p1;
;     p0.x = cvtpk(s[0], s[1]); p0.y = cvtpk(s[2], s[3]); p0.z = cvtpk(s[4], s[5]); p0.w = cvtpk(s[6], s[7]);
;     p1.x = cvtpk(s[8], s[9]); p1.y = cvtpk(s[10], s[11]); p1.z = cvtpk(s[12], s[13]); p1.w = cvtpk(s[14], s[15]);
;     pf0 = __builtin_bit_cast(bf16x8, p0); pf1 = __builtin_bit_cast(bf16x8, p1);
; template <class F, class It, class Pre>
; __device__ __forceinline__ void quad_stream(const bf16x8 (&qf)[4], const QuadStream& st, LAS unsigned char* ring, F& f, It itC, It itD, Pre& pre, int n_own, int nsteps, int hh, f32x16 (&o)[2], float& m, float& l) {
;     ...
;         if (k < n_own) {
;             const int t0 = itC.next(); const int msk = pre(t0);
;             const LAS unsigned char* cur = ring + (k & 7) * 8192;
;             f32x16 s;
; #pragma unroll
;             for (int ks = 0; ks < 4; ++ks) { const bf16x8 kf = *(const LAS bf16x8*)(cur + (st.fk ^ (ks << 5))); s = MFMA32(kf, qf[ks], ks == 0 ? f.cv : s); }
;             bf16x8 pf0, pf1; softmax_body<2>(s, f, 32 * t0, hh, o, m, l, pf0, pf1, msk);
; #pragma unroll
;             for (int dt = 0; dt < 2; ++dt) { const bf16x8 vf0 = *(const LAS bf16x8*)(cur + dt * 2048 + st.fv), vf1 = *(const LAS bf16x8*)(cur + dt * 2048 + (st.fv ^ 32));
;                 o[dt] = MFMA32(vf0, pf0, o[dt]); o[dt] = MFMA32(vf1, pf1, o[dt]); }
.LBB0_727:
	v_max_f32_e32 v80, v78, v78
	v_max_f32_e32 v80, 0xefa18f08, v80
	v_sub_f32_e32 v79, v79, v80
	v_cndmask_b32_e64 v80, v235, v79, s[38:39]
	v_fma_f32 v52, v52, s34, v80
	v_fma_f32 v53, v53, s34, v80
	v_fma_f32 v54, v54, s34, v80
	v_fma_f32 v55, v55, s34, v80
	v_exp_f32_e32 v52, v52
	v_exp_f32_e32 v53, v53
	v_exp_f32_e32 v54, v54
	v_exp_f32_e32 v55, v55
	v_fma_f32 v56, v56, s34, v80
	v_fma_f32 v57, v57, s34, v80
	v_fma_f32 v58, v58, s34, v80
	v_fma_f32 v59, v59, s34, v80
	v_exp_f32_e32 v56, v56
	v_exp_f32_e32 v57, v57
	v_exp_f32_e32 v58, v58
	v_exp_f32_e32 v59, v59
	v_fma_f32 v60, v60, s34, v80
	v_fma_f32 v61, v61, s34, v80
	v_pk_add_f32 v[82:83], v[52:53], 0 op_sel_hi:[1,0]
	v_exp_f32_e32 v60, v60
	v_exp_f32_e32 v61, v61
	v_fma_f32 v62, v62, s34, v80
	v_fma_f32 v63, v63, s34, v80
	v_add_f32_e32 v82, v54, v82
	v_add_f32_e32 v83, v55, v83
	v_exp_f32_e32 v62, v62
	v_exp_f32_e32 v63, v63
	v_fma_f32 v64, v64, s34, v80
	v_fma_f32 v65, v65, s34, v80
	v_add_f32_e32 v82, v56, v82
	v_add_f32_e32 v83, v57, v83
	v_exp_f32_e32 v64, v64
	v_exp_f32_e32 v65, v65
	v_fma_f32 v66, v66, s34, v80
	v_fma_f32 v67, v67, s34, v80
	v_add_f32_e32 v82, v58, v82
	v_add_f32_e32 v83, v59, v83
	v_exp_f32_e32 v66, v66
	v_exp_f32_e32 v67, v67
	v_add_f32_e32 v82, v60, v82
	v_add_f32_e32 v83, v61, v83
	v_cvt_pk_bf16_f32 v52, v52, v53
	v_add_f32_e32 v82, v62, v82
	v_add_f32_e32 v83, v63, v83
	v_cvt_pk_bf16_f32 v53, v54, v55
	v_add_f32_e32 v82, v64, v82
	v_add_f32_e32 v83, v65, v83
	v_cvt_pk_bf16_f32 v54, v56, v57
	v_add_f32_e32 v80, v66, v82
	v_add_f32_e32 v81, v67, v83
	v_cvt_pk_bf16_f32 v56, v60, v61
	v_add_f32_e32 v79, v80, v81
	v_add_f32_e32 v157, v157, v79
	v_add_u32_e32 v79, s50, v73
	v_cvt_pk_bf16_f32 v57, v62, v63
	ds_read_b128 v[60:63], v79 offset:4096
	v_add_u32_e32 v80, s50, v77
	v_cvt_pk_bf16_f32 v55, v58, v59
	v_cvt_pk_bf16_f32 v58, v64, v65
	v_cvt_pk_bf16_f32 v59, v66, v67
	ds_read_b128 v[64:67], v80
	s_waitcnt lgkmcnt(0)
	v_mfma_f32_32x32x16_bf16 v[4:19], v[60:63], v[52:55], v[4:19]
	v_mfma_f32_32x32x16_bf16 v[4:19], v[64:67], v[56:59], v[4:19]
	ds_read_b128 v[60:63], v79 offset:6144
	ds_read_b128 v[64:67], v80 offset:2048
	s_waitcnt lgkmcnt(0)
	v_mfma_f32_32x32x16_bf16 v[20:35], v[60:63], v[52:55], v[20:35]
	v_mfma_f32_32x32x16_bf16 v[20:35], v[64:67], v[56:59], v[20:35]
	s_add_i32 s80, s80, 1
	s_addk_i32 s47, 0x2000
	s_cmp_lg_u32 s37, s80
	s_cbranch_scc0 .LBB0_730

; __device__ __forceinline__ float half_sum(float v) { unsigned a, b; half_swap(__builtin_bit_cast(unsigned, v), a, b); return __builtin_bit_cast(float, a) + __builtin_bit_cast(float, b); }
; __device__ __forceinline__ float sigmoidf_(float x) { return __builtin_amdgcn_rcpf(1.f + __builtin_amdgcn_exp2f(-1.4426950408889634f * x)); }
; __device__ __forceinline__ unsigned cvtpk(float lo, float hi) { f32x2_t v = {lo, hi}; bf16x2_t b = __builtin_convertvector(v, bf16x2_t); return __builtin_bit_cast(unsigned, b); }
; __device__ __forceinline__ size_t vtb_off(int b, int hs, int kb) { return ((size_t)(b * NHS + hs) * VTB_KB + kb) * 4096; }
; #define NSA_ROW() ((size_t)b * SEQ + t0 + (fresh_lane() & 31))
; template <class F, class It, class Pre>
; __device__ __forceinline__ void quad_stream(const bf16x8 (&qf)[4], const QuadStream& st, LAS unsigned char* ring, F& f, It itC, It itD, Pre& pre, int n_own, int nsteps, int hh, f32x16 (&o)[2], float& m, float& l) {
;     asm volatile("s_waitcnt vmcnt(0) lgkmcnt(0)" ::: "memory"); __builtin_amdgcn_s_barrier(); asm volatile("" ::: "memory");
;     int lastv = 0;
; #pragma unroll
;     for (int i = 0; i < QD; ++i) { int t = itD.next(); if (t < 0) t = lastv; else lastv = t; st.dma(t, ring + i * 8192); }
; __device__ __forceinline__ void nsa_quad_item(const bf16* PROJ, const bf16* KC, const unsigned char* VCB, const unsigned char* VTB, const unsigned long long* SEL, bf16* O, LAS unsigned char* lds, int bg, int jp, int wave) {
;     ...
;         l = half_sum(l); const float g1 = sigmoidf_(bf2f(PROJ[NSA_ROW() * NINP + C_GATE + hd * 3 + 1])); const float w = l > 0.f ? g1 / l : 0.f;
; #pragma unroll
;         for (int dt = 0; dt < 2; ++dt)
; #pragma unroll
;             for (int r = 0; r < 16; r += 2) res[dt * 8 + (r >> 1)] = cvtpk(o[dt][r] * w, o[dt][r + 1] * w);
;     }
;     {
;         WinBias f; f.setup(slope2, hh); f.tq = tq; f.t0 = t0;
;         QuadStream st; st.setup(PROJ + (size_t)b * SEQ * NINP + C_WINK + g * 64, (size_t)NINP * 2, VTB + vtb_off(b, 9 + g, 0), lane, wi);
;         zero_ot<2>(o); float m = NEG_BIG, l = 0.f;
;         RangeIt it; it.kt = qt; it.kt0 = t0 >= 512 ? (t0 - 512) >> 5 : 0; RangePre<WinBias> pre{f};
;         const int n_own = win_tiles(qt), n_oth = win_tiles(qto);
;         quad_stream(qf, st, ring, f, it, it, pre, n_own, n_own > n_oth ? n_own : n_oth, hh, o, m, l);
.LBB0_730:
	v_mov_b32_e32 v159, v157
	v_mov_b32_e32 v2, v239
	v_mov_b64_e32 v[36:37], s[14:15]
	v_and_or_b32 v2, v2, 31, s6
	v_mad_u64_u32 v[36:37], s[4:5], v2, s83, v[36:37]
	s_lshl_b32 s16, s73, 1
	s_add_u32 s4, s96, s95
	s_addc_u32 s5, s82, 0
	s_add_u32 s4, s4, s54
	s_addc_u32 s5, s5, 0
	s_add_u32 s4, s4, 0x1280
	v_mad_i32_i24 v37, s7, v238, v37
	s_mov_b32 s17, s19
	s_addc_u32 s5, s5, 0
	v_lshl_add_u64 v[36:37], v[36:37], 0, s[16:17]
	s_add_u32 s17, s33, s55
	s_addc_u32 s18, s78, 0
	s_add_u32 s17, s17, 0x480000
	s_addc_u32 s20, s18, 0
	s_add_i32 s18, s9, 0xfffffe00
	s_ashr_i32 s18, s18, 5
	s_cmp_gt_i32 s8, 15
	s_cselect_b32 s21, s18, 0
	s_sub_i32 s24, s8, s21
	s_add_i32 s18, s22, 0xfffffe00
	s_add_i32 s24, s24, 1
	s_ashr_i32 s18, s18, 5
	s_cmp_gt_i32 s10, 15
	s_cselect_b32 s30, s18, 0
	v_add_co_u32_e32 v36, vcc, s35, v36
	s_sub_i32 s18, s10, s30
	s_nop 0
	v_addc_co_u32_e32 v37, vcc, 0, v37, vcc
	s_add_i32 s18, s18, 1
	flat_load_ushort v163, v[36:37] offset:3602
	v_mov_b32_e32 v37, v102
	v_mov_b32_e32 v36, v118
	s_max_i32 s22, s24, s18
	s_add_i32 s25, s8, -1
	s_max_i32 s18, s8, 0
	s_cmp_ge_i32 s8, s21
	v_ashrrev_i32_e32 v2, 3, v36
	v_mul_lo_u32 v38, v2, s83
	v_add_u32_e32 v2, s53, v2
	s_cselect_b32 s18, s18, 0
	v_lshrrev_b32_e32 v2, 1, v2
	s_mul_i32 s33, s18, 0x60000
	v_xor_b32_e32 v2, v2, v36
	s_mul_hi_u32 s31, s18, 0x60000
	s_add_u32 s36, s4, s33
	v_lshlrev_b32_e32 v2, 4, v2
	s_addc_u32 s37, s5, s31
	s_mov_b32 m0, s56
	v_and_or_b32 v2, v2, s85, v38
	s_waitcnt vmcnt(0) lgkmcnt(0)
	s_barrier
	v_lshlrev_b32_e32 v38, 4, v36
	global_load_lds_dwordx4 v2, s[36:37]
	s_lshl_b64 s[36:37], s[18:19], 12
	s_add_u32 s36, s17, s36
	s_addc_u32 s37, s20, s37
	s_cmp_gt_i32 s8, s21
	s_cselect_b32 s25, s25, -1
	s_add_i32 s31, s8, -2
	s_cmp_lt_i32 s25, 0
	s_cselect_b32 s18, s18, s25
	v_bitop3_b32 v100, v36, v38, 48 bitop3:0x6c
	s_mov_b32 m0, s11
	s_mul_i32 s33, s18, 0x60000
	global_load_lds_dwordx4 v100, s[36:37]
	s_mul_hi_u32 s25, s18, 0x60000
	s_add_u32 s36, s4, s33
	s_addc_u32 s37, s5, s25
	s_mov_b32 m0, s23
	s_movk_i32 s80, 0xff
	global_load_lds_dwordx4 v2, s[36:37]
	s_lshl_b64 s[36:37], s[18:19], 12
	s_add_u32 s36, s17, s36
	s_addc_u32 s37, s20, s37
	s_cmp_ge_i32 s31, s21
	s_cselect_b32 s25, s31, -1
	s_add_i32 s31, s8, -3
	s_cmp_lt_i32 s25, 0
	s_cselect_b32 s18, s18, s25
	s_mov_b32 m0, s45
	s_mul_i32 s33, s18, 0x60000
	global_load_lds_dwordx4 v100, s[36:37]
	s_mul_hi_u32 s25, s18, 0x60000
	s_add_u32 s36, s4, s33
	s_addc_u32 s37, s5, s25
	s_mov_b32 m0, s76
	v_permlane32_swap_b32_e32 v157, v159
	global_load_lds_dwordx4 v2, s[36:37]
	s_lshl_b64 s[36:37], s[18:19], 12
	s_add_u32 s36, s17, s36
	s_addc_u32 s37, s20, s37
	s_cmp_ge_i32 s31, s21
	s_cselect_b32 s25, s31, -1
	s_add_i32 s31, s8, -4
	s_cmp_lt_i32 s25, 0
	s_cselect_b32 s18, s18, s25
	s_mov_b32 m0, s60
	s_mul_i32 s33, s18, 0x60000
	global_load_lds_dwordx4 v100, s[36:37]
	s_mul_hi_u32 s25, s18, 0x60000
	s_add_u32 s36, s4, s33
	s_addc_u32 s37, s5, s25
	s_mov_b32 m0, s77
	s_nop 0
	global_load_lds_dwordx4 v2, s[36:37]
	s_lshl_b64 s[36:37], s[18:19], 12
	s_add_u32 s36, s17, s36
	s_addc_u32 s37, s20, s37
	s_cmp_ge_i32 s31, s21
	s_cselect_b32 s25, s31, -1
	s_add_i32 s31, s8, -5
	s_cmp_lt_i32 s25, 0
	s_cselect_b32 s18, s18, s25
	s_mov_b32 m0, s61
	s_mul_i32 s33, s18, 0x60000
	global_load_lds_dwordx4 v100, s[36:37]
	s_mul_hi_u32 s25, s18, 0x60000
	s_add_u32 s36, s4, s33
	s_addc_u32 s37, s5, s25
	s_mov_b32 m0, s12
	s_nop 0
	global_load_lds_dwordx4 v2, s[36:37]
	s_lshl_b64 s[36:37], s[18:19], 12
	s_add_u32 s36, s17, s36
	s_addc_u32 s37, s20, s37
	s_cmp_ge_i32 s31, s21
	s_cselect_b32 s25, s31, -1
	s_cmp_lt_i32 s25, 0
	s_cselect_b32 s18, s18, s25
	s_mov_b32 m0, s62
	s_mul_i32 s31, s18, 0x60000
	global_load_lds_dwordx4 v100, s[36:37]
	s_mul_hi_u32 s25, s18, 0x60000
	s_add_u32 s36, s4, s31
	s_addc_u32 s37, s5, s25
	s_mov_b32 m0, s13
	s_nop 0
	global_load_lds_dwordx4 v2, s[36:37]
	s_lshl_b64 s[36:37], s[18:19], 12
	s_add_u32 s36, s17, s36
	s_addc_u32 s37, s20, s37
	s_mov_b32 m0, s63
	s_cmp_lt_i32 s22, 1
	global_load_lds_dwordx4 v100, s[36:37]
	s_mov_b32 s22, 0
	s_cbranch_scc1 .LBB0_739
; #define LAS __attribute__((address_space(3)))
; #define MFMA32(a, b, c) __builtin_amdgcn_mfma_f32_32x32x16_bf16((a), (b), (c), 0, 0, 0)
;     __device__ __forceinline__ void setup(float g_, int hh_) { g = g_; hh = hh_; asm volatile("" : "+v"(hh_));
; #pragma unroll
;         for (int r = 0; r < 16; ++r) cv[r] = g_ * (1.f / QK_SCL) * (float)(CR(r) + 4 * hh_); }
; template <class F, class It, class Pre>
; __device__ __forceinline__ void quad_stream(const bf16x8 (&qf)[4], const QuadStream& st, LAS unsigned char* ring, F& f, It itC, It itD, Pre& pre, int n_own, int nsteps, int hh, f32x16 (&o)[2], float& m, float& l) {
;     ...
;         if (k < n_own) {
;             const int t0 = itC.next(); const int msk = pre(t0);
;             const LAS unsigned char* cur = ring + (k & 7) * 8192;
;             f32x16 s;
; #pragma unroll
;             for (int ks = 0; ks < 4; ++ks) { const bf16x8 kf = *(const LAS bf16x8*)(cur + (st.fk ^ (ks << 5))); s = MFMA32(kf, qf[ks], ks == 0 ? f.cv : s); }
;             bf16x8 pf0, pf1; softmax_body<2>(s, f, 32 * t0, hh, o, m, l, pf0, pf1, msk);
; #pragma unroll
;             for (int dt = 0; dt < 2; ++dt) { const bf16x8 vf0 = *(const LAS bf16x8*)(cur + dt * 2048 + st.fv), vf1 = *(const LAS bf16x8*)(cur + dt * 2048 + (st.fv ^ 32));
;                 o[dt] = MFMA32(vf0, pf0, o[dt]); o[dt] = MFMA32(vf1, pf1, o[dt]); }
	v_lshlrev_b32_e32 v37, 2, v37
	v_or_b32_e32 v41, 1, v37
	v_or_b32_e32 v38, 3, v37
	v_or_b32_e32 v40, 2, v37
	v_cvt_f32_i32_e32 v39, v38
	v_cvt_f32_i32_e32 v38, v40
	v_cvt_f32_i32_e32 v40, v37
	v_cvt_f32_i32_e32 v41, v41
	v_add_u32_e32 v42, 8, v37
	v_add_u32_e32 v43, 9, v37
	v_add_u32_e32 v44, 10, v37
	v_add_u32_e32 v45, 11, v37
	v_add_u32_e32 v46, 16, v37
	v_add_u32_e32 v47, 17, v37
	v_add_u32_e32 v48, 18, v37
	v_add_u32_e32 v49, 19, v37
	v_add_u32_e32 v50, 24, v37
	v_add_u32_e32 v51, 25, v37
	v_add_u32_e32 v52, 26, v37
	v_add_u32_e32 v53, 27, v37
	v_mov_b32_e32 v149, v148
	v_cvt_f32_i32_e32 v43, v43
	v_cvt_f32_i32_e32 v42, v42
	v_cvt_f32_i32_e32 v45, v45
	v_cvt_f32_i32_e32 v44, v44
	v_cvt_f32_i32_e32 v47, v47
	v_cvt_f32_i32_e32 v46, v46
	v_cvt_f32_i32_e32 v49, v49
	v_cvt_f32_i32_e32 v48, v48
	v_cvt_f32_i32_e32 v51, v51
	v_cvt_f32_i32_e32 v53, v53
	v_cvt_f32_i32_e32 v52, v52
	v_cvt_f32_i32_e32 v50, v50
	v_mul_f32_e32 v70, v148, v38
	v_mul_f32_e32 v71, v149, v39
	v_mul_f32_e32 v68, v152, v40
	v_mul_f32_e32 v69, v153, v41
	v_and_b32_e32 v37, 31, v36
	v_ashrrev_i32_e32 v38, 5, v36
	v_lshrrev_b32_e32 v40, 1, v36
	v_lshrrev_b32_e32 v36, 2, v36
	v_bitop3_b32 v36, v36, v38, 3 bitop3:0x6c
	v_lshlrev_b32_e32 v36, 4, v36
	v_lshlrev_b32_e32 v39, 7, v37
	v_bitop3_b32 v40, v40, v38, 7 bitop3:0x6c
	v_lshl_add_u32 v104, v37, 6, v36
	s_sub_i32 s30, s74, s30
	s_sub_i32 s31, s75, s21
	v_mul_f32_e32 v82, v148, v52
	v_mul_f32_e32 v83, v149, v53
	v_mul_f32_e32 v80, v148, v50
	v_mul_f32_e32 v81, v149, v51
	v_mul_f32_e32 v78, v148, v48
	v_mul_f32_e32 v79, v149, v49
	v_mul_f32_e32 v76, v148, v46
	v_mul_f32_e32 v77, v149, v47
	v_mul_f32_e32 v74, v148, v44
	v_mul_f32_e32 v75, v149, v45
	v_mul_f32_e32 v72, v148, v42
	v_mul_f32_e32 v73, v149, v43
	v_lshl_add_u32 v103, v40, 4, v39
	v_add_u32_e32 v36, 0x1000, v104
	s_sub_i32 s30, s30, s97
	s_sub_i32 s31, s31, s97
	v_mov_b32_e32 v149, 0
	v_mov_b32_e32 v101, v3
	s_add_i32 s25, s8, -6
	v_xor_b32_e32 v105, 32, v103
	v_xor_b32_e32 v106, 64, v103
	v_xor_b32_e32 v107, 0x60, v103
	v_xor_b32_e32 v108, 32, v36
	s_max_i32 s33, s30, s31
	v_mov_b32_e32 v109, 0xf149f2ca
	s_mov_b32 s36, 0
	s_mov_b32 s37, s8
	v_mov_b32_e32 v36, 0
	v_mov_b32_e32 v37, v149
	v_mov_b32_e32 v38, v149
	v_mov_b32_e32 v39, v149
	v_mov_b32_e32 v40, v149
	v_mov_b32_e32 v41, v149
	v_mov_b32_e32 v42, v149
	v_mov_b32_e32 v43, v149
	v_mov_b32_e32 v44, v149
	v_mov_b32_e32 v45, v149
	v_mov_b32_e32 v46, v149
	v_mov_b32_e32 v47, v149
	v_mov_b32_e32 v48, v149
	v_mov_b32_e32 v49, v149
	v_mov_b32_e32 v50, v149
	v_mov_b32_e32 v51, v149
	v_mov_b32_e32 v52, v149
	v_mov_b32_e32 v53, v149
	v_mov_b32_e32 v54, v149
	v_mov_b32_e32 v55, v149
	v_mov_b32_e32 v56, v149
	v_mov_b32_e32 v57, v149
	v_mov_b32_e32 v58, v149
	v_mov_b32_e32 v59, v149
	v_mov_b32_e32 v60, v149
	v_mov_b32_e32 v61, v149
	v_mov_b32_e32 v62, v149
	v_mov_b32_e32 v63, v149
	v_mov_b32_e32 v64, v149
	v_mov_b32_e32 v65, v149
	v_mov_b32_e32 v66, v149
	v_mov_b32_e32 v67, v149
	s_movk_i32 s82, 0xa3f
	s_mov_b64 s[96:97], 0x2c800000
	s_branch .LBB0_734
.LBB0_732:
	v_max_f32_e32 v111, v109, v109
	v_max_f32_e32 v111, 0xefa18f08, v111
	v_sub_f32_e32 v110, v110, v111
	v_fma_f32 v84, v84, s34, v110
	v_fma_f32 v85, v85, s34, v110
	v_fma_f32 v86, v86, s34, v110
	v_fma_f32 v87, v87, s34, v110
	v_exp_f32_e32 v84, v84
	v_exp_f32_e32 v85, v85
	v_exp_f32_e32 v86, v86
	v_exp_f32_e32 v87, v87
	v_fma_f32 v88, v88, s34, v110
	v_fma_f32 v89, v89, s34, v110
	v_fma_f32 v90, v90, s34, v110
	v_fma_f32 v91, v91, s34, v110
	v_exp_f32_e32 v88, v88
	v_exp_f32_e32 v89, v89
	v_exp_f32_e32 v90, v90
	v_exp_f32_e32 v91, v91
	v_fma_f32 v92, v92, s34, v110
	v_fma_f32 v93, v93, s34, v110
	v_pk_add_f32 v[112:113], v[84:85], 0 op_sel_hi:[1,0]
	v_exp_f32_e32 v92, v92
	v_exp_f32_e32 v93, v93
	v_fma_f32 v94, v94, s34, v110
	v_fma_f32 v95, v95, s34, v110
	v_add_f32_e32 v112, v86, v112
	v_add_f32_e32 v113, v87, v113
	v_exp_f32_e32 v94, v94
	v_exp_f32_e32 v95, v95
	v_fma_f32 v96, v96, s34, v110
	v_fma_f32 v97, v97, s34, v110
	v_add_f32_e32 v112, v88, v112
	v_add_f32_e32 v113, v89, v113
	v_exp_f32_e32 v96, v96
	v_exp_f32_e32 v97, v97
	v_fma_f32 v98, v98, s34, v110
	v_fma_f32 v99, v99, s34, v110
	v_add_f32_e32 v112, v90, v112
	v_add_f32_e32 v113, v91, v113
	v_exp_f32_e32 v98, v98
	v_exp_f32_e32 v99, v99
	v_add_f32_e32 v112, v92, v112
	v_add_f32_e32 v113, v93, v113
	v_cvt_pk_bf16_f32 v84, v84, v85
	v_add_f32_e32 v112, v94, v112
	v_add_f32_e32 v113, v95, v113
	v_cvt_pk_bf16_f32 v85, v86, v87
	v_add_f32_e32 v112, v96, v112
	v_add_f32_e32 v113, v97, v113
	v_cvt_pk_bf16_f32 v86, v88, v89
	v_add_f32_e32 v110, v98, v112
	v_add_f32_e32 v111, v99, v113
	v_cvt_pk_bf16_f32 v88, v92, v93
	v_add_f32_e32 v110, v110, v111
	v_add_f32_e32 v149, v149, v110
	v_add_u32_e32 v110, s30, v104
	v_cvt_pk_bf16_f32 v89, v94, v95
	ds_read_b128 v[92:95], v110 offset:4096
	v_add_u32_e32 v111, s30, v108
	v_cvt_pk_bf16_f32 v87, v90, v91
	v_cvt_pk_bf16_f32 v90, v96, v97
	v_cvt_pk_bf16_f32 v91, v98, v99
	ds_read_b128 v[96:99], v111
	s_waitcnt lgkmcnt(0)
	v_mfma_f32_32x32x16_bf16 v[36:51], v[92:95], v[84:87], v[36:51]
	s_add_i32 s37, s37, -1
	v_mfma_f32_32x32x16_bf16 v[36:51], v[96:99], v[88:91], v[36:51]
	ds_read_b128 v[92:95], v110 offset:6144
	ds_read_b128 v[96:99], v111 offset:2048
	s_waitcnt lgkmcnt(0)
	v_mfma_f32_32x32x16_bf16 v[52:67], v[92:95], v[84:87], v[52:67]
	v_mfma_f32_32x32x16_bf16 v[52:67], v[96:99], v[88:91], v[52:67]

; __device__ __forceinline__ float half_sum(float v) { unsigned a, b; half_swap(__builtin_bit_cast(unsigned, v), a, b); return __builtin_bit_cast(float, a) + __builtin_bit_cast(float, b); }
; __device__ __forceinline__ float sigmoidf_(float x) { return __builtin_amdgcn_rcpf(1.f + __builtin_amdgcn_exp2f(-1.4426950408889634f * x)); }
; __device__ __forceinline__ unsigned cvtpk(float lo, float hi) { f32x2_t v = {lo, hi}; bf16x2_t b = __builtin_convertvector(v, bf16x2_t); return __builtin_bit_cast(unsigned, b); }
; #define NSA_ROW() ((size_t)b * SEQ + t0 + (fresh_lane() & 31))
; __device__ __forceinline__ int cmp_tiles(int qt) { const int tmax = 32 * qt + 31; int ncm = tmax >= 31 ? ((tmax - 31) >> 4) + 1 : 0; ncm = ncm > 255 ? 255 : ncm; return (ncm + 31) >> 5; }
;     __device__ __forceinline__ void setup(float g_, int hh_) { g = g_; hh = hh_; asm volatile("" : "+v"(hh_));
; #pragma unroll
;         for (int r = 0; r < 16; ++r) cv[r] = g_ * (1.f / QK_SCL) * (float)(CR(r) + 4 * hh_); }
; __device__ __forceinline__ void nsa_quad_item(const bf16* PROJ, const bf16* KC, const unsigned char* VCB, const unsigned char* VTB, const unsigned long long* SEL, bf16* O, LAS unsigned char* lds, int bg, int jp, int wave) {
;     ...
;         l = half_sum(l); const float g2 = sigmoidf_(bf2f(PROJ[NSA_ROW() * NINP + C_GATE + hd * 3 + 2])); const float w = l > 0.f ? g2 / l : 0.f;
; #pragma unroll
;         for (int dt = 0; dt < 2; ++dt)
; #pragma unroll
;             for (int r = 0; r < 16; r += 2) { const unsigned pr = res[dt * 8 + (r >> 1)]; res[dt * 8 + (r >> 1)] = cvtpk(fmaf(o[dt][r], w, lo16(pr)), fmaf(o[dt][r + 1], w, hi16(pr))); }
;     }
;     {
;         CmpBias f; f.setup(16.f * slope2, hh); f.tq = tq; f.ncv = tq >= 31 ? ((tq - 31) >> 4) + 1 : 0; f.ncv = f.ncv > 255 ? 255 : f.ncv;
;         f.ncv_min = t0 >= 31 ? ((t0 - 31) >> 4) + 1 : 0; f.ncv_min = f.ncv_min > 255 ? 255 : f.ncv_min;
;         QuadStream st; st.setup(KC + (size_t)((0 * BATCH + b) * 2 + g) * 256 * 64, 128, VCB + (size_t)(b * 2 + g) * 8 * 4096, lane, wi);
;         zero_ot<2>(o); float m = NEG_BIG, l = 0.f;
;         const int n_own = cmp_tiles(qt), n_oth = cmp_tiles(qto);
;         RangeIt it; it.kt = n_own - 1; it.kt0 = 0; RangePre<CmpBias> pre{f};
;         quad_stream(qf, st, ring, f, it, it, pre, n_own, n_own > n_oth ? n_own : n_oth, hh, o, m, l);
.LBB0_740:
	v_mov_b32_e32 v164, v149
	v_mov_b32_e32 v2, v239
	v_mov_b64_e32 v[68:69], s[14:15]
	v_and_or_b32 v2, v2, 31, s6
	v_mad_u64_u32 v[68:69], s[4:5], v2, s83, v[68:69]
	v_mad_i32_i24 v69, s7, v238, v69
	s_mov_b32 s17, s19
	v_lshl_add_u64 v[68:69], v[68:69], 0, s[16:17]
	s_add_u32 s17, s26, s67
	s_addc_u32 s18, s27, 0
	s_add_u32 s4, s17, s55
	s_addc_u32 s5, s18, 0
	s_add_u32 s4, s4, 0x300000
	s_addc_u32 s5, s5, 0
	s_add_u32 s17, s17, s55
	s_addc_u32 s18, s18, 0
	s_add_u32 s17, s17, 0x380000
	s_addc_u32 s20, s18, 0
	s_lshl_b32 s18, s8, 1
	s_or_b32 s18, s18, 1
	s_min_i32 s18, s18, 0xff
	s_add_i32 s18, s18, 31
	s_ashr_i32 s18, s18, 5
	s_cmp_gt_i32 s8, -1
	s_cselect_b32 s21, s18, 0
	s_lshl_b32 s18, s10, 1
	s_or_b32 s18, s18, 1
	s_min_i32 s18, s18, 0xff
	s_add_i32 s18, s18, 31
	v_add_co_u32_e32 v68, vcc, s35, v68
	s_ashr_i32 s18, s18, 5
	s_nop 0
	v_addc_co_u32_e32 v69, vcc, 0, v69, vcc
	s_cmp_gt_i32 s10, -1
	flat_load_ushort v165, v[68:69] offset:3604
	s_cselect_b32 s18, s18, 0
	v_ashrrev_i32_e32 v2, 3, v118
	s_add_i32 s10, s21, -1
	v_lshlrev_b32_e32 v68, 7, v2
	v_add_u32_e32 v2, s53, v2
	s_max_i32 s22, s21, s18
	s_max_i32 s18, s10, 0
	v_lshrrev_b32_e32 v2, 1, v2
	s_lshl_b64 s[24:25], s[18:19], 12
	v_xor_b32_e32 v2, v2, v118
	s_add_u32 s30, s4, s24
	v_lshlrev_b32_e32 v2, 4, v2
	s_addc_u32 s31, s5, s25
	s_mov_b32 m0, s56
	v_and_or_b32 v2, v2, s85, v68
	s_add_u32 s24, s17, s24
	s_waitcnt vmcnt(0) lgkmcnt(0)
	s_barrier
	s_addc_u32 s25, s20, s25
	global_load_lds_dwordx4 v2, s[30:31]
	s_mov_b32 m0, s11
	s_max_i32 s11, s21, 1
	s_add_i32 s11, s11, -2
	v_lshlrev_b32_e32 v68, 4, v118
	s_cmp_lt_i32 s21, 2
	v_bitop3_b32 v160, v118, v68, 48 bitop3:0x6c
	s_cselect_b32 s18, s18, s11
	global_load_lds_dwordx4 v160, s[24:25]
	s_lshl_b64 s[24:25], s[18:19], 12
	s_add_u32 s30, s4, s24
	s_addc_u32 s31, s5, s25
	s_add_u32 s24, s17, s24
	s_addc_u32 s25, s20, s25
	s_max_i32 s11, s21, 2
	s_add_i32 s11, s11, -3
	s_mov_b32 m0, s23
	s_cmp_lt_i32 s21, 3
	s_cselect_b32 s18, s18, s11
	global_load_lds_dwordx4 v2, s[30:31]
	s_mov_b32 m0, s45
	v_permlane32_swap_b32_e32 v149, v164
	global_load_lds_dwordx4 v160, s[24:25]
	s_lshl_b64 s[24:25], s[18:19], 12
	s_add_u32 s30, s4, s24
	s_addc_u32 s31, s5, s25
	s_add_u32 s24, s17, s24
	s_addc_u32 s25, s20, s25
	s_max_i32 s11, s21, 3
	s_add_i32 s11, s11, -4
	s_mov_b32 m0, s76
	s_cmp_lt_i32 s21, 4
	s_cselect_b32 s18, s18, s11
	global_load_lds_dwordx4 v2, s[30:31]
	s_mov_b32 m0, s60
	s_nop 0
	global_load_lds_dwordx4 v160, s[24:25]
	s_lshl_b64 s[24:25], s[18:19], 12
	s_add_u32 s30, s4, s24
	s_addc_u32 s31, s5, s25
	s_add_u32 s24, s17, s24
	s_addc_u32 s25, s20, s25
	s_max_i32 s11, s21, 4
	s_add_i32 s11, s11, -5
	s_mov_b32 m0, s77
	s_cmp_lt_i32 s21, 5
	s_cselect_b32 s18, s18, s11
	global_load_lds_dwordx4 v2, s[30:31]
	s_mov_b32 m0, s61
	s_nop 0
	global_load_lds_dwordx4 v160, s[24:25]
	s_lshl_b64 s[24:25], s[18:19], 12
	s_add_u32 s30, s4, s24
	s_addc_u32 s31, s5, s25
	s_add_u32 s24, s17, s24
	s_addc_u32 s25, s20, s25
	s_max_i32 s11, s21, 5
	s_add_i32 s11, s11, -6
	s_mov_b32 m0, s12
	s_cmp_lt_i32 s21, 6
	s_cselect_b32 s18, s18, s11
	global_load_lds_dwordx4 v2, s[30:31]
	s_mov_b32 m0, s62
	s_mov_b32 s11, 0
	global_load_lds_dwordx4 v160, s[24:25]
	s_lshl_b64 s[24:25], s[18:19], 12
	s_add_u32 s30, s4, s24
	s_addc_u32 s31, s5, s25
	s_mov_b32 m0, s13
	s_add_u32 s12, s17, s24
	s_addc_u32 s13, s20, s25
	global_load_lds_dwordx4 v2, s[30:31]
	s_mov_b32 m0, s63
	s_cmp_lt_i32 s22, 1
	global_load_lds_dwordx4 v160, s[12:13]
	s_cbranch_scc1 .LBB0_671
	v_lshlrev_b32_e32 v70, 2, v102
	v_or_b32_e32 v68, 3, v70
	v_or_b32_e32 v72, 2, v70
	v_add_u32_e32 v74, 8, v70
	v_add_u32_e32 v73, 9, v70
	v_add_u32_e32 v76, 10, v70
	v_add_u32_e32 v75, 11, v70
	v_add_u32_e32 v78, 16, v70
	v_add_u32_e32 v77, 17, v70
	v_add_u32_e32 v80, 18, v70
	v_add_u32_e32 v79, 19, v70
	v_add_u32_e32 v84, 24, v70
	v_add_u32_e32 v81, 25, v70
	v_add_u32_e32 v82, 26, v70
	v_add_u32_e32 v83, 27, v70
	v_cvt_f32_i32_e32 v69, v68
	v_cvt_f32_i32_e32 v68, v72
	v_cvt_f32_i32_e32 v73, v73
	v_cvt_f32_i32_e32 v72, v74
	v_cvt_f32_i32_e32 v75, v75
	v_cvt_f32_i32_e32 v74, v76
	v_cvt_f32_i32_e32 v77, v77
	v_cvt_f32_i32_e32 v76, v78
	v_cvt_f32_i32_e32 v79, v79
	v_cvt_f32_i32_e32 v78, v80
	v_cvt_f32_i32_e32 v81, v81
	v_cvt_f32_i32_e32 v83, v83
	v_cvt_f32_i32_e32 v82, v82
	v_cvt_f32_i32_e32 v80, v84
	v_or_b32_e32 v71, 1, v70
	v_mov_b32_e32 v151, v150
	v_cvt_f32_i32_e32 v70, v70
	v_cvt_f32_i32_e32 v71, v71
	v_mul_f32_e32 v102, v150, v68
	v_mul_f32_e32 v103, v151, v69
	v_mul_f32_e32 v114, v150, v82
	v_mul_f32_e32 v115, v151, v83
	v_mul_f32_e32 v112, v150, v80
	v_mul_f32_e32 v113, v151, v81
	v_mul_f32_e32 v110, v150, v78
	v_mul_f32_e32 v111, v151, v79
	v_mul_f32_e32 v108, v150, v76
	v_mul_f32_e32 v109, v151, v77
	v_mul_f32_e32 v106, v150, v74
	v_mul_f32_e32 v107, v151, v75
	v_mul_f32_e32 v104, v150, v72
	v_mul_f32_e32 v105, v151, v73
	v_subrev_u32_e32 v151, 31, v116
	v_ashrrev_i32_e32 v68, 4, v151
	v_min_i32_e32 v68, 0xfe, v68
	v_add_u32_e32 v68, 1, v68
	v_cmp_lt_i32_e32 vcc, 30, v116
	v_mul_f32_e32 v100, v154, v70
	v_mul_f32_e32 v101, v155, v71
	v_ashrrev_i32_e32 v69, 5, v118
	v_cndmask_b32_e32 v166, 0, v68, vcc
	v_and_b32_e32 v68, 31, v118
	v_lshrrev_b32_e32 v71, 1, v118
	v_lshlrev_b32_e32 v70, 7, v68
	v_bitop3_b32 v71, v71, v69, 7 bitop3:0x6c
	s_sub_i32 s9, s9, 31
	v_lshl_add_u32 v167, v71, 4, v70
	v_lshrrev_b32_e32 v70, 2, v118
	s_ashr_i32 s9, s9, 4
	v_bitop3_b32 v69, v70, v69, 3 bitop3:0x6c
	s_or_b32 s9, s9, 1
	v_lshlrev_b32_e32 v69, 4, v69
	s_min_i32 s9, s9, 0xff
	v_lshl_add_u32 v168, v68, 6, v69
	s_cmp_gt_i32 s8, 0
	v_add_u32_e32 v68, 0x1000, v168
	v_mov_b32_e32 v156, 0
	v_mov_b32_e32 v161, v3
	s_cselect_b32 s8, s9, 0
	s_add_i32 s9, s21, -7
	v_xor_b32_e32 v169, 32, v167
	v_xor_b32_e32 v170, 64, v167
	v_xor_b32_e32 v171, 0x60, v167
	v_xor_b32_e32 v172, 32, v68
	v_mov_b32_e32 v173, 0xf149f2ca
	s_mov_b32 s12, 0
	v_mov_b32_e32 v84, 0
	v_mov_b32_e32 v85, v156
	v_mov_b32_e32 v86, v156
	v_mov_b32_e32 v87, v156
	v_mov_b32_e32 v88, v156
	v_mov_b32_e32 v89, v156
	v_mov_b32_e32 v90, v156
	v_mov_b32_e32 v91, v156
	v_mov_b32_e32 v92, v156
	v_mov_b32_e32 v93, v156
	v_mov_b32_e32 v94, v156
	v_mov_b32_e32 v95, v156
	v_mov_b32_e32 v96, v156
	v_mov_b32_e32 v97, v156
	v_mov_b32_e32 v98, v156
	v_mov_b32_e32 v99, v156
	v_mov_b32_e32 v68, v156
	v_mov_b32_e32 v69, v156
	v_mov_b32_e32 v70, v156
	v_mov_b32_e32 v71, v156
	v_mov_b32_e32 v72, v156
	v_mov_b32_e32 v73, v156
	v_mov_b32_e32 v74, v156
	v_mov_b32_e32 v75, v156
	v_mov_b32_e32 v76, v156
	v_mov_b32_e32 v77, v156
	v_mov_b32_e32 v78, v156
	v_mov_b32_e32 v79, v156
	v_mov_b32_e32 v80, v156
	v_mov_b32_e32 v81, v156
	v_mov_b32_e32 v82, v156
	v_mov_b32_e32 v83, v156
	s_branch .LBB0_744
; #define LAS __attribute__((address_space(3)))
; __device__ __forceinline__ unsigned cvtpk(float lo, float hi) { f32x2_t v = {lo, hi}; bf16x2_t b = __builtin_convertvector(v, bf16x2_t); return __builtin_bit_cast(unsigned, b); }
; #define MFMA32(a, b, c) __builtin_amdgcn_mfma_f32_32x32x16_bf16((a), (b), (c), 0, 0, 0)
; template <int NDT, class F>
; __device__ __forceinline__ void softmax_body(f32x16& s, const F& f, int k0, int hh, f32x16 (&o)[NDT], float& m, float& l, bf16x8& pf0, bf16x8& pf1, const int MASK) {
;     ...
;     const float me = fmaxf(m, -1e29f);
;     const float off = on ? f.tadd - me : NEG_BIG;
;     const f32x2_t sc2 = {QK_SCL, QK_SCL}, of2 = {off, off}; f32x2_t ps2 = {0.f, 0.f};
; #pragma unroll
;     for (int r = 0; r < 16; r += 2) { f32x2_t a = {s[r], s[r + 1]}; a = __builtin_elementwise_fma(a, sc2, of2);
;         f32x2_t p; p.x = __builtin_amdgcn_exp2f(a.x); p.y = __builtin_amdgcn_exp2f(a.y); s[r] = p.x; s[r + 1] = p.y; ps2 += p; }
;     l += ps2.x + ps2.y;
;     v4u p0, p1;
;     p0.x = cvtpk(s[0], s[1]); p0.y = cvtpk(s[2], s[3]); p0.z = cvtpk(s[4], s[5]); p0.w = cvtpk(s[6], s[7]);
;     p1.x = cvtpk(s[8], s[9]); p1.y = cvtpk(s[10], s[11]); p1.z = cvtpk(s[12], s[13]); p1.w = cvtpk(s[14], s[15]);
;     pf0 = __builtin_bit_cast(bf16x8, p0); pf1 = __builtin_bit_cast(bf16x8, p1);
; template <class F, class It, class Pre>
; __device__ __forceinline__ void quad_stream(const bf16x8 (&qf)[4], const QuadStream& st, LAS unsigned char* ring, F& f, It itC, It itD, Pre& pre, int n_own, int nsteps, int hh, f32x16 (&o)[2], float& m, float& l) {
;     ...
;         if (k < n_own) {
;             const int t0 = itC.next(); const int msk = pre(t0);
;             const LAS unsigned char* cur = ring + (k & 7) * 8192;
;             f32x16 s;
; #pragma unroll
;             for (int ks = 0; ks < 4; ++ks) { const bf16x8 kf = *(const LAS bf16x8*)(cur + (st.fk ^ (ks << 5))); s = MFMA32(kf, qf[ks], ks == 0 ? f.cv : s); }
;             bf16x8 pf0, pf1; softmax_body<2>(s, f, 32 * t0, hh, o, m, l, pf0, pf1, msk);
; #pragma unroll
;             for (int dt = 0; dt < 2; ++dt) { const bf16x8 vf0 = *(const LAS bf16x8*)(cur + dt * 2048 + st.fv), vf1 = *(const LAS bf16x8*)(cur + dt * 2048 + (st.fv ^ 32));
;                 o[dt] = MFMA32(vf0, pf0, o[dt]); o[dt] = MFMA32(vf1, pf1, o[dt]); }
.LBB0_742:
	v_max_f32_e32 v175, v173, v173
	v_max_f32_e32 v175, 0xefa18f08, v175
	v_sub_f32_e32 v174, v174, v175
	v_fma_f32 v116, v116, s34, v174
	v_fma_f32 v117, v117, s34, v174
	v_fma_f32 v118, v118, s34, v174
	v_fma_f32 v119, v119, s34, v174
	v_exp_f32_e32 v116, v116
	v_exp_f32_e32 v117, v117
	v_exp_f32_e32 v118, v118
	v_exp_f32_e32 v119, v119
	v_fma_f32 v120, v120, s34, v174
	v_fma_f32 v121, v121, s34, v174
	v_fma_f32 v122, v122, s34, v174
	v_fma_f32 v123, v123, s34, v174
	v_exp_f32_e32 v120, v120
	v_exp_f32_e32 v121, v121
	v_exp_f32_e32 v122, v122
	v_exp_f32_e32 v123, v123
	v_fma_f32 v124, v124, s34, v174
	v_fma_f32 v125, v125, s34, v174
	v_pk_add_f32 v[176:177], v[116:117], 0 op_sel_hi:[1,0]
	v_exp_f32_e32 v124, v124
	v_exp_f32_e32 v125, v125
	v_fma_f32 v126, v126, s34, v174
	v_fma_f32 v127, v127, s34, v174
	v_add_f32_e32 v176, v118, v176
	v_add_f32_e32 v177, v119, v177
	v_exp_f32_e32 v126, v126
	v_exp_f32_e32 v127, v127
	v_fma_f32 v128, v128, s34, v174
	v_fma_f32 v129, v129, s34, v174
	v_add_f32_e32 v176, v120, v176
	v_add_f32_e32 v177, v121, v177
	v_exp_f32_e32 v128, v128
	v_exp_f32_e32 v129, v129
	v_fma_f32 v130, v130, s34, v174
	v_fma_f32 v131, v131, s34, v174
	v_add_f32_e32 v176, v122, v176
	v_add_f32_e32 v177, v123, v177
	v_exp_f32_e32 v130, v130
	v_exp_f32_e32 v131, v131
	v_add_f32_e32 v176, v124, v176
	v_add_f32_e32 v177, v125, v177
	v_cvt_pk_bf16_f32 v116, v116, v117
	v_add_f32_e32 v176, v126, v176
	v_add_f32_e32 v177, v127, v177
	v_cvt_pk_bf16_f32 v117, v118, v119
	v_add_f32_e32 v176, v128, v176
	v_add_f32_e32 v177, v129, v177
	v_cvt_pk_bf16_f32 v118, v120, v121
	v_add_f32_e32 v174, v130, v176
	v_add_f32_e32 v175, v131, v177
	v_cvt_pk_bf16_f32 v120, v124, v125
	v_add_f32_e32 v174, v174, v175
	v_add_f32_e32 v156, v156, v174
	v_add_u32_e32 v174, s13, v168
	v_cvt_pk_bf16_f32 v121, v126, v127
	ds_read_b128 v[124:127], v174 offset:4096
	v_add_u32_e32 v175, s13, v172
	v_cvt_pk_bf16_f32 v119, v122, v123
	v_cvt_pk_bf16_f32 v122, v128, v129
	v_cvt_pk_bf16_f32 v123, v130, v131
	ds_read_b128 v[128:131], v175
	s_waitcnt lgkmcnt(0)
	v_mfma_f32_32x32x16_bf16 v[84:99], v[124:127], v[116:119], v[84:99]
	s_add_i32 s10, s10, -1
	v_mfma_f32_32x32x16_bf16 v[84:99], v[128:131], v[120:123], v[84:99]
	ds_read_b128 v[124:127], v174 offset:6144
	ds_read_b128 v[128:131], v175 offset:2048
	s_waitcnt lgkmcnt(0)
	v_mfma_f32_32x32x16_bf16 v[68:83], v[124:127], v[116:119], v[68:83]
	v_mfma_f32_32x32x16_bf16 v[68:83], v[128:131], v[120:123], v[68:83]

; __device__ __forceinline__ float half_sum(float v) { unsigned a, b; half_swap(__builtin_bit_cast(unsigned, v), a, b); return __builtin_bit_cast(float, a) + __builtin_bit_cast(float, b); }
; __device__ __forceinline__ void dil_item_mfma(const bf16* PROJ, const unsigned char* VTB, bf16* O, LAS unsigned char* ring  , int bj, int r16, int qt8, int lane) {
;     ...
;         l[g] = half_sum(l[g]);
;     }
;     const float mx = fmaxf(m[0], fmaxf(m[1], m[2]));
;     const float e0 = __builtin_amdgcn_exp2f(m[0] - mx), e1 = __builtin_amdgcn_exp2f(m[1] - mx), e2 = __builtin_amdgcn_exp2f(m[2] - mx);
;     const float inv = 1.f / (l[0] * e0 + l[1] * e1 + l[2] * e2);
;     store_ot<2>(O + row * DM + O_DIL + (0 + j) * 64, o[0], e0 * inv, hh);
;     store_ot<2>(O + row * DM + O_DIL + (3 + j) * 64, o[1], e1 * inv, hh);
;     store_ot<2>(O + row * DM + O_DIL + (6 + j) * 64, o[2], e2 * inv, hh);
.LBB0_753:
	v_max3_f32 v100, v1, v180, v167
	v_sub_f32_e32 v1, v1, v100
	v_exp_f32_e32 v102, v1
	v_sub_f32_e32 v1, v180, v100
	v_sub_f32_e32 v100, v167, v100
	v_add_f32_e32 v2, v171, v181
	v_mov_b32_e32 v171, v169
	v_exp_f32_e32 v103, v100
	v_exp_f32_e32 v1, v1
	v_permlane32_swap_b32_e32 v169, v171
	v_add_f32_e32 v100, v168, v170
	v_add_f32_e32 v101, v169, v171
	v_ashrrev_i32_e32 v167, 31, v166
	v_mul_f32_e32 v100, v100, v102
	v_mul_f32_e32 v101, v101, v103
	s_nop 0
	v_fma_f32 v2, v2, v1, v100
	v_add_f32_e32 v2, v2, v101
	v_div_scale_f32 v100, s[4:5], v2, v2, 1.0
	v_rcp_f32_e32 v101, v100
	s_mov_b64 s[4:5], 0x2800780
	v_fma_f32 v104, -v100, v101, 1.0
	v_fmac_f32_e32 v101, v104, v101
	v_div_scale_f32 v104, vcc, 1.0, v2, 1.0
	v_mul_f32_e32 v105, v104, v101
	v_fma_f32 v106, -v100, v105, v104
	v_fmac_f32_e32 v105, v106, v101
	v_fma_f32 v100, -v100, v105, v104
	v_div_fmas_f32 v100, v100, v101, v105
	v_div_fixup_f32 v106, v100, v2, 1.0
	v_lshlrev_b64 v[100:101], 12, v[164:165]
	v_lshl_add_u64 v[100:101], s[14:15], 0, v[100:101]
	v_lshl_add_u64 v[100:101], s[26:27], 1, v[100:101]
	v_mul_f32_e32 v2, v102, v106
	v_lshl_add_u64 v[104:105], v[166:167], 1, v[100:101]
	v_mul_f32_e32 v20, v20, v2
	v_mul_f32_e32 v21, v21, v2
	v_mul_f32_e32 v22, v22, v2
	v_mul_f32_e32 v23, v23, v2
	v_mul_f32_e32 v4, v4, v2
	v_mul_f32_e32 v5, v5, v2
	v_mul_f32_e32 v6, v6, v2
	v_mul_f32_e32 v7, v7, v2
	v_lshl_add_u64 v[100:101], v[104:105], 0, s[4:5]
	v_cvt_pk_bf16_f32 v20, v20, v21
	v_cvt_pk_bf16_f32 v21, v22, v23
	v_add_co_u32_e32 v22, vcc, s88, v104
	v_cvt_pk_bf16_f32 v4, v4, v5
	v_cvt_pk_bf16_f32 v5, v6, v7
	v_addc_co_u32_e32 v23, vcc, 0, v105, vcc
	flat_store_dwordx2 v[100:101], v[4:5] offset:64
	v_mul_f32_e32 v4, v8, v2
	v_mul_f32_e32 v5, v9, v2
	v_mul_f32_e32 v6, v10, v2
	v_mul_f32_e32 v7, v11, v2
	flat_store_dwordx2 v[22:23], v[20:21] offset:1920
	v_mul_f32_e32 v20, v24, v2
	v_mul_f32_e32 v21, v25, v2
	v_mul_f32_e32 v22, v26, v2
	v_mul_f32_e32 v23, v27, v2
	v_cvt_pk_bf16_f32 v4, v4, v5
	v_cvt_pk_bf16_f32 v5, v6, v7
	v_cvt_pk_bf16_f32 v20, v20, v21
	v_cvt_pk_bf16_f32 v21, v22, v23
	flat_store_dwordx2 v[100:101], v[4:5] offset:80
	v_mul_f32_e32 v4, v12, v2
	v_mul_f32_e32 v5, v13, v2
	v_mul_f32_e32 v6, v14, v2
	v_mul_f32_e32 v7, v15, v2
	flat_store_dwordx2 v[100:101], v[20:21] offset:16
	v_mul_f32_e32 v20, v28, v2
	v_mul_f32_e32 v21, v29, v2
	v_mul_f32_e32 v22, v30, v2
	v_mul_f32_e32 v23, v31, v2
	v_cvt_pk_bf16_f32 v4, v4, v5
	v_cvt_pk_bf16_f32 v5, v6, v7
	v_cvt_pk_bf16_f32 v20, v20, v21
	v_cvt_pk_bf16_f32 v21, v22, v23
	flat_store_dwordx2 v[100:101], v[4:5] offset:96
	v_mul_f32_e32 v4, v16, v2
	v_mul_f32_e32 v5, v17, v2
	v_mul_f32_e32 v6, v18, v2
	v_mul_f32_e32 v7, v19, v2
	flat_store_dwordx2 v[100:101], v[20:21] offset:32
	v_mul_f32_e32 v20, v32, v2
	v_mul_f32_e32 v21, v33, v2
	v_mul_f32_e32 v22, v34, v2
	v_mul_f32_e32 v23, v35, v2
	v_cvt_pk_bf16_f32 v4, v4, v5
	v_cvt_pk_bf16_f32 v5, v6, v7
	v_mul_f32_e32 v2, v1, v106
	flat_store_dwordx2 v[100:101], v[4:5] offset:112
	v_mul_f32_e32 v4, v52, v2
	v_mul_f32_e32 v5, v53, v2
	v_mul_f32_e32 v6, v54, v2
	v_mul_f32_e32 v7, v55, v2
	v_cvt_pk_bf16_f32 v4, v4, v5
	v_cvt_pk_bf16_f32 v5, v6, v7
	flat_store_dwordx2 v[100:101], v[4:5] offset:384
	v_mul_f32_e32 v4, v56, v2
	v_mul_f32_e32 v5, v57, v2
	v_mul_f32_e32 v6, v58, v2
	v_mul_f32_e32 v7, v59, v2
	v_cvt_pk_bf16_f32 v4, v4, v5
	v_cvt_pk_bf16_f32 v5, v6, v7
	flat_store_dwordx2 v[100:101], v[4:5] offset:400
	v_mul_f32_e32 v4, v60, v2
	v_mul_f32_e32 v5, v61, v2
	v_mul_f32_e32 v6, v62, v2
	v_mul_f32_e32 v7, v63, v2
	v_cvt_pk_bf16_f32 v4, v4, v5
	v_cvt_pk_bf16_f32 v5, v6, v7
	flat_store_dwordx2 v[100:101], v[4:5] offset:416
	v_mul_f32_e32 v4, v64, v2
	v_mul_f32_e32 v5, v65, v2
	v_mul_f32_e32 v6, v66, v2
	v_mul_f32_e32 v7, v67, v2
	v_cvt_pk_bf16_f32 v4, v4, v5
	v_cvt_pk_bf16_f32 v5, v6, v7
	flat_store_dwordx2 v[100:101], v[4:5] offset:432
	v_mul_f32_e32 v4, v36, v2
	v_mul_f32_e32 v5, v37, v2
	v_mul_f32_e32 v6, v38, v2
	v_mul_f32_e32 v7, v39, v2
	v_cvt_pk_bf16_f32 v4, v4, v5
	v_cvt_pk_bf16_f32 v5, v6, v7
	flat_store_dwordx2 v[100:101], v[4:5] offset:448
	v_mul_f32_e32 v4, v40, v2
	v_mul_f32_e32 v5, v41, v2
	v_mul_f32_e32 v6, v42, v2
	v_mul_f32_e32 v7, v43, v2
	v_cvt_pk_bf16_f32 v4, v4, v5
	v_cvt_pk_bf16_f32 v5, v6, v7
	flat_store_dwordx2 v[100:101], v[4:5] offset:464
	v_mul_f32_e32 v4, v44, v2
	v_mul_f32_e32 v5, v45, v2
	v_mul_f32_e32 v6, v46, v2
	v_mul_f32_e32 v7, v47, v2
	v_cvt_pk_bf16_f32 v4, v4, v5
	v_cvt_pk_bf16_f32 v5, v6, v7
	flat_store_dwordx2 v[100:101], v[4:5] offset:480
	v_mul_f32_e32 v4, v48, v2
	v_mul_f32_e32 v5, v49, v2
	v_mul_f32_e32 v6, v50, v2
	v_mul_f32_e32 v7, v51, v2
	v_cvt_pk_bf16_f32 v4, v4, v5
	v_cvt_pk_bf16_f32 v5, v6, v7
	v_mul_f32_e32 v2, v103, v106
	flat_store_dwordx2 v[100:101], v[4:5] offset:496
	v_mul_f32_e32 v4, v84, v2
	v_mul_f32_e32 v5, v85, v2
	v_mul_f32_e32 v6, v86, v2
	v_mul_f32_e32 v7, v87, v2
	v_cvt_pk_bf16_f32 v4, v4, v5
	v_cvt_pk_bf16_f32 v5, v6, v7
	flat_store_dwordx2 v[100:101], v[4:5] offset:768
	v_mul_f32_e32 v4, v88, v2
	v_mul_f32_e32 v5, v89, v2
	v_mul_f32_e32 v6, v90, v2
	v_mul_f32_e32 v7, v91, v2
	v_cvt_pk_bf16_f32 v4, v4, v5
	v_cvt_pk_bf16_f32 v5, v6, v7
	flat_store_dwordx2 v[100:101], v[4:5] offset:784
	v_mul_f32_e32 v4, v92, v2
	v_mul_f32_e32 v5, v93, v2
	v_mul_f32_e32 v6, v94, v2
	v_mul_f32_e32 v7, v95, v2
	v_cvt_pk_bf16_f32 v4, v4, v5
	v_cvt_pk_bf16_f32 v5, v6, v7
	flat_store_dwordx2 v[100:101], v[4:5] offset:800
	v_mul_f32_e32 v4, v96, v2
	v_mul_f32_e32 v5, v97, v2
	v_mul_f32_e32 v6, v98, v2
	v_mul_f32_e32 v7, v99, v2
	v_cvt_pk_bf16_f32 v4, v4, v5
	v_cvt_pk_bf16_f32 v5, v6, v7
	flat_store_dwordx2 v[100:101], v[4:5] offset:816
	v_mul_f32_e32 v4, v68, v2
	v_mul_f32_e32 v5, v69, v2
	v_mul_f32_e32 v6, v70, v2
	v_mul_f32_e32 v7, v71, v2
	v_cvt_pk_bf16_f32 v4, v4, v5
	v_cvt_pk_bf16_f32 v5, v6, v7
	flat_store_dwordx2 v[100:101], v[4:5] offset:832
	v_mul_f32_e32 v4, v72, v2
	v_mul_f32_e32 v5, v73, v2
	v_mul_f32_e32 v6, v74, v2
	v_mul_f32_e32 v7, v75, v2
	v_cvt_pk_bf16_f32 v4, v4, v5
	v_cvt_pk_bf16_f32 v5, v6, v7
	flat_store_dwordx2 v[100:101], v[4:5] offset:848
	v_mul_f32_e32 v4, v76, v2
	v_mul_f32_e32 v5, v77, v2
	v_mul_f32_e32 v6, v78, v2
	v_mul_f32_e32 v7, v79, v2
	v_cvt_pk_bf16_f32 v4, v4, v5
	v_cvt_pk_bf16_f32 v5, v6, v7
	flat_store_dwordx2 v[100:101], v[4:5] offset:864
	v_mul_f32_e32 v4, v80, v2
	v_mul_f32_e32 v5, v81, v2
	v_mul_f32_e32 v6, v82, v2
	v_mul_f32_e32 v7, v83, v2
	v_cvt_pk_bf16_f32 v20, v20, v21
	v_cvt_pk_bf16_f32 v21, v22, v23
	v_cvt_pk_bf16_f32 v4, v4, v5
	v_cvt_pk_bf16_f32 v5, v6, v7
	s_mov_b64 s[14:15], 0
	flat_store_dwordx2 v[100:101], v[20:21] offset:48
	flat_store_dwordx2 v[100:101], v[4:5] offset:880

; #define LAS __attribute__((address_space(3)))
; #define MFMA32(a, b, c) __builtin_amdgcn_mfma_f32_32x32x16_bf16((a), (b), (c), 0, 0, 0)
; __device__ __forceinline__ size_t vtb_off(int b, int hs, int kb) { return ((size_t)(b * NHS + hs) * VTB_KB + kb) * 4096; }
; template <int K> __device__ __forceinline__ int xor_now(int x) { if (K != 0) asm volatile("v_xor_b32 %0, %1, %0" : "+v"(x) : "n"(K)); return x; }
; #define VMW(n) asm volatile("s_waitcnt vmcnt(" #n ")" ::: "memory")
; template <int NDT, class F, class It, class Pre>
; __device__ __forceinline__ void att_stream(const bf16x8 (&qf)[4], const WvStream& st, LAS unsigned char* ring, F& f, It& it, Pre& pre, int hh, f32x16 (&o)[NDT], float& m, float& l) {
;     ...
;     int t0 = it.next(); if (t0 < 0) return;
;     int t1 = it.next(), t2 = t1 >= 0 ? it.next() : -1, t3 = t2 >= 0 ? it.next() : -1;
;     st.dma_k(t0, ring); if (t1 >= 0) st.dma_k(t1, ring + 8192); st.dma_v(t0, ring);
;     if (t1 >= 0) VMW(8); else VMW(4);
;     f32x16 s;
; #pragma unroll
;     for (int ks = 0; ks < 4; ++ks) { const bf16x8 kf = *(const LAS bf16x8*)(ring + (ks == 0 ? st.fk : ks == 1 ? xor_now<32>(st.fk) : ks == 2 ? xor_now<64>(st.fk) : xor_now<96>(st.fk))); s = MFMA32(kf, qf[ks], ks == 0 ? f.cv : s); }
;     if (t2 >= 0) st.dma_k(t2, ring);
; __device__ __forceinline__ void dil_item_mfma(const bf16* PROJ, const unsigned char* VTB, bf16* O, LAS unsigned char* ring  , int bj, int r16, int qt8, int lane) {
;     ...
;     for (int g = 0; g < 3; ++g) { const int head = 3 * g + j, d = g == 0 ? 1 : (g == 1 ? 4 : 16), seg = SEQ / d, rd = r16 % d;
;         DilBias f; f.setup(__builtin_amdgcn_exp2f(-8.f * (float)(head + 1) / 9.f) * LOG2E * (float)d, hh); f.iq = tq / d;
;         const int imin = (r16 + 16 * (qt8 * 32)) / d, imax = (r16 + 16 * (qt8 * 32 + 31)) / d;
;         const int kt0 = imin >= 128 ? (imin - 128) >> 5 : 0, kt1 = imax >> 5;
;         bf16x8 qf[4]; load_qfrag(PROJ + row * NINP + C_DILQ + head * 64 + 8 * hh, qf);
;         WvStream st; st.setup(PROJ + ((size_t)b * SEQ + rd) * NINP + C_DILK + head * 64, (size_t)d * NINP * 2, VTB + vtb_off(b, 11 + head, rd * (seg >> 5)), lane);
;         zero_ot<2>(o[g]); m[g] = NEG_BIG; l[g] = 0.f;
;         RangeIt it; it.kt = kt1; it.kt0 = kt0; RangePre<DilBias> pre{f};
;         att_stream<2>(qf, st, ring, f, it, pre, hh, o[g], m[g], l[g]);
.LBB0_767:
	s_add_i32 s40, s30, -2
	s_cmp_ge_i32 s40, s13
	s_cselect_b64 s[36:37], -1, 0
	s_and_b64 s[36:37], s[20:21], s[36:37]
	s_and_b64 s[36:37], s[36:37], exec
	s_cselect_b32 s57, s40, -1
	s_cmp_gt_i32 s57, -1
	s_cselect_b64 s[36:37], -1, 0
	s_add_i32 s41, s48, 1
	v_cvt_f32_i32_e32 v5, s41
	s_cmp_lt_i32 s57, 0
	v_mul_f32_e32 v5, 0xc1000000, v5
	v_div_scale_f32 v6, s[60:61], s90, s90, v5
	v_rcp_f32_e32 v7, v6
	s_nop 0
	v_fma_f32 v8, -v6, v7, 1.0
	v_fmac_f32_e32 v7, v8, v7
	v_div_scale_f32 v8, vcc, v5, s90, v5
	v_mul_f32_e32 v9, v8, v7
	v_fma_f32 v10, -v6, v9, v8
	v_fmac_f32_e32 v9, v10, v7
	v_fma_f32 v6, -v6, v9, v8
	v_div_fmas_f32 v6, v6, v7, v9
	v_div_fixup_f32 v5, v6, s90, v5
	v_exp_f32_e32 v5, v5
	v_lshlrev_b32_e32 v7, 2, v4
	v_or_b32_e32 v9, 1, v7
	v_or_b32_e32 v4, 3, v7
	v_or_b32_e32 v8, 2, v7
	v_add_u32_e32 v10, 8, v7
	v_add_u32_e32 v11, 9, v7
	v_add_u32_e32 v12, 10, v7
	v_add_u32_e32 v13, 11, v7
	v_add_u32_e32 v14, 16, v7
	v_add_u32_e32 v15, 17, v7
	v_add_u32_e32 v16, 18, v7
	v_add_u32_e32 v17, 19, v7
	v_add_u32_e32 v18, 24, v7
	v_add_u32_e32 v19, 25, v7
	v_add_u32_e32 v20, 26, v7
	v_add_u32_e32 v21, 27, v7
	v_mul_f32_e32 v108, 0x3fb8aa3b, v5
	v_cvt_f32_i32_e32 v5, v4
	v_cvt_f32_i32_e32 v4, v8
	v_cvt_f32_i32_e32 v8, v7
	v_cvt_f32_i32_e32 v9, v9
	v_cvt_f32_i32_e32 v11, v11
	v_cvt_f32_i32_e32 v10, v10
	v_cvt_f32_i32_e32 v13, v13
	v_cvt_f32_i32_e32 v12, v12
	v_cvt_f32_i32_e32 v15, v15
	v_cvt_f32_i32_e32 v14, v14
	v_cvt_f32_i32_e32 v17, v17
	v_cvt_f32_i32_e32 v16, v16
	v_cvt_f32_i32_e32 v19, v19
	v_cvt_f32_i32_e32 v18, v18
	v_cvt_f32_i32_e32 v21, v21
	v_cvt_f32_i32_e32 v20, v20
	v_mul_f32_e32 v6, 0x40b17218, v108
	v_mul_f32_e32 v48, v6, v18
	v_mul_f32_e32 v49, v6, v19
	v_mul_f32_e32 v46, v6, v16
	v_mul_f32_e32 v47, v6, v17
	v_mul_f32_e32 v50, v6, v20
	v_mul_f32_e32 v51, v6, v21
	v_mul_f32_e32 v44, v6, v14
	v_mul_f32_e32 v45, v6, v15
	v_mul_f32_e32 v42, v6, v12
	v_mul_f32_e32 v43, v6, v13
	v_mul_f32_e32 v40, v6, v10
	v_mul_f32_e32 v41, v6, v11
	v_mul_f32_e32 v38, v6, v4
	v_mul_f32_e32 v39, v6, v5
	v_mul_f32_e32 v36, v6, v8
	v_mul_f32_e32 v37, v6, v9
	v_and_b32_e32 v4, 31, v1
	v_ashrrev_i32_e32 v5, 5, v1
	v_lshrrev_b32_e32 v7, 1, v1
	v_lshlrev_b32_e32 v6, 7, v4
	v_bitop3_b32 v7, v7, v5, 7 bitop3:0x6c
	v_lshl_add_u32 v109, v7, 4, v6
	v_add_u32_e32 v6, s46, v109
	ds_read_b128 v[6:9], v6
	s_waitcnt vmcnt(0) lgkmcnt(0)
	v_mfma_f32_32x32x16_bf16 v[68:83], v[6:9], v[84:87], v[36:51]
	v_mov_b32_e32 v6, v109
	v_xor_b32 v6, 32, v6
	s_nop 0
	v_add_u32_e32 v6, s46, v6
	ds_read_b128 v[6:9], v6
	s_waitcnt lgkmcnt(0)
	v_mfma_f32_32x32x16_bf16 v[68:83], v[6:9], v[88:91], v[68:83]
	v_mov_b32_e32 v6, v109
	v_xor_b32 v6, 64, v6
	s_nop 0
	v_add_u32_e32 v6, s46, v6
	ds_read_b128 v[6:9], v6
	s_waitcnt lgkmcnt(0)
	v_mfma_f32_32x32x16_bf16 v[68:83], v[6:9], v[92:95], v[68:83]
	v_mov_b32_e32 v6, v109
	v_xor_b32 v6, 0x60, v6
	s_nop 0
	v_add_u32_e32 v6, s46, v6
	ds_read_b128 v[6:9], v6
	s_waitcnt lgkmcnt(0)
	v_mfma_f32_32x32x16_bf16 v[68:83], v[6:9], v[96:99], v[68:83]
	s_cbranch_scc1 .LBB0_769
	s_mul_i32 s59, s57, 0x60000
	s_mul_hi_u32 s41, s57, 0x60000
	s_add_u32 s60, s33, s59
	s_addc_u32 s61, s54, s41
	s_mov_b64 s[62:63], s[60:61]
	s_mov_b32 m0, s46
	v_lshl_add_u64 v[6:7], s[62:63], 0, v[100:101]
	s_add_u32 s62, s60, 0x18000
	s_addc_u32 s63, s61, 0
	global_load_lds_dwordx4 v[6:7], off
	s_mov_b32 m0, s58
	s_add_u32 s58, s60, 0x30000
	v_mov_b32_e32 v6, v100
	s_addc_u32 s59, s61, 0
	v_xor_b32 v6, 64, v6
	s_nop 0
	global_load_lds_dwordx4 v6, s[62:63]
	s_mov_b32 m0, s8
	v_lshl_add_u64 v[6:7], s[58:59], 0, v[100:101]
	s_add_u32 s58, s60, 0x48000
	global_load_lds_dwordx4 v[6:7], off
	s_addc_u32 s59, s61, 0
	v_mov_b32_e32 v6, v100
	s_mov_b32 m0, s31
	v_xor_b32 v6, 64, v6
	s_nop 0
	global_load_lds_dwordx4 v6, s[58:59]

; template <int NDT, class F>
; __device__ __forceinline__ void softmax_body(f32x16& s, const F& f, int k0, int hh, f32x16 (&o)[NDT], float& m, float& l, bf16x8& pf0, bf16x8& pf1, const int MASK) {
;     ...
;     const float me = fmaxf(m, -1e29f);
;     const float off = on ? f.tadd - me : NEG_BIG;
;     const f32x2_t sc2 = {QK_SCL, QK_SCL}, of2 = {off, off}; f32x2_t ps2 = {0.f, 0.f};
; #pragma unroll
;     for (int r = 0; r < 16; r += 2) { f32x2_t a = {s[r], s[r + 1]}; a = __builtin_elementwise_fma(a, sc2, of2);
;         f32x2_t p; p.x = __builtin_amdgcn_exp2f(a.x); p.y = __builtin_amdgcn_exp2f(a.y); s[r] = p.x; s[r + 1] = p.y; ps2 += p; }
.LBB0_782:
	v_max_f32_e32 v82, v1, v1
	v_max_f32_e32 v82, 0xefa18f08, v82
	v_sub_f32_e32 v104, v104, v82
	v_fma_f32 v68, v68, s34, v104
	v_fma_f32 v69, v69, s34, v104
	s_cmp_gt_i32 s57, -1
	v_exp_f32_e32 v82, v68
	v_exp_f32_e32 v83, v69
	s_cselect_b64 s[36:37], -1, 0
	s_cmp_lt_i32 s57, 0
	s_mov_b64 s[40:41], -1
	v_cvt_pk_bf16_f32 v69, v82, v83
	s_cbranch_scc0 .LBB0_792
	s_cmp_lt_i32 s18, 0
	s_cbranch_scc0 .LBB0_789
	s_and_b64 vcc, exec, s[20:21]
	s_cbranch_vccz .LBB0_786
	v_mov_b32_e32 v68, v69
	s_waitcnt vmcnt(0)
	s_mov_b64 s[40:41], 0

; #define LAS __attribute__((address_space(3)))
; #define MFMA32(a, b, c) __builtin_amdgcn_mfma_f32_32x32x16_bf16((a), (b), (c), 0, 0, 0)
; template <int NDT, class F>
; __device__ __forceinline__ void softmax_body(f32x16& s, const F& f, int k0, int hh, f32x16 (&o)[NDT], float& m, float& l, bf16x8& pf0, bf16x8& pf1, const int MASK) {
;     ...
;     const float me = fmaxf(m, -1e29f);
;     const float off = on ? f.tadd - me : NEG_BIG;
;     const f32x2_t sc2 = {QK_SCL, QK_SCL}, of2 = {off, off}; f32x2_t ps2 = {0.f, 0.f};
; #pragma unroll
;     for (int r = 0; r < 16; r += 2) { f32x2_t a = {s[r], s[r + 1]}; a = __builtin_elementwise_fma(a, sc2, of2);
;         f32x2_t p; p.x = __builtin_amdgcn_exp2f(a.x); p.y = __builtin_amdgcn_exp2f(a.y); s[r] = p.x; s[r + 1] = p.y; ps2 += p; }
;     l += ps2.x + ps2.y;
; template <int NDT, class F>
; __device__ __forceinline__ void stream_tile(const bf16x8 (&qf)[4], const WvStream& st, LAS unsigned char* cur, LAS unsigned char* nxt, const F& f, f32x16& s, int t0, int t1, int t2, int t3, int hh, f32x16 (&o)[NDT], float& m, float& l, int msk) {
;     f32x16 sn;
;     if (t1 >= 0) {
;         if (t2 >= 0) VMW(12); else VMW(8);
; #pragma unroll
;         for (int ks = 0; ks < 4; ++ks) { const bf16x8 kf = *(const LAS bf16x8*)(nxt + (ks == 0 ? st.fk : ks == 1 ? xor_now<32>(st.fk) : ks == 2 ? xor_now<64>(st.fk) : xor_now<96>(st.fk))); sn = MFMA32(kf, qf[ks], ks == 0 ? f.cv : sn); }
;         if (t3 >= 0) st.dma_k(t3, nxt);
;         __builtin_amdgcn_sched_barrier(0);
;     }
;     bf16x8 pf0, pf1; softmax_body<NDT>(s, f, 32 * t0, hh, o, m, l, pf0, pf1, msk);
;     v4u tie = __builtin_bit_cast(v4u, pf0);
;     if (t3 >= 0) asm volatile("s_waitcnt vmcnt(12)" : "+v"(tie.x) :: "memory");
;     else if (t2 >= 0) asm volatile("s_waitcnt vmcnt(8)" : "+v"(tie.x) :: "memory");
;     else if (t1 >= 0) asm volatile("s_waitcnt vmcnt(4)" : "+v"(tie.x) :: "memory");
;     else asm volatile("s_waitcnt vmcnt(0)" : "+v"(tie.x) :: "memory");
;     pf0 = __builtin_bit_cast(bf16x8, tie);
; #pragma unroll
;     for (int dt = 0; dt < NDT; ++dt) { const bf16x8 vf0 = *(const LAS bf16x8*)(cur + dt * 2048 + st.fv), vf1 = *(const LAS bf16x8*)(cur + dt * 2048 + xor_now<32>(st.fv));
;         o[dt] = MFMA32(vf0, pf0, o[dt]); o[dt] = MFMA32(vf1, pf1, o[dt]); }
;     if (t2 >= 0) st.dma_v(t2, cur);
;     s = sn;
.LBB0_794:
	s_lshl_b32 s20, s60, 13
	s_add_i32 s20, s46, s20
	v_add_u32_e32 v113, s20, v110
	v_mov_b32_e32 v105, v104
	ds_read_b128 v[114:117], v113 offset:4096
	v_fma_f32 v70, v70, s34, v104
	v_fma_f32 v71, v71, s34, v105
	v_mov_b32_e32 v118, v111
	v_exp_f32_e32 v106, v70
	v_exp_f32_e32 v107, v71
	v_fma_f32 v70, v102, s34, v104
	v_fma_f32 v71, v103, s34, v105
	v_xor_b32 v118, 32, v118
	v_fma_f32 v72, v72, s34, v104
	v_fma_f32 v73, v73, s34, v105
	v_exp_f32_e32 v102, v70
	v_exp_f32_e32 v103, v71
	v_fma_f32 v70, v74, s34, v104
	v_fma_f32 v71, v75, s34, v105
	v_add_u32_e32 v118, s20, v118
	v_exp_f32_e32 v74, v70
	v_exp_f32_e32 v75, v71
	v_fma_f32 v70, v76, s34, v104
	v_fma_f32 v71, v77, s34, v105
	v_cvt_pk_bf16_f32 v69, v106, v107
	v_exp_f32_e32 v76, v70
	v_exp_f32_e32 v77, v71
	v_fma_f32 v70, v78, s34, v104
	v_fma_f32 v71, v79, s34, v105
	ds_read_b128 v[118:121], v118
	v_exp_f32_e32 v78, v70
	v_exp_f32_e32 v79, v71
	v_fma_f32 v70, v80, s34, v104
	v_fma_f32 v71, v81, s34, v105
	v_exp_f32_e32 v72, v72
	v_exp_f32_e32 v80, v70
	v_exp_f32_e32 v81, v71
	v_cvt_pk_bf16_f32 v70, v102, v103
	v_cvt_pk_bf16_f32 v71, v74, v75
	v_exp_f32_e32 v73, v73
	v_mov_b32_e32 v104, v111
	s_waitcnt lgkmcnt(0)
	v_mfma_f32_32x32x16_bf16 v[20:35], v[114:117], v[68:71], v[20:35]
	v_cvt_pk_bf16_f32 v114, v76, v77
	v_cvt_pk_bf16_f32 v115, v78, v79
	v_cvt_pk_bf16_f32 v116, v80, v81
	v_cvt_pk_bf16_f32 v117, v72, v73
	s_cmp_lt_i32 s18, 0
	s_nop 0
	v_mfma_f32_32x32x16_bf16 v[20:35], v[118:121], v[114:117], v[20:35]
	ds_read_b128 v[118:121], v113 offset:6144
	v_xor_b32 v104, 32, v104
	s_nop 0
	v_add_u32_e32 v104, s20, v104
	s_waitcnt lgkmcnt(0)
	v_mfma_f32_32x32x16_bf16 v[4:19], v[118:121], v[68:71], v[4:19]
	ds_read_b128 v[68:71], v104 offset:2048
	s_waitcnt lgkmcnt(0)
	v_mfma_f32_32x32x16_bf16 v[4:19], v[68:71], v[114:117], v[4:19]
	s_cbranch_scc1 .LBB0_796
	s_lshl_b64 s[40:41], s[18:19], 12
	s_add_u32 s40, s55, s40
	s_addc_u32 s41, s56, s41
	s_mov_b64 s[60:61], s[40:41]
	s_add_i32 m0, s20, 0x1000
	s_nop 0
	v_lshl_add_u64 v[68:69], s[60:61], 0, v[2:3]
	s_add_u32 s60, s40, 0x400
	s_addc_u32 s61, s41, 0
	global_load_lds_dwordx4 v[68:69], off
	s_add_i32 m0, s20, 0x1400
	v_lshl_add_u64 v[68:69], s[60:61], 0, v[2:3]
	s_add_u32 s60, s40, 0x800
	global_load_lds_dwordx4 v[68:69], off
	s_addc_u32 s61, s41, 0
	s_add_i32 m0, s20, 0x1800
	s_add_u32 s40, s40, 0xc00
	s_addc_u32 s41, s41, 0
	v_lshl_add_u64 v[68:69], s[60:61], 0, v[2:3]
	global_load_lds_dwordx4 v[68:69], off
	s_add_i32 m0, s20, 0x1c00
	v_lshl_add_u64 v[68:69], s[40:41], 0, v[2:3]
	global_load_lds_dwordx4 v[68:69], off
.LBB0_796:
	v_pk_add_f32 v[68:69], v[82:83], 0 op_sel_hi:[1,0]
	s_cmp_ge_i32 s31, s13
	v_add_f32_e32 v68, v106, v68
	v_add_f32_e32 v69, v107, v69
	s_cselect_b64 s[40:41], -1, 0
	v_add_f32_e32 v68, v102, v68
	v_add_f32_e32 v69, v103, v69
	s_nop 0
	v_add_f32_e32 v68, v74, v68
	v_add_f32_e32 v69, v75, v69
	s_nop 0
	v_add_f32_e32 v68, v76, v68
	v_add_f32_e32 v69, v77, v69
	s_nop 0
	v_add_f32_e32 v68, v78, v68
	v_add_f32_e32 v69, v79, v69
	s_nop 0
	v_add_f32_e32 v68, v80, v68
	v_add_f32_e32 v69, v81, v69
	s_nop 0
	v_add_f32_e32 v68, v72, v68
	v_add_f32_e32 v69, v73, v69
	s_nop 0
	v_add_f32_e32 v68, v68, v69
	v_cndmask_b32_e64 v69, 0, 1, s[36:37]
	s_and_b64 s[36:37], s[36:37], s[40:41]
	v_readfirstlane_b32 s20, v69
	s_sub_i32 s21, s31, s20
	s_and_b64 s[36:37], s[36:37], exec
	s_cselect_b32 s20, s31, -1
	s_cmp_gt_i32 s58, -1
	v_add_f32_e32 v168, v168, v68
	s_cbranch_scc0 .LBB0_799
	v_mov_b64_e32 v[82:83], v[66:67]
	s_mov_b32 s31, s21
	v_mov_b64_e32 v[80:81], v[64:65]
	v_mov_b64_e32 v[78:79], v[62:63]
	v_mov_b64_e32 v[76:77], v[60:61]
	v_mov_b64_e32 v[74:75], v[58:59]
	v_mov_b64_e32 v[72:73], v[56:57]
	v_mov_b64_e32 v[70:71], v[54:55]
	v_mov_b64_e32 v[68:69], v[52:53]
	s_mov_b32 s60, s59
	s_mov_b32 s30, s58
	s_branch .LBB0_772

; #define LAS __attribute__((address_space(3)))
; #define MFMA32(a, b, c) __builtin_amdgcn_mfma_f32_32x32x16_bf16((a), (b), (c), 0, 0, 0)
; __device__ __forceinline__ size_t vtb_off(int b, int hs, int kb) { return ((size_t)(b * NHS + hs) * VTB_KB + kb) * 4096; }
; template <int K> __device__ __forceinline__ int xor_now(int x) { if (K != 0) asm volatile("v_xor_b32 %0, %1, %0" : "+v"(x) : "n"(K)); return x; }
; #define VMW(n) asm volatile("s_waitcnt vmcnt(" #n ")" ::: "memory")
; template <int NDT, class F, class It, class Pre>
; __device__ __forceinline__ void att_stream(const bf16x8 (&qf)[4], const WvStream& st, LAS unsigned char* ring, F& f, It& it, Pre& pre, int hh, f32x16 (&o)[NDT], float& m, float& l) {
;     ...
;     int t0 = it.next(); if (t0 < 0) return;
;     int t1 = it.next(), t2 = t1 >= 0 ? it.next() : -1, t3 = t2 >= 0 ? it.next() : -1;
;     st.dma_k(t0, ring); if (t1 >= 0) st.dma_k(t1, ring + 8192); st.dma_v(t0, ring);
;     if (t1 >= 0) VMW(8); else VMW(4);
;     f32x16 s;
; #pragma unroll
;     for (int ks = 0; ks < 4; ++ks) { const bf16x8 kf = *(const LAS bf16x8*)(ring + (ks == 0 ? st.fk : ks == 1 ? xor_now<32>(st.fk) : ks == 2 ? xor_now<64>(st.fk) : xor_now<96>(st.fk))); s = MFMA32(kf, qf[ks], ks == 0 ? f.cv : s); }
;     if (t2 >= 0) st.dma_k(t2, ring);
; __device__ __forceinline__ void dil_item_mfma(const bf16* PROJ, const unsigned char* VTB, bf16* O, LAS unsigned char* ring  , int bj, int r16, int qt8, int lane) {
;     ...
;     for (int g = 0; g < 3; ++g) { const int head = 3 * g + j, d = g == 0 ? 1 : (g == 1 ? 4 : 16), seg = SEQ / d, rd = r16 % d;
;         DilBias f; f.setup(__builtin_amdgcn_exp2f(-8.f * (float)(head + 1) / 9.f) * LOG2E * (float)d, hh); f.iq = tq / d;
;         const int imin = (r16 + 16 * (qt8 * 32)) / d, imax = (r16 + 16 * (qt8 * 32 + 31)) / d;
;         const int kt0 = imin >= 128 ? (imin - 128) >> 5 : 0, kt1 = imax >> 5;
;         bf16x8 qf[4]; load_qfrag(PROJ + row * NINP + C_DILQ + head * 64 + 8 * hh, qf);
;         WvStream st; st.setup(PROJ + ((size_t)b * SEQ + rd) * NINP + C_DILK + head * 64, (size_t)d * NINP * 2, VTB + vtb_off(b, 11 + head, rd * (seg >> 5)), lane);
;         zero_ot<2>(o[g]); m[g] = NEG_BIG; l[g] = 0.f;
;         RangeIt it; it.kt = kt1; it.kt0 = kt0; RangePre<DilBias> pre{f};
;         att_stream<2>(qf, st, ring, f, it, pre, hh, o[g], m[g], l[g]);
.LBB0_806:
	s_add_i32 s37, s30, -2
	s_cmp_ge_i32 s37, s13
	s_cselect_b64 s[24:25], -1, 0
	s_and_b64 s[24:25], s[20:21], s[24:25]
	s_and_b64 s[24:25], s[24:25], exec
	s_cselect_b32 s55, s37, -1
	s_cmp_gt_i32 s55, -1
	s_cselect_b64 s[24:25], -1, 0
	s_add_i32 s40, s48, 4
	v_cvt_f32_u32_e32 v38, s40
	v_lshlrev_b32_e32 v37, 2, v37
	v_add_u32_e32 v44, 8, v37
	v_add_u32_e32 v45, 9, v37
	v_mul_f32_e32 v38, 0xc1000000, v38
	v_div_scale_f32 v39, s[40:41], s90, s90, v38
	v_rcp_f32_e32 v40, v39
	v_add_u32_e32 v46, 10, v37
	v_add_u32_e32 v47, 11, v37
	v_add_u32_e32 v48, 16, v37
	v_fma_f32 v41, -v39, v40, 1.0
	v_fmac_f32_e32 v40, v41, v40
	v_div_scale_f32 v41, vcc, v38, s90, v38
	v_mul_f32_e32 v42, v41, v40
	v_fma_f32 v43, -v39, v42, v41
	v_fmac_f32_e32 v42, v43, v40
	v_fma_f32 v39, -v39, v42, v41
	v_div_fmas_f32 v39, v39, v40, v42
	v_div_fixup_f32 v38, v39, s90, v38
	v_exp_f32_e32 v38, v38
	v_or_b32_e32 v39, 1, v37
	v_or_b32_e32 v40, 3, v37
	v_or_b32_e32 v42, 2, v37
	v_add_u32_e32 v49, 17, v37
	v_add_u32_e32 v50, 18, v37
	v_add_u32_e32 v51, 19, v37
	v_add_u32_e32 v52, 24, v37
	v_add_u32_e32 v53, 25, v37
	v_add_u32_e32 v54, 26, v37
	v_add_u32_e32 v55, 27, v37
	v_cvt_f32_i32_e32 v41, v40
	v_cvt_f32_i32_e32 v40, v42
	v_cvt_f32_i32_e32 v42, v37
	v_cvt_f32_i32_e32 v43, v39
	v_cvt_f32_i32_e32 v45, v45
	v_cvt_f32_i32_e32 v44, v44
	v_cvt_f32_i32_e32 v47, v47
	v_cvt_f32_i32_e32 v46, v46
	v_cvt_f32_i32_e32 v49, v49
	v_cvt_f32_i32_e32 v48, v48
	v_cvt_f32_i32_e32 v51, v51
	v_cvt_f32_i32_e32 v50, v50
	v_cvt_f32_i32_e32 v53, v53
	v_cvt_f32_i32_e32 v52, v52
	v_cvt_f32_i32_e32 v55, v55
	v_cvt_f32_i32_e32 v54, v54
	v_mul_f32_e32 v38, 0x3fb8aa3b, v38
	v_mul_f32_e32 v143, 4.0, v38
	v_mul_f32_e32 v38, 0x40b17218, v143
	v_mul_f32_e32 v82, v38, v54
	v_mul_f32_e32 v83, v38, v55
	v_mul_f32_e32 v80, v38, v52
	v_mul_f32_e32 v81, v38, v53
	v_mul_f32_e32 v78, v38, v50
	v_mul_f32_e32 v79, v38, v51
	v_mul_f32_e32 v76, v38, v48
	v_mul_f32_e32 v77, v38, v49
	v_mul_f32_e32 v74, v38, v46
	v_mul_f32_e32 v75, v38, v47
	v_mul_f32_e32 v72, v38, v44
	v_mul_f32_e32 v73, v38, v45
	v_mul_f32_e32 v70, v38, v40
	v_mul_f32_e32 v71, v38, v41
	v_mul_f32_e32 v68, v38, v42
	v_mul_f32_e32 v69, v38, v43
	v_and_b32_e32 v37, 31, v36
	v_ashrrev_i32_e32 v38, 5, v36
	v_lshrrev_b32_e32 v40, 1, v36
	v_lshlrev_b32_e32 v39, 7, v37
	v_bitop3_b32 v40, v40, v38, 7 bitop3:0x6c
	v_lshl_add_u32 v144, v40, 4, v39
	v_add_u32_e32 v39, s46, v144
	ds_read_b128 v[40:43], v39
	v_mov_b32_e32 v39, v144
	v_xor_b32 v39, 32, v39
	s_waitcnt vmcnt(0) lgkmcnt(0)
	v_mfma_f32_32x32x16_bf16 v[100:115], v[40:43], v[116:119], v[68:83]
	v_add_u32_e32 v39, s46, v39
	ds_read_b128 v[40:43], v39
	v_mov_b32_e32 v39, v144
	v_xor_b32 v39, 64, v39
	s_cmp_lt_i32 s55, 0
	v_add_u32_e32 v39, s46, v39
	s_waitcnt lgkmcnt(0)
	v_mfma_f32_32x32x16_bf16 v[100:115], v[40:43], v[120:123], v[100:115]
	ds_read_b128 v[40:43], v39
	v_mov_b32_e32 v39, v144
	v_xor_b32 v39, 0x60, v39
	s_nop 0
	v_add_u32_e32 v39, s46, v39
	s_waitcnt lgkmcnt(0)
	v_mfma_f32_32x32x16_bf16 v[100:115], v[40:43], v[124:127], v[100:115]
	ds_read_b128 v[40:43], v39
	s_waitcnt lgkmcnt(0)
	v_mfma_f32_32x32x16_bf16 v[100:115], v[40:43], v[128:131], v[100:115]
	s_cbranch_scc1 .LBB0_808
	s_mul_i32 s40, s55, 0x180000
	s_mul_hi_u32 s41, s55, 0x180000
	s_add_u32 s40, s4, s40
	s_addc_u32 s41, s23, s41
	s_mov_b64 s[56:57], s[40:41]
	s_mov_b32 m0, s46
	v_lshl_add_u64 v[40:41], s[56:57], 0, v[134:135]
	s_add_u32 s56, s40, 0x60000
	s_addc_u32 s57, s41, 0
	global_load_lds_dwordx4 v[40:41], off
	v_mov_b32_e32 v39, v134
	s_mov_b32 m0, s36
	v_xor_b32 v39, 64, v39
	s_nop 0
	global_load_lds_dwordx4 v39, s[56:57]
	s_add_u32 s56, s40, 0xc0000
	s_addc_u32 s57, s41, 0
	s_mov_b32 m0, s8
	v_lshl_add_u64 v[40:41], s[56:57], 0, v[134:135]
	s_add_u32 s40, s40, 0x120000
	global_load_lds_dwordx4 v[40:41], off
	s_addc_u32 s41, s41, 0
	v_mov_b32_e32 v39, v134
	s_mov_b32 m0, s31
	v_xor_b32 v39, 64, v39
	s_nop 0
	global_load_lds_dwordx4 v39, s[40:41]

; template <int NDT, class F>
; __device__ __forceinline__ void softmax_body(f32x16& s, const F& f, int k0, int hh, f32x16 (&o)[NDT], float& m, float& l, bf16x8& pf0, bf16x8& pf1, const int MASK) {
;     ...
;     const float me = fmaxf(m, -1e29f);
;     const float off = on ? f.tadd - me : NEG_BIG;
;     const f32x2_t sc2 = {QK_SCL, QK_SCL}, of2 = {off, off}; f32x2_t ps2 = {0.f, 0.f};
; #pragma unroll
;     for (int r = 0; r < 16; r += 2) { f32x2_t a = {s[r], s[r + 1]}; a = __builtin_elementwise_fma(a, sc2, of2);
;         f32x2_t p; p.x = __builtin_amdgcn_exp2f(a.x); p.y = __builtin_amdgcn_exp2f(a.y); s[r] = p.x; s[r + 1] = p.y; ps2 += p; }
.LBB0_821:
	v_max_f32_e32 v114, v180, v180
	v_max_f32_e32 v114, 0xefa18f08, v114
	v_sub_f32_e32 v138, v138, v114
	v_fma_f32 v100, v100, s34, v138
	v_fma_f32 v101, v101, s34, v138
	s_cmp_gt_i32 s55, -1
	v_exp_f32_e32 v114, v100
	v_exp_f32_e32 v115, v101
	s_cselect_b64 s[24:25], -1, 0
	s_mov_b64 s[36:37], -1
	s_and_b64 vcc, exec, s[24:25]
	v_cvt_pk_bf16_f32 v101, v114, v115
	s_cbranch_vccnz .LBB0_831
	s_cmp_gt_i32 s18, -1
	s_cbranch_scc1 .LBB0_828
	s_andn2_b64 vcc, exec, s[20:21]
	s_mov_b64 s[20:21], -1
	s_cbranch_vccnz .LBB0_825
	v_mov_b32_e32 v100, v101
	s_waitcnt vmcnt(0)
	s_mov_b64 s[20:21], 0

; #define LAS __attribute__((address_space(3)))
; #define MFMA32(a, b, c) __builtin_amdgcn_mfma_f32_32x32x16_bf16((a), (b), (c), 0, 0, 0)
; template <int NDT, class F>
; __device__ __forceinline__ void softmax_body(f32x16& s, const F& f, int k0, int hh, f32x16 (&o)[NDT], float& m, float& l, bf16x8& pf0, bf16x8& pf1, const int MASK) {
;     ...
;     const float me = fmaxf(m, -1e29f);
;     const float off = on ? f.tadd - me : NEG_BIG;
;     const f32x2_t sc2 = {QK_SCL, QK_SCL}, of2 = {off, off}; f32x2_t ps2 = {0.f, 0.f};
; #pragma unroll
;     for (int r = 0; r < 16; r += 2) { f32x2_t a = {s[r], s[r + 1]}; a = __builtin_elementwise_fma(a, sc2, of2);
;         f32x2_t p; p.x = __builtin_amdgcn_exp2f(a.x); p.y = __builtin_amdgcn_exp2f(a.y); s[r] = p.x; s[r + 1] = p.y; ps2 += p; }
;     l += ps2.x + ps2.y;
; template <int NDT, class F>
; __device__ __forceinline__ void stream_tile(const bf16x8 (&qf)[4], const WvStream& st, LAS unsigned char* cur, LAS unsigned char* nxt, const F& f, f32x16& s, int t0, int t1, int t2, int t3, int hh, f32x16 (&o)[NDT], float& m, float& l, int msk) {
;     f32x16 sn;
;     if (t1 >= 0) {
;         if (t2 >= 0) VMW(12); else VMW(8);
; #pragma unroll
;         for (int ks = 0; ks < 4; ++ks) { const bf16x8 kf = *(const LAS bf16x8*)(nxt + (ks == 0 ? st.fk : ks == 1 ? xor_now<32>(st.fk) : ks == 2 ? xor_now<64>(st.fk) : xor_now<96>(st.fk))); sn = MFMA32(kf, qf[ks], ks == 0 ? f.cv : sn); }
;         if (t3 >= 0) st.dma_k(t3, nxt);
;         __builtin_amdgcn_sched_barrier(0);
;     }
;     bf16x8 pf0, pf1; softmax_body<NDT>(s, f, 32 * t0, hh, o, m, l, pf0, pf1, msk);
;     v4u tie = __builtin_bit_cast(v4u, pf0);
;     if (t3 >= 0) asm volatile("s_waitcnt vmcnt(12)" : "+v"(tie.x) :: "memory");
;     else if (t2 >= 0) asm volatile("s_waitcnt vmcnt(8)" : "+v"(tie.x) :: "memory");
;     else if (t1 >= 0) asm volatile("s_waitcnt vmcnt(4)" : "+v"(tie.x) :: "memory");
;     else asm volatile("s_waitcnt vmcnt(0)" : "+v"(tie.x) :: "memory");
;     pf0 = __builtin_bit_cast(bf16x8, tie);
; #pragma unroll
;     for (int dt = 0; dt < NDT; ++dt) { const bf16x8 vf0 = *(const LAS bf16x8*)(cur + dt * 2048 + st.fv), vf1 = *(const LAS bf16x8*)(cur + dt * 2048 + xor_now<32>(st.fv));
;         o[dt] = MFMA32(vf0, pf0, o[dt]); o[dt] = MFMA32(vf1, pf1, o[dt]); }
;     if (t2 >= 0) st.dma_v(t2, cur);
;     s = sn;
.LBB0_833:
	s_lshl_b32 s20, s58, 13
	s_add_i32 s20, s46, s20
	v_add_u32_e32 v149, s20, v146
	v_mov_b32_e32 v139, v138
	ds_read_b128 v[150:153], v149 offset:4096
	v_fma_f32 v102, v102, s34, v138
	v_fma_f32 v103, v103, s34, v139
	v_mov_b32_e32 v154, v147
	v_exp_f32_e32 v140, v102
	v_exp_f32_e32 v141, v103
	v_fma_f32 v102, v136, s34, v138
	v_fma_f32 v103, v137, s34, v139
	v_xor_b32 v154, 32, v154
	v_fma_f32 v104, v104, s34, v138
	v_fma_f32 v105, v105, s34, v139
	v_exp_f32_e32 v136, v102
	v_exp_f32_e32 v137, v103
	v_fma_f32 v102, v106, s34, v138
	v_fma_f32 v103, v107, s34, v139
	v_add_u32_e32 v154, s20, v154
	v_exp_f32_e32 v106, v102
	v_exp_f32_e32 v107, v103
	v_fma_f32 v102, v108, s34, v138
	v_fma_f32 v103, v109, s34, v139
	v_cvt_pk_bf16_f32 v101, v140, v141
	v_exp_f32_e32 v108, v102
	v_exp_f32_e32 v109, v103
	v_fma_f32 v102, v110, s34, v138
	v_fma_f32 v103, v111, s34, v139
	ds_read_b128 v[154:157], v154
	v_exp_f32_e32 v110, v102
	v_exp_f32_e32 v111, v103
	v_fma_f32 v102, v112, s34, v138
	v_fma_f32 v103, v113, s34, v139
	v_exp_f32_e32 v104, v104
	v_exp_f32_e32 v112, v102
	v_exp_f32_e32 v113, v103
	v_cvt_pk_bf16_f32 v102, v136, v137
	v_cvt_pk_bf16_f32 v103, v106, v107
	v_exp_f32_e32 v105, v105
	v_mov_b32_e32 v138, v147
	s_waitcnt lgkmcnt(0)
	v_mfma_f32_32x32x16_bf16 v[52:67], v[150:153], v[100:103], v[52:67]
	v_cvt_pk_bf16_f32 v150, v108, v109
	v_cvt_pk_bf16_f32 v151, v110, v111
	v_cvt_pk_bf16_f32 v152, v112, v113
	v_cvt_pk_bf16_f32 v153, v104, v105
	s_cmp_lt_i32 s18, 0
	s_nop 0
	v_mfma_f32_32x32x16_bf16 v[52:67], v[154:157], v[150:153], v[52:67]
	ds_read_b128 v[154:157], v149 offset:6144
	v_xor_b32 v138, 32, v138
	s_nop 0
	v_add_u32_e32 v138, s20, v138
	s_waitcnt lgkmcnt(0)
	v_mfma_f32_32x32x16_bf16 v[36:51], v[154:157], v[100:103], v[36:51]
	ds_read_b128 v[100:103], v138 offset:2048
	s_waitcnt lgkmcnt(0)
	v_mfma_f32_32x32x16_bf16 v[36:51], v[100:103], v[150:153], v[36:51]
	s_cbranch_scc1 .LBB0_835
	s_lshl_b64 s[36:37], s[18:19], 12
	s_add_u32 s36, s33, s36
	s_addc_u32 s37, s54, s37
	s_mov_b64 s[40:41], s[36:37]
	s_add_i32 m0, s20, 0x1000
	s_nop 0
	v_lshl_add_u64 v[100:101], s[40:41], 0, v[2:3]
	s_add_u32 s40, s36, 0x400
	s_addc_u32 s41, s37, 0
	global_load_lds_dwordx4 v[100:101], off
	s_add_i32 m0, s20, 0x1400
	v_lshl_add_u64 v[100:101], s[40:41], 0, v[2:3]
	s_add_u32 s40, s36, 0x800
	global_load_lds_dwordx4 v[100:101], off
	s_addc_u32 s41, s37, 0
	s_add_i32 m0, s20, 0x1800
	s_add_u32 s36, s36, 0xc00
	s_addc_u32 s37, s37, 0
	v_lshl_add_u64 v[100:101], s[40:41], 0, v[2:3]
	global_load_lds_dwordx4 v[100:101], off
	s_add_i32 m0, s20, 0x1c00
	v_lshl_add_u64 v[100:101], s[36:37], 0, v[2:3]
	global_load_lds_dwordx4 v[100:101], off
.LBB0_835:
	v_pk_add_f32 v[100:101], v[114:115], 0 op_sel_hi:[1,0]
	s_cmp_ge_i32 s31, s13
	v_add_f32_e32 v100, v140, v100
	v_add_f32_e32 v101, v141, v101
	s_cselect_b64 s[36:37], -1, 0
	v_add_f32_e32 v100, v136, v100
	v_add_f32_e32 v101, v137, v101
	s_nop 0
	v_add_f32_e32 v100, v106, v100
	v_add_f32_e32 v101, v107, v101
	s_nop 0
	v_add_f32_e32 v100, v108, v100
	v_add_f32_e32 v101, v109, v101
	s_nop 0
	v_add_f32_e32 v100, v110, v100
	v_add_f32_e32 v101, v111, v101
	s_nop 0
	v_add_f32_e32 v100, v112, v100
	v_add_f32_e32 v101, v113, v101
	s_nop 0
	v_add_f32_e32 v100, v104, v100
	v_add_f32_e32 v101, v105, v101
	s_nop 0
	v_add_f32_e32 v100, v100, v101
	v_cndmask_b32_e64 v101, 0, 1, s[24:25]
	s_and_b64 s[24:25], s[24:25], s[36:37]
	v_readfirstlane_b32 s20, v101
	s_sub_i32 s21, s31, s20
	s_and_b64 s[24:25], s[24:25], exec
	s_cselect_b32 s20, s31, -1
	s_cmp_gt_i32 s56, -1
	v_add_f32_e32 v171, v171, v100
	s_cbranch_scc0 .LBB0_838
	v_mov_b64_e32 v[114:115], v[98:99]
	s_mov_b32 s31, s21
	v_mov_b64_e32 v[112:113], v[96:97]
	v_mov_b64_e32 v[110:111], v[94:95]
	v_mov_b64_e32 v[108:109], v[92:93]
	v_mov_b64_e32 v[106:107], v[90:91]
	v_mov_b64_e32 v[104:105], v[88:89]
	v_mov_b64_e32 v[102:103], v[86:87]
	v_mov_b64_e32 v[100:101], v[84:85]
	s_mov_b32 s58, s57
	s_mov_b32 s30, s56
	s_branch .LBB0_811

; #define LAS __attribute__((address_space(3)))
; #define MFMA32(a, b, c) __builtin_amdgcn_mfma_f32_32x32x16_bf16((a), (b), (c), 0, 0, 0)
; __device__ __forceinline__ size_t vtb_off(int b, int hs, int kb) { return ((size_t)(b * NHS + hs) * VTB_KB + kb) * 4096; }
; template <int K> __device__ __forceinline__ int xor_now(int x) { if (K != 0) asm volatile("v_xor_b32 %0, %1, %0" : "+v"(x) : "n"(K)); return x; }
; #define VMW(n) asm volatile("s_waitcnt vmcnt(" #n ")" ::: "memory")
; template <int NDT, class F, class It, class Pre>
; __device__ __forceinline__ void att_stream(const bf16x8 (&qf)[4], const WvStream& st, LAS unsigned char* ring, F& f, It& it, Pre& pre, int hh, f32x16 (&o)[NDT], float& m, float& l) {
;     ...
;     int t0 = it.next(); if (t0 < 0) return;
;     int t1 = it.next(), t2 = t1 >= 0 ? it.next() : -1, t3 = t2 >= 0 ? it.next() : -1;
;     st.dma_k(t0, ring); if (t1 >= 0) st.dma_k(t1, ring + 8192); st.dma_v(t0, ring);
;     if (t1 >= 0) VMW(8); else VMW(4);
;     f32x16 s;
; #pragma unroll
;     for (int ks = 0; ks < 4; ++ks) { const bf16x8 kf = *(const LAS bf16x8*)(ring + (ks == 0 ? st.fk : ks == 1 ? xor_now<32>(st.fk) : ks == 2 ? xor_now<64>(st.fk) : xor_now<96>(st.fk))); s = MFMA32(kf, qf[ks], ks == 0 ? f.cv : s); }
;     if (t2 >= 0) st.dma_k(t2, ring);
; __device__ __forceinline__ void dil_item_mfma(const bf16* PROJ, const unsigned char* VTB, bf16* O, LAS unsigned char* ring  , int bj, int r16, int qt8, int lane) {
;     ...
;     for (int g = 0; g < 3; ++g) { const int head = 3 * g + j, d = g == 0 ? 1 : (g == 1 ? 4 : 16), seg = SEQ / d, rd = r16 % d;
;         DilBias f; f.setup(__builtin_amdgcn_exp2f(-8.f * (float)(head + 1) / 9.f) * LOG2E * (float)d, hh); f.iq = tq / d;
;         const int imin = (r16 + 16 * (qt8 * 32)) / d, imax = (r16 + 16 * (qt8 * 32 + 31)) / d;
;         const int kt0 = imin >= 128 ? (imin - 128) >> 5 : 0, kt1 = imax >> 5;
;         bf16x8 qf[4]; load_qfrag(PROJ + row * NINP + C_DILQ + head * 64 + 8 * hh, qf);
;         WvStream st; st.setup(PROJ + ((size_t)b * SEQ + rd) * NINP + C_DILK + head * 64, (size_t)d * NINP * 2, VTB + vtb_off(b, 11 + head, rd * (seg >> 5)), lane);
;         zero_ot<2>(o[g]); m[g] = NEG_BIG; l[g] = 0.f;
;         RangeIt it; it.kt = kt1; it.kt0 = kt0; RangePre<DilBias> pre{f};
;         att_stream<2>(qf, st, ring, f, it, pre, hh, o[g], m[g], l[g]);
.LBB0_845:
	s_add_i32 s31, s23, -2
	s_cmp_ge_i32 s31, s4
	s_cselect_b64 s[20:21], -1, 0
	s_and_b64 s[20:21], s[16:17], s[20:21]
	s_and_b64 s[20:21], s[20:21], exec
	s_cselect_b32 s25, s31, -1
	s_cmp_gt_i32 s25, -1
	s_cselect_b64 s[20:21], -1, 0
	s_add_i32 s48, s48, 7
	v_cvt_f32_u32_e32 v68, s48
	s_cmp_lt_i32 s25, 0
	v_mul_f32_e32 v68, 0xc1000000, v68
	v_div_scale_f32 v69, s[36:37], s90, s90, v68
	v_rcp_f32_e32 v70, v69
	s_nop 0
	v_fma_f32 v71, -v69, v70, 1.0
	v_fmac_f32_e32 v70, v71, v70
	v_div_scale_f32 v71, vcc, v68, s90, v68
	v_mul_f32_e32 v72, v71, v70
	v_fma_f32 v73, -v69, v72, v71
	v_fmac_f32_e32 v72, v73, v70
	v_fma_f32 v69, -v69, v72, v71
	v_div_fmas_f32 v69, v69, v70, v72
	v_div_fixup_f32 v68, v69, s90, v68
	v_exp_f32_e32 v68, v68
	v_lshlrev_b32_e32 v69, 2, v142
	v_or_b32_e32 v73, 1, v69
	v_or_b32_e32 v70, 3, v69
	v_or_b32_e32 v72, 2, v69
	v_add_u32_e32 v74, 8, v69
	v_add_u32_e32 v75, 9, v69
	v_add_u32_e32 v76, 10, v69
	v_add_u32_e32 v77, 11, v69
	v_add_u32_e32 v78, 16, v69
	v_add_u32_e32 v79, 17, v69
	v_add_u32_e32 v80, 18, v69
	v_add_u32_e32 v81, 19, v69
	v_add_u32_e32 v82, 24, v69
	v_add_u32_e32 v83, 25, v69
	s_waitcnt vmcnt(0)
	v_add_u32_e32 v84, 26, v69
	v_add_u32_e32 v85, 27, v69
	v_cvt_f32_i32_e32 v71, v70
	v_cvt_f32_i32_e32 v70, v72
	v_cvt_f32_i32_e32 v72, v69
	v_cvt_f32_i32_e32 v73, v73
	v_cvt_f32_i32_e32 v75, v75
	v_cvt_f32_i32_e32 v74, v74
	v_cvt_f32_i32_e32 v77, v77
	v_cvt_f32_i32_e32 v76, v76
	v_cvt_f32_i32_e32 v79, v79
	v_cvt_f32_i32_e32 v78, v78
	v_cvt_f32_i32_e32 v81, v81
	v_cvt_f32_i32_e32 v80, v80
	v_cvt_f32_i32_e32 v83, v83
	v_cvt_f32_i32_e32 v82, v82
	v_cvt_f32_i32_e32 v85, v85
	v_cvt_f32_i32_e32 v84, v84
	v_mul_f32_e32 v68, 0x3fb8aa3b, v68
	v_mul_f32_e32 v182, 0x41800000, v68
	v_mul_f32_e32 v68, 0x40b17218, v182
	v_mul_f32_e32 v114, v68, v84
	v_mul_f32_e32 v115, v68, v85
	v_mul_f32_e32 v112, v68, v82
	v_mul_f32_e32 v113, v68, v83
	v_mul_f32_e32 v110, v68, v80
	v_mul_f32_e32 v111, v68, v81
	v_mul_f32_e32 v108, v68, v78
	v_mul_f32_e32 v109, v68, v79
	v_mul_f32_e32 v106, v68, v76
	v_mul_f32_e32 v107, v68, v77
	v_mul_f32_e32 v104, v68, v74
	v_mul_f32_e32 v105, v68, v75
	v_mul_f32_e32 v102, v68, v70
	v_mul_f32_e32 v103, v68, v71
	v_mul_f32_e32 v100, v68, v72
	v_mul_f32_e32 v101, v68, v73
	v_and_b32_e32 v68, 31, v167
	v_ashrrev_i32_e32 v69, 5, v167
	v_lshrrev_b32_e32 v71, 1, v167
	v_lshlrev_b32_e32 v70, 7, v68
	v_bitop3_b32 v71, v71, v69, 7 bitop3:0x6c
	v_lshl_add_u32 v183, v71, 4, v70
	v_add_u32_e32 v70, s46, v183
	ds_read_b128 v[70:73], v70
	s_waitcnt lgkmcnt(0)
	v_mfma_f32_32x32x16_bf16 v[132:147], v[70:73], v[148:151], v[100:115]
	v_mov_b32_e32 v70, v183
	v_xor_b32 v70, 32, v70
	s_nop 0
	v_add_u32_e32 v70, s46, v70
	ds_read_b128 v[70:73], v70
	s_waitcnt lgkmcnt(0)
	v_mfma_f32_32x32x16_bf16 v[132:147], v[70:73], v[152:155], v[132:147]
	v_mov_b32_e32 v70, v183
	v_xor_b32 v70, 64, v70
	s_nop 0
	v_add_u32_e32 v70, s46, v70
	ds_read_b128 v[70:73], v70
	s_waitcnt lgkmcnt(0)
	v_mfma_f32_32x32x16_bf16 v[132:147], v[70:73], v[156:159], v[132:147]
	v_mov_b32_e32 v70, v183
	v_xor_b32 v70, 0x60, v70
	s_nop 0
	v_add_u32_e32 v70, s46, v70
	ds_read_b128 v[70:73], v70
	s_waitcnt lgkmcnt(0)
	v_mfma_f32_32x32x16_bf16 v[132:147], v[70:73], v[160:163], v[132:147]
	s_cbranch_scc1 .LBB0_847
	s_mul_i32 s36, s25, 0x600000
	s_mul_hi_u32 s33, s25, 0x600000
	s_add_u32 s36, s5, s36
	s_addc_u32 s37, s12, s33
	s_mov_b64 s[40:41], s[36:37]
	s_mov_b32 m0, s46
	v_lshl_add_u64 v[70:71], s[40:41], 0, v[172:173]
	s_add_u32 s40, s36, 0x180000
	s_addc_u32 s41, s37, 0
	global_load_lds_dwordx4 v[70:71], off
	v_mov_b32_e32 v70, v172
	s_mov_b32 m0, s30
	v_xor_b32 v70, 64, v70
	s_nop 0
	global_load_lds_dwordx4 v70, s[40:41]
	s_add_u32 s40, s36, 0x300000
	s_addc_u32 s41, s37, 0
	s_mov_b32 m0, s8
	v_lshl_add_u64 v[70:71], s[40:41], 0, v[172:173]
	s_add_u32 s36, s36, 0x480000
	global_load_lds_dwordx4 v[70:71], off
	s_addc_u32 s37, s37, 0
	v_mov_b32_e32 v70, v172
	s_mov_b32 m0, s22
	v_xor_b32 v70, 64, v70
	s_nop 0
	global_load_lds_dwordx4 v70, s[36:37]

; template <int NDT, class F>
; __device__ __forceinline__ void softmax_body(f32x16& s, const F& f, int k0, int hh, f32x16 (&o)[NDT], float& m, float& l, bf16x8& pf0, bf16x8& pf1, const int MASK) {
;     ...
;     const float me = fmaxf(m, -1e29f);
;     const float off = on ? f.tadd - me : NEG_BIG;
;     const f32x2_t sc2 = {QK_SCL, QK_SCL}, of2 = {off, off}; f32x2_t ps2 = {0.f, 0.f};
; #pragma unroll
;     for (int r = 0; r < 16; r += 2) { f32x2_t a = {s[r], s[r + 1]}; a = __builtin_elementwise_fma(a, sc2, of2);
;         f32x2_t p; p.x = __builtin_amdgcn_exp2f(a.x); p.y = __builtin_amdgcn_exp2f(a.y); s[r] = p.x; s[r + 1] = p.y; ps2 += p; }
;     l += ps2.x + ps2.y;
.LBB0_860:
	v_max_f32_e32 v146, v167, v167
	v_max_f32_e32 v146, 0xefa18f08, v146
	v_sub_f32_e32 v176, v176, v146
	v_fma_f32 v132, v132, s34, v176
	v_fma_f32 v133, v133, s34, v176
	s_cmp_gt_i32 s25, -1
	v_exp_f32_e32 v146, v132
	v_exp_f32_e32 v147, v133
	s_cselect_b64 s[20:21], -1, 0
	s_mov_b64 s[22:23], -1
	s_and_b64 vcc, exec, s[20:21]
	v_cvt_pk_bf16_f32 v133, v146, v147
	s_cbranch_vccnz .LBB0_870
	s_cmp_gt_i32 s18, -1
	s_cbranch_scc1 .LBB0_867
	s_andn2_b64 vcc, exec, s[16:17]
	s_mov_b64 s[16:17], -1
	s_cbranch_vccnz .LBB0_864
	v_mov_b32_e32 v132, v133
	s_waitcnt vmcnt(0)
	s_mov_b64 s[16:17], 0

; #define LAS __attribute__((address_space(3)))
; __device__ __forceinline__ unsigned cvtpk(float lo, float hi) { f32x2_t v = {lo, hi}; bf16x2_t b = __builtin_convertvector(v, bf16x2_t); return __builtin_bit_cast(unsigned, b); }
; #define MFMA32(a, b, c) __builtin_amdgcn_mfma_f32_32x32x16_bf16((a), (b), (c), 0, 0, 0)
; template <int K> __device__ __forceinline__ int xor_now(int x) { if (K != 0) asm volatile("v_xor_b32 %0, %1, %0" : "+v"(x) : "n"(K)); return x; }
; template <int NDT, class F>
; __device__ __forceinline__ void softmax_body(f32x16& s, const F& f, int k0, int hh, f32x16 (&o)[NDT], float& m, float& l, bf16x8& pf0, bf16x8& pf1, const int MASK) {
;     ...
;     const f32x2_t sc2 = {QK_SCL, QK_SCL}, of2 = {off, off}; f32x2_t ps2 = {0.f, 0.f};
; #pragma unroll
;     for (int r = 0; r < 16; r += 2) { f32x2_t a = {s[r], s[r + 1]}; a = __builtin_elementwise_fma(a, sc2, of2);
;         f32x2_t p; p.x = __builtin_amdgcn_exp2f(a.x); p.y = __builtin_amdgcn_exp2f(a.y); s[r] = p.x; s[r + 1] = p.y; ps2 += p; }
;     l += ps2.x + ps2.y;
;     v4u p0, p1;
;     p0.x = cvtpk(s[0], s[1]); p0.y = cvtpk(s[2], s[3]); p0.z = cvtpk(s[4], s[5]); p0.w = cvtpk(s[6], s[7]);
;     p1.x = cvtpk(s[8], s[9]); p1.y = cvtpk(s[10], s[11]); p1.z = cvtpk(s[12], s[13]); p1.w = cvtpk(s[14], s[15]);
; template <int NDT, class F>
; __device__ __forceinline__ void stream_tile(const bf16x8 (&qf)[4], const WvStream& st, LAS unsigned char* cur, LAS unsigned char* nxt, const F& f, f32x16& s, int t0, int t1, int t2, int t3, int hh, f32x16 (&o)[NDT], float& m, float& l, int msk) {
;     ...
; #pragma unroll
;     for (int dt = 0; dt < NDT; ++dt) { const bf16x8 vf0 = *(const LAS bf16x8*)(cur + dt * 2048 + st.fv), vf1 = *(const LAS bf16x8*)(cur + dt * 2048 + xor_now<32>(st.fv));
;         o[dt] = MFMA32(vf0, pf0, o[dt]); o[dt] = MFMA32(vf1, pf1, o[dt]); }
;     if (t2 >= 0) st.dma_v(t2, cur);
.LBB0_872:
	s_lshl_b32 s16, s36, 13
	s_add_i32 s16, s46, s16
	v_add_u32_e32 v196, s16, v185
	v_mov_b32_e32 v177, v176
	ds_read_b128 v[188:191], v196 offset:4096
	v_fma_f32 v134, v134, s34, v176
	v_fma_f32 v135, v135, s34, v177
	v_mov_b32_e32 v192, v186
	v_exp_f32_e32 v178, v134
	v_exp_f32_e32 v179, v135
	v_fma_f32 v134, v174, s34, v176
	v_fma_f32 v135, v175, s34, v177
	v_xor_b32 v192, 32, v192
	v_fma_f32 v136, v136, s34, v176
	v_fma_f32 v137, v137, s34, v177
	v_exp_f32_e32 v174, v134
	v_exp_f32_e32 v175, v135
	v_fma_f32 v134, v138, s34, v176
	v_fma_f32 v135, v139, s34, v177
	v_add_u32_e32 v192, s16, v192
	v_exp_f32_e32 v138, v134
	v_exp_f32_e32 v139, v135
	v_fma_f32 v134, v140, s34, v176
	v_fma_f32 v135, v141, s34, v177
	v_cvt_pk_bf16_f32 v133, v178, v179
	v_exp_f32_e32 v140, v134
	v_exp_f32_e32 v141, v135
	v_fma_f32 v134, v142, s34, v176
	v_fma_f32 v135, v143, s34, v177
	ds_read_b128 v[192:195], v192
	v_exp_f32_e32 v142, v134
	v_exp_f32_e32 v143, v135
	v_fma_f32 v134, v144, s34, v176
	v_fma_f32 v135, v145, s34, v177
	v_exp_f32_e32 v136, v136
	v_exp_f32_e32 v144, v134
	v_exp_f32_e32 v145, v135
	v_cvt_pk_bf16_f32 v134, v174, v175
	v_cvt_pk_bf16_f32 v135, v138, v139
	v_exp_f32_e32 v137, v137
	v_mov_b32_e32 v176, v186
	s_waitcnt lgkmcnt(0)
	v_mfma_f32_32x32x16_bf16 v[84:99], v[188:191], v[132:135], v[84:99]
	v_cvt_pk_bf16_f32 v188, v140, v141
	v_cvt_pk_bf16_f32 v189, v142, v143
	v_cvt_pk_bf16_f32 v190, v144, v145
	v_cvt_pk_bf16_f32 v191, v136, v137
	s_cmp_lt_i32 s18, 0
	s_nop 0
	v_mfma_f32_32x32x16_bf16 v[84:99], v[192:195], v[188:191], v[84:99]
	ds_read_b128 v[192:195], v196 offset:6144
	v_xor_b32 v176, 32, v176
	s_nop 0
	v_add_u32_e32 v176, s16, v176
	s_waitcnt lgkmcnt(0)
	v_mfma_f32_32x32x16_bf16 v[68:83], v[192:195], v[132:135], v[68:83]
	ds_read_b128 v[132:135], v176 offset:2048
	s_waitcnt lgkmcnt(0)
	v_mfma_f32_32x32x16_bf16 v[68:83], v[132:135], v[188:191], v[68:83]
	s_cbranch_scc1 .LBB0_874
	s_lshl_b64 s[22:23], s[18:19], 12
	s_add_u32 s22, s13, s22
	s_addc_u32 s23, s24, s23
	s_mov_b64 s[36:37], s[22:23]
	s_add_i32 m0, s16, 0x1000
	s_nop 0
	v_lshl_add_u64 v[132:133], s[36:37], 0, v[2:3]
	s_add_u32 s36, s22, 0x400
	s_addc_u32 s37, s23, 0
	global_load_lds_dwordx4 v[132:133], off
	s_add_i32 m0, s16, 0x1400
	v_lshl_add_u64 v[132:133], s[36:37], 0, v[2:3]
	s_add_u32 s36, s22, 0x800
	global_load_lds_dwordx4 v[132:133], off
	s_addc_u32 s37, s23, 0
	s_add_i32 m0, s16, 0x1800
	s_add_u32 s22, s22, 0xc00
	s_addc_u32 s23, s23, 0
	v_lshl_add_u64 v[132:133], s[36:37], 0, v[2:3]
	global_load_lds_dwordx4 v[132:133], off
	s_add_i32 m0, s16, 0x1c00
	v_lshl_add_u64 v[132:133], s[22:23], 0, v[2:3]
	global_load_lds_dwordx4 v[132:133], off
.LBB0_874:
	v_pk_add_f32 v[132:133], v[146:147], 0 op_sel_hi:[1,0]
	s_cmp_ge_i32 s30, s4
	v_add_f32_e32 v132, v178, v132
	v_add_f32_e32 v133, v179, v133
	s_cselect_b64 s[22:23], -1, 0
	v_add_f32_e32 v132, v174, v132
	v_add_f32_e32 v133, v175, v133
	s_nop 0
	v_add_f32_e32 v132, v138, v132
	v_add_f32_e32 v133, v139, v133
	s_nop 0
	v_add_f32_e32 v132, v140, v132
	v_add_f32_e32 v133, v141, v133
	s_nop 0
	v_add_f32_e32 v132, v142, v132
	v_add_f32_e32 v133, v143, v133
	s_nop 0
	v_add_f32_e32 v132, v144, v132
	v_add_f32_e32 v133, v145, v133
	s_nop 0
	v_add_f32_e32 v132, v136, v132
	v_add_f32_e32 v133, v137, v133
	s_nop 0
	v_add_f32_e32 v132, v132, v133
	v_cndmask_b32_e64 v133, 0, 1, s[20:21]
	s_and_b64 s[20:21], s[20:21], s[22:23]
	v_readfirstlane_b32 s16, v133
	s_sub_i32 s17, s30, s16
	s_and_b64 s[20:21], s[20:21], exec
	s_cselect_b32 s16, s30, -1
	s_cmp_gt_i32 s31, -1
	v_add_f32_e32 v169, v169, v132
	s_cbranch_scc0 .LBB0_753
	v_mov_b64_e32 v[146:147], v[130:131]
	s_mov_b32 s30, s17
	v_mov_b64_e32 v[144:145], v[128:129]
	v_mov_b64_e32 v[142:143], v[126:127]
	v_mov_b64_e32 v[140:141], v[124:125]
	v_mov_b64_e32 v[138:139], v[122:123]
	v_mov_b64_e32 v[136:137], v[120:121]
	v_mov_b64_e32 v[134:135], v[118:119]
	v_mov_b64_e32 v[132:133], v[116:117]
	s_mov_b32 s36, s33
	s_mov_b32 s23, s31
	s_branch .LBB0_850
